# removed trailing vmcnt(0) drains at the end of batched epilogues
# baseline (speedup 1.0000x reference)
; DI int otid() { int t = threadIdx.x; asm volatile("" : "+v"(t)); return t; }
; DI bf16_t cv1(float x) { return (bf16_t)(pk2(x, 0.f) & 0xffffu); }
; DI float bf2f(bf16_t v) { return (float)__builtin_bit_cast(_Float16, v); }
; DI int crow(int i, int h) { return (i & 3) + 8 * (i >> 2) + 4 * h; }
;     DI void operator()(int unit, const f32x16 (&acc)[MT][NT]) const {
;         const int lane = otid() & 63, r = lane & 31, h = lane >> 5;
; #pragma unroll
;         for (int mi = 0; mi < MT; ++mi)
; #pragma unroll
;             for (int nj = 0; nj < NT; ++nj)
; #pragma unroll
;                 for (int i = 0; i < 16; ++i) {
;                     bf16_t* rowp = priv + (mi * 32 + crow(i, h) + (mi == 2 ? d2 : 0)) * PRIVW; const int c = unit * UW + nj * 32 + r;
;                     float v = bf2f(rowp[gcol + c]) * acc[mi][nj][i];
;                     if (SECOND) v += bf2f(rowp[PC_M + c]);
;                     rowp[PC_M + c] = cv1(v);
;                     if (i == 15) __builtin_amdgcn_sched_barrier(0);
;                 }
;     }
.LBB0_388:
	s_and_saveexec_b64 s[28:29], s[4:5]
	s_cbranch_execz .LBB0_377
	s_waitcnt vmcnt(0)
	v_and_b32_e32 v2, 31, v176
	v_lshrrev_b32_e32 v3, 3, v176
	v_and_b32_e32 v3, 4, v3
	v_mul_u32_u24_e32 v3, 0x2c00, v3
	v_lshl_add_u32 v4, v2, 1, v3
	v_lshl_add_u32 v4, v232, 7, v4
	v_add_u32_e32 v5, 0x1400, v4
	global_load_ushort v117, v5, s[6:7] offset:-3072
	global_load_ushort v118, v5, s[6:7] offset:-3008
	v_add_u32_e32 v6, 0x4000, v4
	global_load_ushort v119, v6, s[6:7] offset:-3072
	global_load_ushort v120, v6, s[6:7] offset:-3008
	v_add_u32_e32 v7, 0x6c00, v4
	global_load_ushort v121, v7, s[6:7] offset:-3072
	global_load_ushort v122, v7, s[6:7] offset:-3008
	v_add_u32_e32 v8, 0x9800, v4
	global_load_ushort v123, v8, s[6:7] offset:-3072
	global_load_ushort v124, v8, s[6:7] offset:-3008
	v_add_u32_e32 v9, 0x17400, v4
	global_load_ushort v125, v9, s[6:7] offset:-3072
	global_load_ushort v126, v9, s[6:7] offset:-3008
	v_add_u32_e32 v10, 0x1a000, v4
	global_load_ushort v127, v10, s[6:7] offset:-3072
	global_load_ushort v128, v10, s[6:7] offset:-3008
	v_add_u32_e32 v11, 0x1cc00, v4
	global_load_ushort v129, v11, s[6:7] offset:-3072
	global_load_ushort v130, v11, s[6:7] offset:-3008
	v_add_u32_e32 v12, 0x1f800, v4
	global_load_ushort v131, v12, s[6:7] offset:-3072
	global_load_ushort v132, v12, s[6:7] offset:-3008
	v_add_u32_e32 v13, 0x2d400, v4
	global_load_ushort v133, v13, s[6:7] offset:-3072
	global_load_ushort v134, v13, s[6:7] offset:-3008
	v_add_u32_e32 v14, 0x30000, v4
	global_load_ushort v135, v14, s[6:7] offset:-3072
	global_load_ushort v136, v14, s[6:7] offset:-3008
	v_add_u32_e32 v15, 0x32c00, v4
	global_load_ushort v137, v15, s[6:7] offset:-3072
	global_load_ushort v138, v15, s[6:7] offset:-3008
	v_add_u32_e32 v112, 0x35800, v4
	global_load_ushort v139, v112, s[6:7] offset:-3072
	global_load_ushort v140, v112, s[6:7] offset:-3008
	v_add_u32_e32 v113, 0x43400, v4
	global_load_ushort v141, v113, s[6:7] offset:-3072
	global_load_ushort v142, v113, s[6:7] offset:-3008
	v_add_u32_e32 v114, 0x46000, v4
	global_load_ushort v143, v114, s[6:7] offset:-3072
	global_load_ushort v144, v114, s[6:7] offset:-3008
	v_add_u32_e32 v115, 0x48c00, v4
	global_load_ushort v145, v115, s[6:7] offset:-3072
	global_load_ushort v146, v115, s[6:7] offset:-3008
	v_add_u32_e32 v116, 0x4b800, v4
	global_load_ushort v147, v116, s[6:7] offset:-3072
	global_load_ushort v148, v116, s[6:7] offset:-3008
	s_waitcnt vmcnt(0)
	v_fma_mixlo_f16 v117, v96, v117, 0 op_sel_hi:[0,1,0]
	global_store_short v5, v117, s[6:7] offset:3072
	v_fma_mixlo_f16 v118, v80, v118, 0 op_sel_hi:[0,1,0]
	global_store_short v5, v118, s[6:7] offset:3136
	v_fma_mixlo_f16 v119, v97, v119, 0 op_sel_hi:[0,1,0]
	global_store_short v6, v119, s[6:7] offset:3072
	v_fma_mixlo_f16 v120, v81, v120, 0 op_sel_hi:[0,1,0]
	global_store_short v6, v120, s[6:7] offset:3136
	v_fma_mixlo_f16 v121, v98, v121, 0 op_sel_hi:[0,1,0]
	global_store_short v7, v121, s[6:7] offset:3072
	v_fma_mixlo_f16 v122, v82, v122, 0 op_sel_hi:[0,1,0]
	global_store_short v7, v122, s[6:7] offset:3136
	v_fma_mixlo_f16 v123, v99, v123, 0 op_sel_hi:[0,1,0]
	global_store_short v8, v123, s[6:7] offset:3072
	v_fma_mixlo_f16 v124, v83, v124, 0 op_sel_hi:[0,1,0]
	global_store_short v8, v124, s[6:7] offset:3136
	v_fma_mixlo_f16 v125, v100, v125, 0 op_sel_hi:[0,1,0]
	global_store_short v9, v125, s[6:7] offset:3072
	v_fma_mixlo_f16 v126, v84, v126, 0 op_sel_hi:[0,1,0]
	global_store_short v9, v126, s[6:7] offset:3136
	v_fma_mixlo_f16 v127, v101, v127, 0 op_sel_hi:[0,1,0]
	global_store_short v10, v127, s[6:7] offset:3072
	v_fma_mixlo_f16 v128, v85, v128, 0 op_sel_hi:[0,1,0]
	global_store_short v10, v128, s[6:7] offset:3136
	v_fma_mixlo_f16 v129, v102, v129, 0 op_sel_hi:[0,1,0]
	global_store_short v11, v129, s[6:7] offset:3072
	v_fma_mixlo_f16 v130, v86, v130, 0 op_sel_hi:[0,1,0]
	global_store_short v11, v130, s[6:7] offset:3136
	v_fma_mixlo_f16 v131, v103, v131, 0 op_sel_hi:[0,1,0]
	global_store_short v12, v131, s[6:7] offset:3072
	v_fma_mixlo_f16 v132, v87, v132, 0 op_sel_hi:[0,1,0]
	global_store_short v12, v132, s[6:7] offset:3136
	v_fma_mixlo_f16 v133, v104, v133, 0 op_sel_hi:[0,1,0]
	global_store_short v13, v133, s[6:7] offset:3072
	v_fma_mixlo_f16 v134, v88, v134, 0 op_sel_hi:[0,1,0]
	global_store_short v13, v134, s[6:7] offset:3136
	v_fma_mixlo_f16 v135, v105, v135, 0 op_sel_hi:[0,1,0]
	global_store_short v14, v135, s[6:7] offset:3072
	v_fma_mixlo_f16 v136, v89, v136, 0 op_sel_hi:[0,1,0]
	global_store_short v14, v136, s[6:7] offset:3136
	v_fma_mixlo_f16 v137, v106, v137, 0 op_sel_hi:[0,1,0]
	global_store_short v15, v137, s[6:7] offset:3072
	v_fma_mixlo_f16 v138, v90, v138, 0 op_sel_hi:[0,1,0]
	global_store_short v15, v138, s[6:7] offset:3136
	v_fma_mixlo_f16 v139, v107, v139, 0 op_sel_hi:[0,1,0]
	global_store_short v112, v139, s[6:7] offset:3072
	v_fma_mixlo_f16 v140, v91, v140, 0 op_sel_hi:[0,1,0]
	global_store_short v112, v140, s[6:7] offset:3136
	v_fma_mixlo_f16 v141, v108, v141, 0 op_sel_hi:[0,1,0]
	global_store_short v113, v141, s[6:7] offset:3072
	v_fma_mixlo_f16 v142, v92, v142, 0 op_sel_hi:[0,1,0]
	global_store_short v113, v142, s[6:7] offset:3136
	v_fma_mixlo_f16 v143, v109, v143, 0 op_sel_hi:[0,1,0]
	global_store_short v114, v143, s[6:7] offset:3072
	v_fma_mixlo_f16 v144, v93, v144, 0 op_sel_hi:[0,1,0]
	global_store_short v114, v144, s[6:7] offset:3136
	v_fma_mixlo_f16 v145, v110, v145, 0 op_sel_hi:[0,1,0]
	global_store_short v115, v145, s[6:7] offset:3072
	v_fma_mixlo_f16 v146, v94, v146, 0 op_sel_hi:[0,1,0]
	global_store_short v115, v146, s[6:7] offset:3136
	v_fma_mixlo_f16 v147, v111, v147, 0 op_sel_hi:[0,1,0]
; DI int otid() { int t = threadIdx.x; asm volatile("" : "+v"(t)); return t; }
; DI bf16_t cv1(float x) { return (bf16_t)(pk2(x, 0.f) & 0xffffu); }
; DI float bf2f(bf16_t v) { return (float)__builtin_bit_cast(_Float16, v); }
; DI int crow(int i, int h) { return (i & 3) + 8 * (i >> 2) + 4 * h; }
;     DI void operator()(int unit, const f32x16 (&acc)[MT][NT]) const {
;         const int lane = otid() & 63, r = lane & 31, h = lane >> 5;
; #pragma unroll
;         for (int mi = 0; mi < MT; ++mi)
; #pragma unroll
;             for (int nj = 0; nj < NT; ++nj)
; #pragma unroll
;                 for (int i = 0; i < 16; ++i) {
;                     bf16_t* rowp = priv + (mi * 32 + crow(i, h) + (mi == 2 ? d2 : 0)) * PRIVW; const int c = unit * UW + nj * 32 + r;
;                     float v = bf2f(rowp[gcol + c]) * acc[mi][nj][i];
;                     if (SECOND) v += bf2f(rowp[PC_M + c]);
;                     rowp[PC_M + c] = cv1(v);
;                     if (i == 15) __builtin_amdgcn_sched_barrier(0);
;                 }
;     }
	global_store_short v116, v147, s[6:7] offset:3072
	v_fma_mixlo_f16 v148, v95, v148, 0 op_sel_hi:[0,1,0]
	global_store_short v116, v148, s[6:7] offset:3136
	v_add_u32_e32 v5, 0x59400, v4
	global_load_ushort v117, v5, s[6:7] offset:-3072
	global_load_ushort v118, v5, s[6:7] offset:-3008
	v_add_u32_e32 v6, 0x5c000, v4
	global_load_ushort v119, v6, s[6:7] offset:-3072
	global_load_ushort v120, v6, s[6:7] offset:-3008
	v_add_u32_e32 v7, 0x5ec00, v4
	global_load_ushort v121, v7, s[6:7] offset:-3072
	global_load_ushort v122, v7, s[6:7] offset:-3008
	v_add_u32_e32 v8, 0x61800, v4
	global_load_ushort v123, v8, s[6:7] offset:-3072
	global_load_ushort v124, v8, s[6:7] offset:-3008
	v_add_u32_e32 v9, 0x6f400, v4
	global_load_ushort v125, v9, s[6:7] offset:-3072
	global_load_ushort v126, v9, s[6:7] offset:-3008
	v_add_u32_e32 v10, 0x72000, v4
	global_load_ushort v127, v10, s[6:7] offset:-3072
	global_load_ushort v128, v10, s[6:7] offset:-3008
	v_add_u32_e32 v11, 0x74c00, v4
	global_load_ushort v129, v11, s[6:7] offset:-3072
	global_load_ushort v130, v11, s[6:7] offset:-3008
	v_add_u32_e32 v12, 0x77800, v4
	global_load_ushort v131, v12, s[6:7] offset:-3072
	global_load_ushort v132, v12, s[6:7] offset:-3008
	v_add_u32_e32 v13, 0x85400, v4
	global_load_ushort v133, v13, s[6:7] offset:-3072
	global_load_ushort v134, v13, s[6:7] offset:-3008
	v_add_u32_e32 v14, 0x88000, v4
	global_load_ushort v135, v14, s[6:7] offset:-3072
	global_load_ushort v136, v14, s[6:7] offset:-3008
	v_add_u32_e32 v15, 0x8ac00, v4
	global_load_ushort v137, v15, s[6:7] offset:-3072
	global_load_ushort v138, v15, s[6:7] offset:-3008
	v_add_u32_e32 v112, 0x8d800, v4
	global_load_ushort v139, v112, s[6:7] offset:-3072
	global_load_ushort v140, v112, s[6:7] offset:-3008
	v_add_u32_e32 v113, 0x9b400, v4
	global_load_ushort v141, v113, s[6:7] offset:-3072
	global_load_ushort v142, v113, s[6:7] offset:-3008
	v_add_u32_e32 v114, 0x9e000, v4
	global_load_ushort v143, v114, s[6:7] offset:-3072
	global_load_ushort v144, v114, s[6:7] offset:-3008
	v_add_u32_e32 v115, 0xa0c00, v4
	global_load_ushort v145, v115, s[6:7] offset:-3072
	global_load_ushort v146, v115, s[6:7] offset:-3008
	v_add_u32_e32 v116, 0xa3800, v4
	global_load_ushort v147, v116, s[6:7] offset:-3072
	global_load_ushort v148, v116, s[6:7] offset:-3008
	s_waitcnt vmcnt(0)
	v_fma_mixlo_f16 v117, v64, v117, 0 op_sel_hi:[0,1,0]
	global_store_short v5, v117, s[6:7] offset:3072
	v_fma_mixlo_f16 v118, v48, v118, 0 op_sel_hi:[0,1,0]
	global_store_short v5, v118, s[6:7] offset:3136
	v_fma_mixlo_f16 v119, v65, v119, 0 op_sel_hi:[0,1,0]
	global_store_short v6, v119, s[6:7] offset:3072
	v_fma_mixlo_f16 v120, v49, v120, 0 op_sel_hi:[0,1,0]
	global_store_short v6, v120, s[6:7] offset:3136
	v_fma_mixlo_f16 v121, v66, v121, 0 op_sel_hi:[0,1,0]
	global_store_short v7, v121, s[6:7] offset:3072
	v_fma_mixlo_f16 v122, v50, v122, 0 op_sel_hi:[0,1,0]
	global_store_short v7, v122, s[6:7] offset:3136
	v_fma_mixlo_f16 v123, v67, v123, 0 op_sel_hi:[0,1,0]
	global_store_short v8, v123, s[6:7] offset:3072
	v_fma_mixlo_f16 v124, v51, v124, 0 op_sel_hi:[0,1,0]
	global_store_short v8, v124, s[6:7] offset:3136
	v_fma_mixlo_f16 v125, v68, v125, 0 op_sel_hi:[0,1,0]
	global_store_short v9, v125, s[6:7] offset:3072
	v_fma_mixlo_f16 v126, v52, v126, 0 op_sel_hi:[0,1,0]
	global_store_short v9, v126, s[6:7] offset:3136
	v_fma_mixlo_f16 v127, v69, v127, 0 op_sel_hi:[0,1,0]
	global_store_short v10, v127, s[6:7] offset:3072
	v_fma_mixlo_f16 v128, v53, v128, 0 op_sel_hi:[0,1,0]
	global_store_short v10, v128, s[6:7] offset:3136
	v_fma_mixlo_f16 v129, v70, v129, 0 op_sel_hi:[0,1,0]
	global_store_short v11, v129, s[6:7] offset:3072
	v_fma_mixlo_f16 v130, v54, v130, 0 op_sel_hi:[0,1,0]
	global_store_short v11, v130, s[6:7] offset:3136
	v_fma_mixlo_f16 v131, v71, v131, 0 op_sel_hi:[0,1,0]
	global_store_short v12, v131, s[6:7] offset:3072
	v_fma_mixlo_f16 v132, v55, v132, 0 op_sel_hi:[0,1,0]
	global_store_short v12, v132, s[6:7] offset:3136
	v_fma_mixlo_f16 v133, v72, v133, 0 op_sel_hi:[0,1,0]
	global_store_short v13, v133, s[6:7] offset:3072
	v_fma_mixlo_f16 v134, v56, v134, 0 op_sel_hi:[0,1,0]
	global_store_short v13, v134, s[6:7] offset:3136
	v_fma_mixlo_f16 v135, v73, v135, 0 op_sel_hi:[0,1,0]
	global_store_short v14, v135, s[6:7] offset:3072
	v_fma_mixlo_f16 v136, v57, v136, 0 op_sel_hi:[0,1,0]
	global_store_short v14, v136, s[6:7] offset:3136
	v_fma_mixlo_f16 v137, v74, v137, 0 op_sel_hi:[0,1,0]
	global_store_short v15, v137, s[6:7] offset:3072
	v_fma_mixlo_f16 v138, v58, v138, 0 op_sel_hi:[0,1,0]
	global_store_short v15, v138, s[6:7] offset:3136
	v_fma_mixlo_f16 v139, v75, v139, 0 op_sel_hi:[0,1,0]
	global_store_short v112, v139, s[6:7] offset:3072
	v_fma_mixlo_f16 v140, v59, v140, 0 op_sel_hi:[0,1,0]
	global_store_short v112, v140, s[6:7] offset:3136
	v_fma_mixlo_f16 v141, v76, v141, 0 op_sel_hi:[0,1,0]
	global_store_short v113, v141, s[6:7] offset:3072
	v_fma_mixlo_f16 v142, v60, v142, 0 op_sel_hi:[0,1,0]
	global_store_short v113, v142, s[6:7] offset:3136
	v_fma_mixlo_f16 v143, v77, v143, 0 op_sel_hi:[0,1,0]
	global_store_short v114, v143, s[6:7] offset:3072
	v_fma_mixlo_f16 v144, v61, v144, 0 op_sel_hi:[0,1,0]
	global_store_short v114, v144, s[6:7] offset:3136
	v_fma_mixlo_f16 v145, v78, v145, 0 op_sel_hi:[0,1,0]
	global_store_short v115, v145, s[6:7] offset:3072
	v_fma_mixlo_f16 v146, v62, v146, 0 op_sel_hi:[0,1,0]
	global_store_short v115, v146, s[6:7] offset:3136
	v_fma_mixlo_f16 v147, v79, v147, 0 op_sel_hi:[0,1,0]
	global_store_short v116, v147, s[6:7] offset:3072
	v_fma_mixlo_f16 v148, v63, v148, 0 op_sel_hi:[0,1,0]
; DI int otid() { int t = threadIdx.x; asm volatile("" : "+v"(t)); return t; }
; DI bf16_t cv1(float x) { return (bf16_t)(pk2(x, 0.f) & 0xffffu); }
; DI float bf2f(bf16_t v) { return (float)__builtin_bit_cast(_Float16, v); }
; DI int crow(int i, int h) { return (i & 3) + 8 * (i >> 2) + 4 * h; }
;     DI void operator()(int unit, const f32x16 (&acc)[MT][NT]) const {
;         const int lane = otid() & 63, r = lane & 31, h = lane >> 5;
; #pragma unroll
;         for (int mi = 0; mi < MT; ++mi)
; #pragma unroll
;             for (int nj = 0; nj < NT; ++nj)
; #pragma unroll
;                 for (int i = 0; i < 16; ++i) {
;                     bf16_t* rowp = priv + (mi * 32 + crow(i, h) + (mi == 2 ? d2 : 0)) * PRIVW; const int c = unit * UW + nj * 32 + r;
;                     float v = bf2f(rowp[gcol + c]) * acc[mi][nj][i];
;                     if (SECOND) v += bf2f(rowp[PC_M + c]);
;                     rowp[PC_M + c] = cv1(v);
;                     if (i == 15) __builtin_amdgcn_sched_barrier(0);
;                 }
;     }
	global_store_short v116, v148, s[6:7] offset:3136
	s_sub_i32 s100, 0x4000, s62
	s_mul_i32 s101, s100, 0x2c00
	v_add_u32_e32 v3, s101, v4
	v_add_u32_e32 v5, 0x1400, v3
	global_load_ushort v117, v5, s[6:7] offset:-3072
	global_load_ushort v118, v5, s[6:7] offset:-3008
	v_add_u32_e32 v6, 0x4000, v3
	global_load_ushort v119, v6, s[6:7] offset:-3072
	global_load_ushort v120, v6, s[6:7] offset:-3008
	v_add_u32_e32 v7, 0x6c00, v3
	global_load_ushort v121, v7, s[6:7] offset:-3072
	global_load_ushort v122, v7, s[6:7] offset:-3008
	v_add_u32_e32 v8, 0x9800, v3
	global_load_ushort v123, v8, s[6:7] offset:-3072
	global_load_ushort v124, v8, s[6:7] offset:-3008
	v_add_u32_e32 v9, 0x17400, v3
	global_load_ushort v125, v9, s[6:7] offset:-3072
	global_load_ushort v126, v9, s[6:7] offset:-3008
	v_add_u32_e32 v10, 0x1a000, v3
	global_load_ushort v127, v10, s[6:7] offset:-3072
	global_load_ushort v128, v10, s[6:7] offset:-3008
	v_add_u32_e32 v11, 0x1cc00, v3
	global_load_ushort v129, v11, s[6:7] offset:-3072
	global_load_ushort v130, v11, s[6:7] offset:-3008
	v_add_u32_e32 v12, 0x1f800, v3
	global_load_ushort v131, v12, s[6:7] offset:-3072
	global_load_ushort v132, v12, s[6:7] offset:-3008
	v_add_u32_e32 v13, 0x2d400, v3
	global_load_ushort v133, v13, s[6:7] offset:-3072
	global_load_ushort v134, v13, s[6:7] offset:-3008
	v_add_u32_e32 v14, 0x30000, v3
	global_load_ushort v135, v14, s[6:7] offset:-3072
	global_load_ushort v136, v14, s[6:7] offset:-3008
	v_add_u32_e32 v15, 0x32c00, v3
	global_load_ushort v137, v15, s[6:7] offset:-3072
	global_load_ushort v138, v15, s[6:7] offset:-3008
	v_add_u32_e32 v112, 0x35800, v3
	global_load_ushort v139, v112, s[6:7] offset:-3072
	global_load_ushort v140, v112, s[6:7] offset:-3008
	v_add_u32_e32 v113, 0x43400, v3
	global_load_ushort v141, v113, s[6:7] offset:-3072
	global_load_ushort v142, v113, s[6:7] offset:-3008
	v_add_u32_e32 v114, 0x46000, v3
	global_load_ushort v143, v114, s[6:7] offset:-3072
	global_load_ushort v144, v114, s[6:7] offset:-3008
	v_add_u32_e32 v115, 0x48c00, v3
	global_load_ushort v145, v115, s[6:7] offset:-3072
	global_load_ushort v146, v115, s[6:7] offset:-3008
	v_add_u32_e32 v116, 0x4b800, v3
	global_load_ushort v147, v116, s[6:7] offset:-3072
	global_load_ushort v148, v116, s[6:7] offset:-3008
	s_waitcnt vmcnt(0)
	v_fma_mixlo_f16 v117, v32, v117, 0 op_sel_hi:[0,1,0]
	global_store_short v5, v117, s[6:7] offset:3072
	v_fma_mixlo_f16 v118, v16, v118, 0 op_sel_hi:[0,1,0]
	global_store_short v5, v118, s[6:7] offset:3136
	v_fma_mixlo_f16 v119, v33, v119, 0 op_sel_hi:[0,1,0]
	global_store_short v6, v119, s[6:7] offset:3072
	v_fma_mixlo_f16 v120, v17, v120, 0 op_sel_hi:[0,1,0]
	global_store_short v6, v120, s[6:7] offset:3136
	v_fma_mixlo_f16 v121, v34, v121, 0 op_sel_hi:[0,1,0]
	global_store_short v7, v121, s[6:7] offset:3072
	v_fma_mixlo_f16 v122, v18, v122, 0 op_sel_hi:[0,1,0]
	global_store_short v7, v122, s[6:7] offset:3136
	v_fma_mixlo_f16 v123, v35, v123, 0 op_sel_hi:[0,1,0]
	global_store_short v8, v123, s[6:7] offset:3072
	v_fma_mixlo_f16 v124, v19, v124, 0 op_sel_hi:[0,1,0]
	global_store_short v8, v124, s[6:7] offset:3136
	v_fma_mixlo_f16 v125, v36, v125, 0 op_sel_hi:[0,1,0]
	global_store_short v9, v125, s[6:7] offset:3072
	v_fma_mixlo_f16 v126, v20, v126, 0 op_sel_hi:[0,1,0]
	global_store_short v9, v126, s[6:7] offset:3136
	v_fma_mixlo_f16 v127, v37, v127, 0 op_sel_hi:[0,1,0]
	global_store_short v10, v127, s[6:7] offset:3072
	v_fma_mixlo_f16 v128, v21, v128, 0 op_sel_hi:[0,1,0]
	global_store_short v10, v128, s[6:7] offset:3136
	v_fma_mixlo_f16 v129, v38, v129, 0 op_sel_hi:[0,1,0]
	global_store_short v11, v129, s[6:7] offset:3072
	v_fma_mixlo_f16 v130, v22, v130, 0 op_sel_hi:[0,1,0]
	global_store_short v11, v130, s[6:7] offset:3136
	v_fma_mixlo_f16 v131, v39, v131, 0 op_sel_hi:[0,1,0]
	global_store_short v12, v131, s[6:7] offset:3072
	v_fma_mixlo_f16 v132, v23, v132, 0 op_sel_hi:[0,1,0]
	global_store_short v12, v132, s[6:7] offset:3136
	v_fma_mixlo_f16 v133, v40, v133, 0 op_sel_hi:[0,1,0]
	global_store_short v13, v133, s[6:7] offset:3072
	v_fma_mixlo_f16 v134, v24, v134, 0 op_sel_hi:[0,1,0]
	global_store_short v13, v134, s[6:7] offset:3136
	v_fma_mixlo_f16 v135, v41, v135, 0 op_sel_hi:[0,1,0]
	global_store_short v14, v135, s[6:7] offset:3072
	v_fma_mixlo_f16 v136, v25, v136, 0 op_sel_hi:[0,1,0]
	global_store_short v14, v136, s[6:7] offset:3136
	v_fma_mixlo_f16 v137, v42, v137, 0 op_sel_hi:[0,1,0]
	global_store_short v15, v137, s[6:7] offset:3072
	v_fma_mixlo_f16 v138, v26, v138, 0 op_sel_hi:[0,1,0]
	global_store_short v15, v138, s[6:7] offset:3136
	v_fma_mixlo_f16 v139, v43, v139, 0 op_sel_hi:[0,1,0]
	global_store_short v112, v139, s[6:7] offset:3072
	v_fma_mixlo_f16 v140, v27, v140, 0 op_sel_hi:[0,1,0]
	global_store_short v112, v140, s[6:7] offset:3136
	v_fma_mixlo_f16 v141, v44, v141, 0 op_sel_hi:[0,1,0]
	global_store_short v113, v141, s[6:7] offset:3072
	v_fma_mixlo_f16 v142, v28, v142, 0 op_sel_hi:[0,1,0]
	global_store_short v113, v142, s[6:7] offset:3136
	v_fma_mixlo_f16 v143, v45, v143, 0 op_sel_hi:[0,1,0]
	global_store_short v114, v143, s[6:7] offset:3072
	v_fma_mixlo_f16 v144, v29, v144, 0 op_sel_hi:[0,1,0]
	global_store_short v114, v144, s[6:7] offset:3136
	v_fma_mixlo_f16 v145, v46, v145, 0 op_sel_hi:[0,1,0]
	global_store_short v115, v145, s[6:7] offset:3072
	v_fma_mixlo_f16 v146, v30, v146, 0 op_sel_hi:[0,1,0]
	global_store_short v115, v146, s[6:7] offset:3136
	v_fma_mixlo_f16 v147, v47, v147, 0 op_sel_hi:[0,1,0]
	global_store_short v116, v147, s[6:7] offset:3072
	v_fma_mixlo_f16 v148, v31, v148, 0 op_sel_hi:[0,1,0]
	global_store_short v116, v148, s[6:7] offset:3136
	s_branch .LBB0_377

; DI int otid() { int t = threadIdx.x; asm volatile("" : "+v"(t)); return t; }
; DI bf16_t cv1(float x) { return (bf16_t)(pk2(x, 0.f) & 0xffffu); }
; DI float bf2f(bf16_t v) { return (float)__builtin_bit_cast(_Float16, v); }
; DI int crow(int i, int h) { return (i & 3) + 8 * (i >> 2) + 4 * h; }
;     DI void operator()(int unit, const f32x16 (&acc)[MT][NT]) const {
;         const int lane = otid() & 63, r = lane & 31, h = lane >> 5;
; #pragma unroll
;         for (int mi = 0; mi < MT; ++mi)
; #pragma unroll
;             for (int nj = 0; nj < NT; ++nj)
; #pragma unroll
;                 for (int i = 0; i < 16; ++i) {
;                     bf16_t* rowp = priv + (mi * 32 + crow(i, h) + (mi == 2 ? d2 : 0)) * PRIVW; const int c = unit * UW + nj * 32 + r;
;                     float v = bf2f(rowp[gcol + c]) * acc[mi][nj][i];
;                     if (SECOND) v += bf2f(rowp[PC_M + c]);
;                     rowp[PC_M + c] = cv1(v);
;                     if (i == 15) __builtin_amdgcn_sched_barrier(0);
;                 }
;     }
.LBB0_402:
	s_and_saveexec_b64 s[28:29], s[4:5]
	s_cbranch_execz .LBB0_391
	s_waitcnt vmcnt(0)
	v_and_b32_e32 v2, 31, v176
	v_lshrrev_b32_e32 v3, 3, v176
	v_and_b32_e32 v3, 4, v3
	v_mul_u32_u24_e32 v3, 0x2c00, v3
	v_lshl_add_u32 v4, v2, 1, v3
	v_lshl_add_u32 v4, v232, 7, v4
	v_add_u32_e32 v5, 0x1800, v4
	global_load_ushort v117, v5, s[6:7] offset:-2048
	global_load_ushort v149, v5, s[6:7] offset:2048
	global_load_ushort v118, v5, s[6:7] offset:-1984
	global_load_ushort v150, v5, s[6:7] offset:2112
	v_add_u32_e32 v6, 0x4400, v4
	global_load_ushort v119, v6, s[6:7] offset:-2048
	global_load_ushort v151, v6, s[6:7] offset:2048
	global_load_ushort v120, v6, s[6:7] offset:-1984
	global_load_ushort v152, v6, s[6:7] offset:2112
	v_add_u32_e32 v7, 0x7000, v4
	global_load_ushort v121, v7, s[6:7] offset:-2048
	global_load_ushort v153, v7, s[6:7] offset:2048
	global_load_ushort v122, v7, s[6:7] offset:-1984
	global_load_ushort v154, v7, s[6:7] offset:2112
	v_add_u32_e32 v8, 0x9c00, v4
	global_load_ushort v123, v8, s[6:7] offset:-2048
	global_load_ushort v155, v8, s[6:7] offset:2048
	global_load_ushort v124, v8, s[6:7] offset:-1984
	global_load_ushort v166, v8, s[6:7] offset:2112
	v_add_u32_e32 v9, 0x17800, v4
	global_load_ushort v125, v9, s[6:7] offset:-2048
	global_load_ushort v167, v9, s[6:7] offset:2048
	global_load_ushort v126, v9, s[6:7] offset:-1984
	global_load_ushort v168, v9, s[6:7] offset:2112
	v_add_u32_e32 v10, 0x1a400, v4
	global_load_ushort v127, v10, s[6:7] offset:-2048
	global_load_ushort v169, v10, s[6:7] offset:2048
	global_load_ushort v128, v10, s[6:7] offset:-1984
	global_load_ushort v170, v10, s[6:7] offset:2112
	v_add_u32_e32 v11, 0x1d000, v4
	global_load_ushort v129, v11, s[6:7] offset:-2048
	global_load_ushort v171, v11, s[6:7] offset:2048
	global_load_ushort v130, v11, s[6:7] offset:-1984
	global_load_ushort v172, v11, s[6:7] offset:2112
	v_add_u32_e32 v12, 0x1fc00, v4
	global_load_ushort v131, v12, s[6:7] offset:-2048
	global_load_ushort v173, v12, s[6:7] offset:2048
	global_load_ushort v132, v12, s[6:7] offset:-1984
	global_load_ushort v174, v12, s[6:7] offset:2112
	v_add_u32_e32 v13, 0x2d800, v4
	global_load_ushort v133, v13, s[6:7] offset:-2048
	global_load_ushort v175, v13, s[6:7] offset:2048
	global_load_ushort v134, v13, s[6:7] offset:-1984
	global_load_ushort v180, v13, s[6:7] offset:2112
	v_add_u32_e32 v14, 0x30400, v4
	global_load_ushort v135, v14, s[6:7] offset:-2048
	global_load_ushort v181, v14, s[6:7] offset:2048
	global_load_ushort v136, v14, s[6:7] offset:-1984
	global_load_ushort v182, v14, s[6:7] offset:2112
	v_add_u32_e32 v15, 0x33000, v4
	global_load_ushort v137, v15, s[6:7] offset:-2048
	global_load_ushort v183, v15, s[6:7] offset:2048
	global_load_ushort v138, v15, s[6:7] offset:-1984
	global_load_ushort v184, v15, s[6:7] offset:2112
	v_add_u32_e32 v112, 0x35c00, v4
	global_load_ushort v139, v112, s[6:7] offset:-2048
	global_load_ushort v219, v112, s[6:7] offset:2048
	global_load_ushort v140, v112, s[6:7] offset:-1984
	global_load_ushort v233, v112, s[6:7] offset:2112
	v_add_u32_e32 v113, 0x43800, v4
	global_load_ushort v141, v113, s[6:7] offset:-2048
	global_load_ushort v234, v113, s[6:7] offset:2048
	global_load_ushort v142, v113, s[6:7] offset:-1984
	global_load_ushort v235, v113, s[6:7] offset:2112
	v_add_u32_e32 v114, 0x46400, v4
	global_load_ushort v143, v114, s[6:7] offset:-2048
	global_load_ushort v236, v114, s[6:7] offset:2048
	global_load_ushort v144, v114, s[6:7] offset:-1984
	global_load_ushort v237, v114, s[6:7] offset:2112
	v_add_u32_e32 v115, 0x49000, v4
	global_load_ushort v145, v115, s[6:7] offset:-2048
	global_load_ushort v238, v115, s[6:7] offset:2048
	global_load_ushort v146, v115, s[6:7] offset:-1984
	global_load_ushort v239, v115, s[6:7] offset:2112
	v_add_u32_e32 v116, 0x4bc00, v4
	global_load_ushort v147, v116, s[6:7] offset:-2048
	global_load_ushort v240, v116, s[6:7] offset:2048
	global_load_ushort v148, v116, s[6:7] offset:-1984
	global_load_ushort v241, v116, s[6:7] offset:2112
	s_waitcnt vmcnt(0)
	v_fma_mixlo_f16 v117, v96, v117, v149 op_sel_hi:[0,1,1]
	global_store_short v5, v117, s[6:7] offset:2048
	v_fma_mixlo_f16 v118, v80, v118, v150 op_sel_hi:[0,1,1]
	global_store_short v5, v118, s[6:7] offset:2112
	v_fma_mixlo_f16 v119, v97, v119, v151 op_sel_hi:[0,1,1]
	global_store_short v6, v119, s[6:7] offset:2048
	v_fma_mixlo_f16 v120, v81, v120, v152 op_sel_hi:[0,1,1]
	global_store_short v6, v120, s[6:7] offset:2112
	v_fma_mixlo_f16 v121, v98, v121, v153 op_sel_hi:[0,1,1]
	global_store_short v7, v121, s[6:7] offset:2048
	v_fma_mixlo_f16 v122, v82, v122, v154 op_sel_hi:[0,1,1]
	global_store_short v7, v122, s[6:7] offset:2112
	v_fma_mixlo_f16 v123, v99, v123, v155 op_sel_hi:[0,1,1]
	global_store_short v8, v123, s[6:7] offset:2048
	v_fma_mixlo_f16 v124, v83, v124, v166 op_sel_hi:[0,1,1]
	global_store_short v8, v124, s[6:7] offset:2112
	v_fma_mixlo_f16 v125, v100, v125, v167 op_sel_hi:[0,1,1]
	global_store_short v9, v125, s[6:7] offset:2048
	v_fma_mixlo_f16 v126, v84, v126, v168 op_sel_hi:[0,1,1]
	global_store_short v9, v126, s[6:7] offset:2112
	v_fma_mixlo_f16 v127, v101, v127, v169 op_sel_hi:[0,1,1]
	global_store_short v10, v127, s[6:7] offset:2048
	v_fma_mixlo_f16 v128, v85, v128, v170 op_sel_hi:[0,1,1]
	global_store_short v10, v128, s[6:7] offset:2112
	v_fma_mixlo_f16 v129, v102, v129, v171 op_sel_hi:[0,1,1]
	global_store_short v11, v129, s[6:7] offset:2048
	v_fma_mixlo_f16 v130, v86, v130, v172 op_sel_hi:[0,1,1]
	global_store_short v11, v130, s[6:7] offset:2112
	v_fma_mixlo_f16 v131, v103, v131, v173 op_sel_hi:[0,1,1]
	global_store_short v12, v131, s[6:7] offset:2048
; DI int otid() { int t = threadIdx.x; asm volatile("" : "+v"(t)); return t; }
; DI bf16_t cv1(float x) { return (bf16_t)(pk2(x, 0.f) & 0xffffu); }
; DI float bf2f(bf16_t v) { return (float)__builtin_bit_cast(_Float16, v); }
; DI int crow(int i, int h) { return (i & 3) + 8 * (i >> 2) + 4 * h; }
;     DI void operator()(int unit, const f32x16 (&acc)[MT][NT]) const {
;         const int lane = otid() & 63, r = lane & 31, h = lane >> 5;
; #pragma unroll
;         for (int mi = 0; mi < MT; ++mi)
; #pragma unroll
;             for (int nj = 0; nj < NT; ++nj)
; #pragma unroll
;                 for (int i = 0; i < 16; ++i) {
;                     bf16_t* rowp = priv + (mi * 32 + crow(i, h) + (mi == 2 ? d2 : 0)) * PRIVW; const int c = unit * UW + nj * 32 + r;
;                     float v = bf2f(rowp[gcol + c]) * acc[mi][nj][i];
;                     if (SECOND) v += bf2f(rowp[PC_M + c]);
;                     rowp[PC_M + c] = cv1(v);
;                     if (i == 15) __builtin_amdgcn_sched_barrier(0);
;                 }
;     }
	v_fma_mixlo_f16 v132, v87, v132, v174 op_sel_hi:[0,1,1]
	global_store_short v12, v132, s[6:7] offset:2112
	v_fma_mixlo_f16 v133, v104, v133, v175 op_sel_hi:[0,1,1]
	global_store_short v13, v133, s[6:7] offset:2048
	v_fma_mixlo_f16 v134, v88, v134, v180 op_sel_hi:[0,1,1]
	global_store_short v13, v134, s[6:7] offset:2112
	v_fma_mixlo_f16 v135, v105, v135, v181 op_sel_hi:[0,1,1]
	global_store_short v14, v135, s[6:7] offset:2048
	v_fma_mixlo_f16 v136, v89, v136, v182 op_sel_hi:[0,1,1]
	global_store_short v14, v136, s[6:7] offset:2112
	v_fma_mixlo_f16 v137, v106, v137, v183 op_sel_hi:[0,1,1]
	global_store_short v15, v137, s[6:7] offset:2048
	v_fma_mixlo_f16 v138, v90, v138, v184 op_sel_hi:[0,1,1]
	global_store_short v15, v138, s[6:7] offset:2112
	v_fma_mixlo_f16 v139, v107, v139, v219 op_sel_hi:[0,1,1]
	global_store_short v112, v139, s[6:7] offset:2048
	v_fma_mixlo_f16 v140, v91, v140, v233 op_sel_hi:[0,1,1]
	global_store_short v112, v140, s[6:7] offset:2112
	v_fma_mixlo_f16 v141, v108, v141, v234 op_sel_hi:[0,1,1]
	global_store_short v113, v141, s[6:7] offset:2048
	v_fma_mixlo_f16 v142, v92, v142, v235 op_sel_hi:[0,1,1]
	global_store_short v113, v142, s[6:7] offset:2112
	v_fma_mixlo_f16 v143, v109, v143, v236 op_sel_hi:[0,1,1]
	global_store_short v114, v143, s[6:7] offset:2048
	v_fma_mixlo_f16 v144, v93, v144, v237 op_sel_hi:[0,1,1]
	global_store_short v114, v144, s[6:7] offset:2112
	v_fma_mixlo_f16 v145, v110, v145, v238 op_sel_hi:[0,1,1]
	global_store_short v115, v145, s[6:7] offset:2048
	v_fma_mixlo_f16 v146, v94, v146, v239 op_sel_hi:[0,1,1]
	global_store_short v115, v146, s[6:7] offset:2112
	v_fma_mixlo_f16 v147, v111, v147, v240 op_sel_hi:[0,1,1]
	global_store_short v116, v147, s[6:7] offset:2048
	v_fma_mixlo_f16 v148, v95, v148, v241 op_sel_hi:[0,1,1]
	global_store_short v116, v148, s[6:7] offset:2112
	v_add_u32_e32 v5, 0x59800, v4
	global_load_ushort v117, v5, s[6:7] offset:-2048
	global_load_ushort v149, v5, s[6:7] offset:2048
	global_load_ushort v118, v5, s[6:7] offset:-1984
	global_load_ushort v150, v5, s[6:7] offset:2112
	v_add_u32_e32 v6, 0x5c400, v4
	global_load_ushort v119, v6, s[6:7] offset:-2048
	global_load_ushort v151, v6, s[6:7] offset:2048
	global_load_ushort v120, v6, s[6:7] offset:-1984
	global_load_ushort v152, v6, s[6:7] offset:2112
	v_add_u32_e32 v7, 0x5f000, v4
	global_load_ushort v121, v7, s[6:7] offset:-2048
	global_load_ushort v153, v7, s[6:7] offset:2048
	global_load_ushort v122, v7, s[6:7] offset:-1984
	global_load_ushort v154, v7, s[6:7] offset:2112
	v_add_u32_e32 v8, 0x61c00, v4
	global_load_ushort v123, v8, s[6:7] offset:-2048
	global_load_ushort v155, v8, s[6:7] offset:2048
	global_load_ushort v124, v8, s[6:7] offset:-1984
	global_load_ushort v166, v8, s[6:7] offset:2112
	v_add_u32_e32 v9, 0x6f800, v4
	global_load_ushort v125, v9, s[6:7] offset:-2048
	global_load_ushort v167, v9, s[6:7] offset:2048
	global_load_ushort v126, v9, s[6:7] offset:-1984
	global_load_ushort v168, v9, s[6:7] offset:2112
	v_add_u32_e32 v10, 0x72400, v4
	global_load_ushort v127, v10, s[6:7] offset:-2048
	global_load_ushort v169, v10, s[6:7] offset:2048
	global_load_ushort v128, v10, s[6:7] offset:-1984
	global_load_ushort v170, v10, s[6:7] offset:2112
	v_add_u32_e32 v11, 0x75000, v4
	global_load_ushort v129, v11, s[6:7] offset:-2048
	global_load_ushort v171, v11, s[6:7] offset:2048
	global_load_ushort v130, v11, s[6:7] offset:-1984
	global_load_ushort v172, v11, s[6:7] offset:2112
	v_add_u32_e32 v12, 0x77c00, v4
	global_load_ushort v131, v12, s[6:7] offset:-2048
	global_load_ushort v173, v12, s[6:7] offset:2048
	global_load_ushort v132, v12, s[6:7] offset:-1984
	global_load_ushort v174, v12, s[6:7] offset:2112
	v_add_u32_e32 v13, 0x85800, v4
	global_load_ushort v133, v13, s[6:7] offset:-2048
	global_load_ushort v175, v13, s[6:7] offset:2048
	global_load_ushort v134, v13, s[6:7] offset:-1984
	global_load_ushort v180, v13, s[6:7] offset:2112
	v_add_u32_e32 v14, 0x88400, v4
	global_load_ushort v135, v14, s[6:7] offset:-2048
	global_load_ushort v181, v14, s[6:7] offset:2048
	global_load_ushort v136, v14, s[6:7] offset:-1984
	global_load_ushort v182, v14, s[6:7] offset:2112
	v_add_u32_e32 v15, 0x8b000, v4
	global_load_ushort v137, v15, s[6:7] offset:-2048
	global_load_ushort v183, v15, s[6:7] offset:2048
	global_load_ushort v138, v15, s[6:7] offset:-1984
	global_load_ushort v184, v15, s[6:7] offset:2112
	v_add_u32_e32 v112, 0x8dc00, v4
	global_load_ushort v139, v112, s[6:7] offset:-2048
	global_load_ushort v219, v112, s[6:7] offset:2048
	global_load_ushort v140, v112, s[6:7] offset:-1984
	global_load_ushort v233, v112, s[6:7] offset:2112
	v_add_u32_e32 v113, 0x9b800, v4
	global_load_ushort v141, v113, s[6:7] offset:-2048
	global_load_ushort v234, v113, s[6:7] offset:2048
	global_load_ushort v142, v113, s[6:7] offset:-1984
	global_load_ushort v235, v113, s[6:7] offset:2112
	v_add_u32_e32 v114, 0x9e400, v4
	global_load_ushort v143, v114, s[6:7] offset:-2048
	global_load_ushort v236, v114, s[6:7] offset:2048
	global_load_ushort v144, v114, s[6:7] offset:-1984
	global_load_ushort v237, v114, s[6:7] offset:2112
	v_add_u32_e32 v115, 0xa1000, v4
	global_load_ushort v145, v115, s[6:7] offset:-2048
	global_load_ushort v238, v115, s[6:7] offset:2048
	global_load_ushort v146, v115, s[6:7] offset:-1984
	global_load_ushort v239, v115, s[6:7] offset:2112
	v_add_u32_e32 v116, 0xa3c00, v4
	global_load_ushort v147, v116, s[6:7] offset:-2048
	global_load_ushort v240, v116, s[6:7] offset:2048
	global_load_ushort v148, v116, s[6:7] offset:-1984
	global_load_ushort v241, v116, s[6:7] offset:2112
	s_waitcnt vmcnt(0)
; DI int otid() { int t = threadIdx.x; asm volatile("" : "+v"(t)); return t; }
; DI bf16_t cv1(float x) { return (bf16_t)(pk2(x, 0.f) & 0xffffu); }
; DI float bf2f(bf16_t v) { return (float)__builtin_bit_cast(_Float16, v); }
; DI int crow(int i, int h) { return (i & 3) + 8 * (i >> 2) + 4 * h; }
;     DI void operator()(int unit, const f32x16 (&acc)[MT][NT]) const {
;         const int lane = otid() & 63, r = lane & 31, h = lane >> 5;
; #pragma unroll
;         for (int mi = 0; mi < MT; ++mi)
; #pragma unroll
;             for (int nj = 0; nj < NT; ++nj)
; #pragma unroll
;                 for (int i = 0; i < 16; ++i) {
;                     bf16_t* rowp = priv + (mi * 32 + crow(i, h) + (mi == 2 ? d2 : 0)) * PRIVW; const int c = unit * UW + nj * 32 + r;
;                     float v = bf2f(rowp[gcol + c]) * acc[mi][nj][i];
;                     if (SECOND) v += bf2f(rowp[PC_M + c]);
;                     rowp[PC_M + c] = cv1(v);
;                     if (i == 15) __builtin_amdgcn_sched_barrier(0);
;                 }
;     }
	v_fma_mixlo_f16 v117, v64, v117, v149 op_sel_hi:[0,1,1]
	global_store_short v5, v117, s[6:7] offset:2048
	v_fma_mixlo_f16 v118, v48, v118, v150 op_sel_hi:[0,1,1]
	global_store_short v5, v118, s[6:7] offset:2112
	v_fma_mixlo_f16 v119, v65, v119, v151 op_sel_hi:[0,1,1]
	global_store_short v6, v119, s[6:7] offset:2048
	v_fma_mixlo_f16 v120, v49, v120, v152 op_sel_hi:[0,1,1]
	global_store_short v6, v120, s[6:7] offset:2112
	v_fma_mixlo_f16 v121, v66, v121, v153 op_sel_hi:[0,1,1]
	global_store_short v7, v121, s[6:7] offset:2048
	v_fma_mixlo_f16 v122, v50, v122, v154 op_sel_hi:[0,1,1]
	global_store_short v7, v122, s[6:7] offset:2112
	v_fma_mixlo_f16 v123, v67, v123, v155 op_sel_hi:[0,1,1]
	global_store_short v8, v123, s[6:7] offset:2048
	v_fma_mixlo_f16 v124, v51, v124, v166 op_sel_hi:[0,1,1]
	global_store_short v8, v124, s[6:7] offset:2112
	v_fma_mixlo_f16 v125, v68, v125, v167 op_sel_hi:[0,1,1]
	global_store_short v9, v125, s[6:7] offset:2048
	v_fma_mixlo_f16 v126, v52, v126, v168 op_sel_hi:[0,1,1]
	global_store_short v9, v126, s[6:7] offset:2112
	v_fma_mixlo_f16 v127, v69, v127, v169 op_sel_hi:[0,1,1]
	global_store_short v10, v127, s[6:7] offset:2048
	v_fma_mixlo_f16 v128, v53, v128, v170 op_sel_hi:[0,1,1]
	global_store_short v10, v128, s[6:7] offset:2112
	v_fma_mixlo_f16 v129, v70, v129, v171 op_sel_hi:[0,1,1]
	global_store_short v11, v129, s[6:7] offset:2048
	v_fma_mixlo_f16 v130, v54, v130, v172 op_sel_hi:[0,1,1]
	global_store_short v11, v130, s[6:7] offset:2112
	v_fma_mixlo_f16 v131, v71, v131, v173 op_sel_hi:[0,1,1]
	global_store_short v12, v131, s[6:7] offset:2048
	v_fma_mixlo_f16 v132, v55, v132, v174 op_sel_hi:[0,1,1]
	global_store_short v12, v132, s[6:7] offset:2112
	v_fma_mixlo_f16 v133, v72, v133, v175 op_sel_hi:[0,1,1]
	global_store_short v13, v133, s[6:7] offset:2048
	v_fma_mixlo_f16 v134, v56, v134, v180 op_sel_hi:[0,1,1]
	global_store_short v13, v134, s[6:7] offset:2112
	v_fma_mixlo_f16 v135, v73, v135, v181 op_sel_hi:[0,1,1]
	global_store_short v14, v135, s[6:7] offset:2048
	v_fma_mixlo_f16 v136, v57, v136, v182 op_sel_hi:[0,1,1]
	global_store_short v14, v136, s[6:7] offset:2112
	v_fma_mixlo_f16 v137, v74, v137, v183 op_sel_hi:[0,1,1]
	global_store_short v15, v137, s[6:7] offset:2048
	v_fma_mixlo_f16 v138, v58, v138, v184 op_sel_hi:[0,1,1]
	global_store_short v15, v138, s[6:7] offset:2112
	v_fma_mixlo_f16 v139, v75, v139, v219 op_sel_hi:[0,1,1]
	global_store_short v112, v139, s[6:7] offset:2048
	v_fma_mixlo_f16 v140, v59, v140, v233 op_sel_hi:[0,1,1]
	global_store_short v112, v140, s[6:7] offset:2112
	v_fma_mixlo_f16 v141, v76, v141, v234 op_sel_hi:[0,1,1]
	global_store_short v113, v141, s[6:7] offset:2048
	v_fma_mixlo_f16 v142, v60, v142, v235 op_sel_hi:[0,1,1]
	global_store_short v113, v142, s[6:7] offset:2112
	v_fma_mixlo_f16 v143, v77, v143, v236 op_sel_hi:[0,1,1]
	global_store_short v114, v143, s[6:7] offset:2048
	v_fma_mixlo_f16 v144, v61, v144, v237 op_sel_hi:[0,1,1]
	global_store_short v114, v144, s[6:7] offset:2112
	v_fma_mixlo_f16 v145, v78, v145, v238 op_sel_hi:[0,1,1]
	global_store_short v115, v145, s[6:7] offset:2048
	v_fma_mixlo_f16 v146, v62, v146, v239 op_sel_hi:[0,1,1]
	global_store_short v115, v146, s[6:7] offset:2112
	v_fma_mixlo_f16 v147, v79, v147, v240 op_sel_hi:[0,1,1]
	global_store_short v116, v147, s[6:7] offset:2048
	v_fma_mixlo_f16 v148, v63, v148, v241 op_sel_hi:[0,1,1]
	global_store_short v116, v148, s[6:7] offset:2112
	s_sub_i32 s100, 0x4000, s62
	s_mul_i32 s101, s100, 0x2c00
	v_add_u32_e32 v3, s101, v4
	v_add_u32_e32 v5, 0x1800, v3
	global_load_ushort v117, v5, s[6:7] offset:-2048
	global_load_ushort v149, v5, s[6:7] offset:2048
	global_load_ushort v118, v5, s[6:7] offset:-1984
	global_load_ushort v150, v5, s[6:7] offset:2112
	v_add_u32_e32 v6, 0x4400, v3
	global_load_ushort v119, v6, s[6:7] offset:-2048
	global_load_ushort v151, v6, s[6:7] offset:2048
	global_load_ushort v120, v6, s[6:7] offset:-1984
	global_load_ushort v152, v6, s[6:7] offset:2112
	v_add_u32_e32 v7, 0x7000, v3
	global_load_ushort v121, v7, s[6:7] offset:-2048
	global_load_ushort v153, v7, s[6:7] offset:2048
	global_load_ushort v122, v7, s[6:7] offset:-1984
	global_load_ushort v154, v7, s[6:7] offset:2112
	v_add_u32_e32 v8, 0x9c00, v3
	global_load_ushort v123, v8, s[6:7] offset:-2048
	global_load_ushort v155, v8, s[6:7] offset:2048
	global_load_ushort v124, v8, s[6:7] offset:-1984
	global_load_ushort v166, v8, s[6:7] offset:2112
	v_add_u32_e32 v9, 0x17800, v3
	global_load_ushort v125, v9, s[6:7] offset:-2048
	global_load_ushort v167, v9, s[6:7] offset:2048
	global_load_ushort v126, v9, s[6:7] offset:-1984
	global_load_ushort v168, v9, s[6:7] offset:2112
	v_add_u32_e32 v10, 0x1a400, v3
	global_load_ushort v127, v10, s[6:7] offset:-2048
	global_load_ushort v169, v10, s[6:7] offset:2048
	global_load_ushort v128, v10, s[6:7] offset:-1984
	global_load_ushort v170, v10, s[6:7] offset:2112
	v_add_u32_e32 v11, 0x1d000, v3
	global_load_ushort v129, v11, s[6:7] offset:-2048
	global_load_ushort v171, v11, s[6:7] offset:2048
	global_load_ushort v130, v11, s[6:7] offset:-1984
	global_load_ushort v172, v11, s[6:7] offset:2112
	v_add_u32_e32 v12, 0x1fc00, v3
	global_load_ushort v131, v12, s[6:7] offset:-2048
	global_load_ushort v173, v12, s[6:7] offset:2048
	global_load_ushort v132, v12, s[6:7] offset:-1984
	global_load_ushort v174, v12, s[6:7] offset:2112
; DI int otid() { int t = threadIdx.x; asm volatile("" : "+v"(t)); return t; }
; DI bf16_t cv1(float x) { return (bf16_t)(pk2(x, 0.f) & 0xffffu); }
; DI float bf2f(bf16_t v) { return (float)__builtin_bit_cast(_Float16, v); }
; DI int crow(int i, int h) { return (i & 3) + 8 * (i >> 2) + 4 * h; }
;     DI void operator()(int unit, const f32x16 (&acc)[MT][NT]) const {
;         const int lane = otid() & 63, r = lane & 31, h = lane >> 5;
; #pragma unroll
;         for (int mi = 0; mi < MT; ++mi)
; #pragma unroll
;             for (int nj = 0; nj < NT; ++nj)
; #pragma unroll
;                 for (int i = 0; i < 16; ++i) {
;                     bf16_t* rowp = priv + (mi * 32 + crow(i, h) + (mi == 2 ? d2 : 0)) * PRIVW; const int c = unit * UW + nj * 32 + r;
;                     float v = bf2f(rowp[gcol + c]) * acc[mi][nj][i];
;                     if (SECOND) v += bf2f(rowp[PC_M + c]);
;                     rowp[PC_M + c] = cv1(v);
;                     if (i == 15) __builtin_amdgcn_sched_barrier(0);
;                 }
;     }
	v_add_u32_e32 v13, 0x2d800, v3
	global_load_ushort v133, v13, s[6:7] offset:-2048
	global_load_ushort v175, v13, s[6:7] offset:2048
	global_load_ushort v134, v13, s[6:7] offset:-1984
	global_load_ushort v180, v13, s[6:7] offset:2112
	v_add_u32_e32 v14, 0x30400, v3
	global_load_ushort v135, v14, s[6:7] offset:-2048
	global_load_ushort v181, v14, s[6:7] offset:2048
	global_load_ushort v136, v14, s[6:7] offset:-1984
	global_load_ushort v182, v14, s[6:7] offset:2112
	v_add_u32_e32 v15, 0x33000, v3
	global_load_ushort v137, v15, s[6:7] offset:-2048
	global_load_ushort v183, v15, s[6:7] offset:2048
	global_load_ushort v138, v15, s[6:7] offset:-1984
	global_load_ushort v184, v15, s[6:7] offset:2112
	v_add_u32_e32 v112, 0x35c00, v3
	global_load_ushort v139, v112, s[6:7] offset:-2048
	global_load_ushort v219, v112, s[6:7] offset:2048
	global_load_ushort v140, v112, s[6:7] offset:-1984
	global_load_ushort v233, v112, s[6:7] offset:2112
	v_add_u32_e32 v113, 0x43800, v3
	global_load_ushort v141, v113, s[6:7] offset:-2048
	global_load_ushort v234, v113, s[6:7] offset:2048
	global_load_ushort v142, v113, s[6:7] offset:-1984
	global_load_ushort v235, v113, s[6:7] offset:2112
	v_add_u32_e32 v114, 0x46400, v3
	global_load_ushort v143, v114, s[6:7] offset:-2048
	global_load_ushort v236, v114, s[6:7] offset:2048
	global_load_ushort v144, v114, s[6:7] offset:-1984
	global_load_ushort v237, v114, s[6:7] offset:2112
	v_add_u32_e32 v115, 0x49000, v3
	global_load_ushort v145, v115, s[6:7] offset:-2048
	global_load_ushort v238, v115, s[6:7] offset:2048
	global_load_ushort v146, v115, s[6:7] offset:-1984
	global_load_ushort v239, v115, s[6:7] offset:2112
	v_add_u32_e32 v116, 0x4bc00, v3
	global_load_ushort v147, v116, s[6:7] offset:-2048
	global_load_ushort v240, v116, s[6:7] offset:2048
	global_load_ushort v148, v116, s[6:7] offset:-1984
	global_load_ushort v241, v116, s[6:7] offset:2112
	s_waitcnt vmcnt(0)
	v_fma_mixlo_f16 v117, v32, v117, v149 op_sel_hi:[0,1,1]
	global_store_short v5, v117, s[6:7] offset:2048
	v_fma_mixlo_f16 v118, v16, v118, v150 op_sel_hi:[0,1,1]
	global_store_short v5, v118, s[6:7] offset:2112
	v_fma_mixlo_f16 v119, v33, v119, v151 op_sel_hi:[0,1,1]
	global_store_short v6, v119, s[6:7] offset:2048
	v_fma_mixlo_f16 v120, v17, v120, v152 op_sel_hi:[0,1,1]
	global_store_short v6, v120, s[6:7] offset:2112
	v_fma_mixlo_f16 v121, v34, v121, v153 op_sel_hi:[0,1,1]
	global_store_short v7, v121, s[6:7] offset:2048
	v_fma_mixlo_f16 v122, v18, v122, v154 op_sel_hi:[0,1,1]
	global_store_short v7, v122, s[6:7] offset:2112
	v_fma_mixlo_f16 v123, v35, v123, v155 op_sel_hi:[0,1,1]
	global_store_short v8, v123, s[6:7] offset:2048
	v_fma_mixlo_f16 v124, v19, v124, v166 op_sel_hi:[0,1,1]
	global_store_short v8, v124, s[6:7] offset:2112
	v_fma_mixlo_f16 v125, v36, v125, v167 op_sel_hi:[0,1,1]
	global_store_short v9, v125, s[6:7] offset:2048
	v_fma_mixlo_f16 v126, v20, v126, v168 op_sel_hi:[0,1,1]
	global_store_short v9, v126, s[6:7] offset:2112
	v_fma_mixlo_f16 v127, v37, v127, v169 op_sel_hi:[0,1,1]
	global_store_short v10, v127, s[6:7] offset:2048
	v_fma_mixlo_f16 v128, v21, v128, v170 op_sel_hi:[0,1,1]
	global_store_short v10, v128, s[6:7] offset:2112
	v_fma_mixlo_f16 v129, v38, v129, v171 op_sel_hi:[0,1,1]
	global_store_short v11, v129, s[6:7] offset:2048
	v_fma_mixlo_f16 v130, v22, v130, v172 op_sel_hi:[0,1,1]
	global_store_short v11, v130, s[6:7] offset:2112
	v_fma_mixlo_f16 v131, v39, v131, v173 op_sel_hi:[0,1,1]
	global_store_short v12, v131, s[6:7] offset:2048
	v_fma_mixlo_f16 v132, v23, v132, v174 op_sel_hi:[0,1,1]
	global_store_short v12, v132, s[6:7] offset:2112
	v_fma_mixlo_f16 v133, v40, v133, v175 op_sel_hi:[0,1,1]
	global_store_short v13, v133, s[6:7] offset:2048
	v_fma_mixlo_f16 v134, v24, v134, v180 op_sel_hi:[0,1,1]
	global_store_short v13, v134, s[6:7] offset:2112
	v_fma_mixlo_f16 v135, v41, v135, v181 op_sel_hi:[0,1,1]
	global_store_short v14, v135, s[6:7] offset:2048
	v_fma_mixlo_f16 v136, v25, v136, v182 op_sel_hi:[0,1,1]
	global_store_short v14, v136, s[6:7] offset:2112
	v_fma_mixlo_f16 v137, v42, v137, v183 op_sel_hi:[0,1,1]
	global_store_short v15, v137, s[6:7] offset:2048
	v_fma_mixlo_f16 v138, v26, v138, v184 op_sel_hi:[0,1,1]
	global_store_short v15, v138, s[6:7] offset:2112
	v_fma_mixlo_f16 v139, v43, v139, v219 op_sel_hi:[0,1,1]
	global_store_short v112, v139, s[6:7] offset:2048
	v_fma_mixlo_f16 v140, v27, v140, v233 op_sel_hi:[0,1,1]
	global_store_short v112, v140, s[6:7] offset:2112
	v_fma_mixlo_f16 v141, v44, v141, v234 op_sel_hi:[0,1,1]
	global_store_short v113, v141, s[6:7] offset:2048
	v_fma_mixlo_f16 v142, v28, v142, v235 op_sel_hi:[0,1,1]
	global_store_short v113, v142, s[6:7] offset:2112
	v_fma_mixlo_f16 v143, v45, v143, v236 op_sel_hi:[0,1,1]
	global_store_short v114, v143, s[6:7] offset:2048
	v_fma_mixlo_f16 v144, v29, v144, v237 op_sel_hi:[0,1,1]
	global_store_short v114, v144, s[6:7] offset:2112
	v_fma_mixlo_f16 v145, v46, v145, v238 op_sel_hi:[0,1,1]
	global_store_short v115, v145, s[6:7] offset:2048
	v_fma_mixlo_f16 v146, v30, v146, v239 op_sel_hi:[0,1,1]
	global_store_short v115, v146, s[6:7] offset:2112
	v_fma_mixlo_f16 v147, v47, v147, v240 op_sel_hi:[0,1,1]
	global_store_short v116, v147, s[6:7] offset:2048
	v_fma_mixlo_f16 v148, v31, v148, v241 op_sel_hi:[0,1,1]
	global_store_short v116, v148, s[6:7] offset:2112
	s_branch .LBB0_391

; DI int otid() { int t = threadIdx.x; asm volatile("" : "+v"(t)); return t; }
; DI int crow(int i, int h) { return (i & 3) + 8 * (i >> 2) + 4 * h; }
;     DI void operator()(int unit, const f32x16 (&acc)[MT][NT]) const {
;         const int lane = otid() & 63, r = lane & 31, h = lane >> 5;
; #pragma unroll
;         for (int mi = 0; mi < MT; ++mi)
; #pragma unroll
;             for (int nj = 0; nj < NT; ++nj)
; #pragma unroll
;                 for (int i = 0; i < 16; ++i) { float* q = x + ((mi * 32 + crow(i, h) + (mi == 2 ? d2 : 0)) * DM + unit * UW + nj * 32 + r); *q = *q + acc[mi][nj][i]; if (i == 15) __builtin_amdgcn_sched_barrier(0); }
;     }
.LBB0_416:
	s_and_saveexec_b64 s[56:57], s[4:5]
	s_cbranch_execz .LBB0_405
	s_waitcnt vmcnt(0)
	v_and_b32_e32 v2, 31, v176
	v_lshlrev_b32_e32 v3, 9, v176
	v_and_b32_e32 v3, 0x4000, v3
	v_lshl_or_b32 v4, v2, 2, v3
	v_lshl_add_u32 v4, v232, 8, v4
	v_add_u32_e32 v5, 0x1000, v4
	global_load_dword v13, v5, s[0:1] offset:-4096
	global_load_dword v14, v5, s[0:1] offset:-3968
	global_load_dword v15, v5, s[0:1] offset:0
	global_load_dword v112, v5, s[0:1] offset:128
	v_add_u32_e32 v6, 0x3000, v4
	global_load_dword v113, v6, s[0:1] offset:-4096
	global_load_dword v114, v6, s[0:1] offset:-3968
	global_load_dword v115, v6, s[0:1] offset:0
	global_load_dword v116, v6, s[0:1] offset:128
	v_add_u32_e32 v7, 0x9000, v4
	global_load_dword v117, v7, s[0:1] offset:-4096
	global_load_dword v118, v7, s[0:1] offset:-3968
	global_load_dword v119, v7, s[0:1] offset:0
	global_load_dword v120, v7, s[0:1] offset:128
	v_add_u32_e32 v8, 0xb000, v4
	global_load_dword v121, v8, s[0:1] offset:-4096
	global_load_dword v122, v8, s[0:1] offset:-3968
	global_load_dword v123, v8, s[0:1] offset:0
	global_load_dword v124, v8, s[0:1] offset:128
	v_add_u32_e32 v9, 0x11000, v4
	global_load_dword v125, v9, s[0:1] offset:-4096
	global_load_dword v126, v9, s[0:1] offset:-3968
	global_load_dword v127, v9, s[0:1] offset:0
	global_load_dword v128, v9, s[0:1] offset:128
	v_add_u32_e32 v10, 0x13000, v4
	global_load_dword v129, v10, s[0:1] offset:-4096
	global_load_dword v130, v10, s[0:1] offset:-3968
	global_load_dword v131, v10, s[0:1] offset:0
	global_load_dword v132, v10, s[0:1] offset:128
	v_add_u32_e32 v11, 0x19000, v4
	global_load_dword v133, v11, s[0:1] offset:-4096
	global_load_dword v134, v11, s[0:1] offset:-3968
	global_load_dword v135, v11, s[0:1] offset:0
	global_load_dword v136, v11, s[0:1] offset:128
	v_add_u32_e32 v12, 0x1b000, v4
	global_load_dword v137, v12, s[0:1] offset:-4096
	global_load_dword v138, v12, s[0:1] offset:-3968
	global_load_dword v139, v12, s[0:1] offset:0
	global_load_dword v140, v12, s[0:1] offset:128
	s_waitcnt vmcnt(0)
	v_add_f32_e32 v13, v96, v13
	global_store_dword v5, v13, s[0:1] offset:-4096
	v_add_f32_e32 v14, v80, v14
	global_store_dword v5, v14, s[0:1] offset:-3968
	v_add_f32_e32 v15, v97, v15
	global_store_dword v5, v15, s[0:1] offset:0
	v_add_f32_e32 v112, v81, v112
	global_store_dword v5, v112, s[0:1] offset:128
	v_add_f32_e32 v113, v98, v113
	global_store_dword v6, v113, s[0:1] offset:-4096
	v_add_f32_e32 v114, v82, v114
	global_store_dword v6, v114, s[0:1] offset:-3968
	v_add_f32_e32 v115, v99, v115
	global_store_dword v6, v115, s[0:1] offset:0
	v_add_f32_e32 v116, v83, v116
	global_store_dword v6, v116, s[0:1] offset:128
	v_add_f32_e32 v117, v100, v117
	global_store_dword v7, v117, s[0:1] offset:-4096
	v_add_f32_e32 v118, v84, v118
	global_store_dword v7, v118, s[0:1] offset:-3968
	v_add_f32_e32 v119, v101, v119
	global_store_dword v7, v119, s[0:1] offset:0
	v_add_f32_e32 v120, v85, v120
	global_store_dword v7, v120, s[0:1] offset:128
	v_add_f32_e32 v121, v102, v121
	global_store_dword v8, v121, s[0:1] offset:-4096
	v_add_f32_e32 v122, v86, v122
	global_store_dword v8, v122, s[0:1] offset:-3968
	v_add_f32_e32 v123, v103, v123
	global_store_dword v8, v123, s[0:1] offset:0
	v_add_f32_e32 v124, v87, v124
	global_store_dword v8, v124, s[0:1] offset:128
	v_add_f32_e32 v125, v104, v125
	global_store_dword v9, v125, s[0:1] offset:-4096
	v_add_f32_e32 v126, v88, v126
	global_store_dword v9, v126, s[0:1] offset:-3968
	v_add_f32_e32 v127, v105, v127
	global_store_dword v9, v127, s[0:1] offset:0
	v_add_f32_e32 v128, v89, v128
	global_store_dword v9, v128, s[0:1] offset:128
	v_add_f32_e32 v129, v106, v129
	global_store_dword v10, v129, s[0:1] offset:-4096
	v_add_f32_e32 v130, v90, v130
	global_store_dword v10, v130, s[0:1] offset:-3968
	v_add_f32_e32 v131, v107, v131
	global_store_dword v10, v131, s[0:1] offset:0
	v_add_f32_e32 v132, v91, v132
	global_store_dword v10, v132, s[0:1] offset:128
	v_add_f32_e32 v133, v108, v133
	global_store_dword v11, v133, s[0:1] offset:-4096
	v_add_f32_e32 v134, v92, v134
	global_store_dword v11, v134, s[0:1] offset:-3968
	v_add_f32_e32 v135, v109, v135
	global_store_dword v11, v135, s[0:1] offset:0
	v_add_f32_e32 v136, v93, v136
	global_store_dword v11, v136, s[0:1] offset:128
	v_add_f32_e32 v137, v110, v137
	global_store_dword v12, v137, s[0:1] offset:-4096
	v_add_f32_e32 v138, v94, v138
	global_store_dword v12, v138, s[0:1] offset:-3968
	v_add_f32_e32 v139, v111, v139
	global_store_dword v12, v139, s[0:1] offset:0
	v_add_f32_e32 v140, v95, v140
	global_store_dword v12, v140, s[0:1] offset:128
	v_add_u32_e32 v5, 0x21000, v4
	global_load_dword v13, v5, s[0:1] offset:-4096
	global_load_dword v14, v5, s[0:1] offset:-3968
	global_load_dword v15, v5, s[0:1] offset:0
	global_load_dword v112, v5, s[0:1] offset:128
	v_add_u32_e32 v6, 0x23000, v4
	global_load_dword v113, v6, s[0:1] offset:-4096
	global_load_dword v114, v6, s[0:1] offset:-3968
	global_load_dword v115, v6, s[0:1] offset:0
	global_load_dword v116, v6, s[0:1] offset:128
	v_add_u32_e32 v7, 0x29000, v4
	global_load_dword v117, v7, s[0:1] offset:-4096
	global_load_dword v118, v7, s[0:1] offset:-3968
	global_load_dword v119, v7, s[0:1] offset:0
	global_load_dword v120, v7, s[0:1] offset:128
	v_add_u32_e32 v8, 0x2b000, v4
	global_load_dword v121, v8, s[0:1] offset:-4096
	global_load_dword v122, v8, s[0:1] offset:-3968
	global_load_dword v123, v8, s[0:1] offset:0
	global_load_dword v124, v8, s[0:1] offset:128
	v_add_u32_e32 v9, 0x31000, v4
	global_load_dword v125, v9, s[0:1] offset:-4096
	global_load_dword v126, v9, s[0:1] offset:-3968
	global_load_dword v127, v9, s[0:1] offset:0
	global_load_dword v128, v9, s[0:1] offset:128
	v_add_u32_e32 v10, 0x33000, v4
	global_load_dword v129, v10, s[0:1] offset:-4096
	global_load_dword v130, v10, s[0:1] offset:-3968
	global_load_dword v131, v10, s[0:1] offset:0
	global_load_dword v132, v10, s[0:1] offset:128
	v_add_u32_e32 v11, 0x39000, v4
	global_load_dword v133, v11, s[0:1] offset:-4096
	global_load_dword v134, v11, s[0:1] offset:-3968
	global_load_dword v135, v11, s[0:1] offset:0
	global_load_dword v136, v11, s[0:1] offset:128
	v_add_u32_e32 v12, 0x3b000, v4
	global_load_dword v137, v12, s[0:1] offset:-4096
	global_load_dword v138, v12, s[0:1] offset:-3968
	global_load_dword v139, v12, s[0:1] offset:0
	global_load_dword v140, v12, s[0:1] offset:128
	s_waitcnt vmcnt(0)
; DI int otid() { int t = threadIdx.x; asm volatile("" : "+v"(t)); return t; }
; DI int crow(int i, int h) { return (i & 3) + 8 * (i >> 2) + 4 * h; }
;     DI void operator()(int unit, const f32x16 (&acc)[MT][NT]) const {
;         const int lane = otid() & 63, r = lane & 31, h = lane >> 5;
; #pragma unroll
;         for (int mi = 0; mi < MT; ++mi)
; #pragma unroll
;             for (int nj = 0; nj < NT; ++nj)
; #pragma unroll
;                 for (int i = 0; i < 16; ++i) { float* q = x + ((mi * 32 + crow(i, h) + (mi == 2 ? d2 : 0)) * DM + unit * UW + nj * 32 + r); *q = *q + acc[mi][nj][i]; if (i == 15) __builtin_amdgcn_sched_barrier(0); }
;     }
	v_add_f32_e32 v13, v64, v13
	global_store_dword v5, v13, s[0:1] offset:-4096
	v_add_f32_e32 v14, v48, v14
	global_store_dword v5, v14, s[0:1] offset:-3968
	v_add_f32_e32 v15, v65, v15
	global_store_dword v5, v15, s[0:1] offset:0
	v_add_f32_e32 v112, v49, v112
	global_store_dword v5, v112, s[0:1] offset:128
	v_add_f32_e32 v113, v66, v113
	global_store_dword v6, v113, s[0:1] offset:-4096
	v_add_f32_e32 v114, v50, v114
	global_store_dword v6, v114, s[0:1] offset:-3968
	v_add_f32_e32 v115, v67, v115
	global_store_dword v6, v115, s[0:1] offset:0
	v_add_f32_e32 v116, v51, v116
	global_store_dword v6, v116, s[0:1] offset:128
	v_add_f32_e32 v117, v68, v117
	global_store_dword v7, v117, s[0:1] offset:-4096
	v_add_f32_e32 v118, v52, v118
	global_store_dword v7, v118, s[0:1] offset:-3968
	v_add_f32_e32 v119, v69, v119
	global_store_dword v7, v119, s[0:1] offset:0
	v_add_f32_e32 v120, v53, v120
	global_store_dword v7, v120, s[0:1] offset:128
	v_add_f32_e32 v121, v70, v121
	global_store_dword v8, v121, s[0:1] offset:-4096
	v_add_f32_e32 v122, v54, v122
	global_store_dword v8, v122, s[0:1] offset:-3968
	v_add_f32_e32 v123, v71, v123
	global_store_dword v8, v123, s[0:1] offset:0
	v_add_f32_e32 v124, v55, v124
	global_store_dword v8, v124, s[0:1] offset:128
	v_add_f32_e32 v125, v72, v125
	global_store_dword v9, v125, s[0:1] offset:-4096
	v_add_f32_e32 v126, v56, v126
	global_store_dword v9, v126, s[0:1] offset:-3968
	v_add_f32_e32 v127, v73, v127
	global_store_dword v9, v127, s[0:1] offset:0
	v_add_f32_e32 v128, v57, v128
	global_store_dword v9, v128, s[0:1] offset:128
	v_add_f32_e32 v129, v74, v129
	global_store_dword v10, v129, s[0:1] offset:-4096
	v_add_f32_e32 v130, v58, v130
	global_store_dword v10, v130, s[0:1] offset:-3968
	v_add_f32_e32 v131, v75, v131
	global_store_dword v10, v131, s[0:1] offset:0
	v_add_f32_e32 v132, v59, v132
	global_store_dword v10, v132, s[0:1] offset:128
	v_add_f32_e32 v133, v76, v133
	global_store_dword v11, v133, s[0:1] offset:-4096
	v_add_f32_e32 v134, v60, v134
	global_store_dword v11, v134, s[0:1] offset:-3968
	v_add_f32_e32 v135, v77, v135
	global_store_dword v11, v135, s[0:1] offset:0
	v_add_f32_e32 v136, v61, v136
	global_store_dword v11, v136, s[0:1] offset:128
	v_add_f32_e32 v137, v78, v137
	global_store_dword v12, v137, s[0:1] offset:-4096
	v_add_f32_e32 v138, v62, v138
	global_store_dword v12, v138, s[0:1] offset:-3968
	v_add_f32_e32 v139, v79, v139
	global_store_dword v12, v139, s[0:1] offset:0
	v_add_f32_e32 v140, v63, v140
	global_store_dword v12, v140, s[0:1] offset:128
	v_lshl_add_u32 v3, s59, 12, v4
	v_add_u32_e32 v5, 0x1000, v3
	global_load_dword v13, v5, s[0:1] offset:-4096
	global_load_dword v14, v5, s[0:1] offset:-3968
	global_load_dword v15, v5, s[0:1] offset:0
	global_load_dword v112, v5, s[0:1] offset:128
	v_add_u32_e32 v6, 0x3000, v3
	global_load_dword v113, v6, s[0:1] offset:-4096
	global_load_dword v114, v6, s[0:1] offset:-3968
	global_load_dword v115, v6, s[0:1] offset:0
	global_load_dword v116, v6, s[0:1] offset:128
	v_add_u32_e32 v7, 0x9000, v3
	global_load_dword v117, v7, s[0:1] offset:-4096
	global_load_dword v118, v7, s[0:1] offset:-3968
	global_load_dword v119, v7, s[0:1] offset:0
	global_load_dword v120, v7, s[0:1] offset:128
	v_add_u32_e32 v8, 0xb000, v3
	global_load_dword v121, v8, s[0:1] offset:-4096
	global_load_dword v122, v8, s[0:1] offset:-3968
	global_load_dword v123, v8, s[0:1] offset:0
	global_load_dword v124, v8, s[0:1] offset:128
	v_add_u32_e32 v9, 0x11000, v3
	global_load_dword v125, v9, s[0:1] offset:-4096
	global_load_dword v126, v9, s[0:1] offset:-3968
	global_load_dword v127, v9, s[0:1] offset:0
	global_load_dword v128, v9, s[0:1] offset:128
	v_add_u32_e32 v10, 0x13000, v3
	global_load_dword v129, v10, s[0:1] offset:-4096
	global_load_dword v130, v10, s[0:1] offset:-3968
	global_load_dword v131, v10, s[0:1] offset:0
	global_load_dword v132, v10, s[0:1] offset:128
	v_add_u32_e32 v11, 0x19000, v3
	global_load_dword v133, v11, s[0:1] offset:-4096
	global_load_dword v134, v11, s[0:1] offset:-3968
	global_load_dword v135, v11, s[0:1] offset:0
	global_load_dword v136, v11, s[0:1] offset:128
	v_add_u32_e32 v12, 0x1b000, v3
	global_load_dword v137, v12, s[0:1] offset:-4096
	global_load_dword v138, v12, s[0:1] offset:-3968
	global_load_dword v139, v12, s[0:1] offset:0
	global_load_dword v140, v12, s[0:1] offset:128
	s_waitcnt vmcnt(0)
	v_add_f32_e32 v13, v32, v13
	global_store_dword v5, v13, s[0:1] offset:-4096
	v_add_f32_e32 v14, v16, v14
	global_store_dword v5, v14, s[0:1] offset:-3968
	v_add_f32_e32 v15, v33, v15
	global_store_dword v5, v15, s[0:1] offset:0
	v_add_f32_e32 v112, v17, v112
	global_store_dword v5, v112, s[0:1] offset:128
	v_add_f32_e32 v113, v34, v113
	global_store_dword v6, v113, s[0:1] offset:-4096
	v_add_f32_e32 v114, v18, v114
	global_store_dword v6, v114, s[0:1] offset:-3968
	v_add_f32_e32 v115, v35, v115
	global_store_dword v6, v115, s[0:1] offset:0
	v_add_f32_e32 v116, v19, v116
	global_store_dword v6, v116, s[0:1] offset:128
	v_add_f32_e32 v117, v36, v117
	global_store_dword v7, v117, s[0:1] offset:-4096
	v_add_f32_e32 v118, v20, v118
	global_store_dword v7, v118, s[0:1] offset:-3968
	v_add_f32_e32 v119, v37, v119
	global_store_dword v7, v119, s[0:1] offset:0
	v_add_f32_e32 v120, v21, v120
	global_store_dword v7, v120, s[0:1] offset:128
	v_add_f32_e32 v121, v38, v121
	global_store_dword v8, v121, s[0:1] offset:-4096
	v_add_f32_e32 v122, v22, v122
	global_store_dword v8, v122, s[0:1] offset:-3968
	v_add_f32_e32 v123, v39, v123
	global_store_dword v8, v123, s[0:1] offset:0
	v_add_f32_e32 v124, v23, v124
	global_store_dword v8, v124, s[0:1] offset:128
	v_add_f32_e32 v125, v40, v125
	global_store_dword v9, v125, s[0:1] offset:-4096
	v_add_f32_e32 v126, v24, v126
	global_store_dword v9, v126, s[0:1] offset:-3968
	v_add_f32_e32 v127, v41, v127
	global_store_dword v9, v127, s[0:1] offset:0
	v_add_f32_e32 v128, v25, v128
	global_store_dword v9, v128, s[0:1] offset:128
	v_add_f32_e32 v129, v42, v129
	global_store_dword v10, v129, s[0:1] offset:-4096
	v_add_f32_e32 v130, v26, v130
	global_store_dword v10, v130, s[0:1] offset:-3968
	v_add_f32_e32 v131, v43, v131
	global_store_dword v10, v131, s[0:1] offset:0
	v_add_f32_e32 v132, v27, v132
	global_store_dword v10, v132, s[0:1] offset:128
	v_add_f32_e32 v133, v44, v133
	global_store_dword v11, v133, s[0:1] offset:-4096
	v_add_f32_e32 v134, v28, v134
	global_store_dword v11, v134, s[0:1] offset:-3968
	v_add_f32_e32 v135, v45, v135
	global_store_dword v11, v135, s[0:1] offset:0
	v_add_f32_e32 v136, v29, v136
	global_store_dword v11, v136, s[0:1] offset:128
	v_add_f32_e32 v137, v46, v137
	global_store_dword v12, v137, s[0:1] offset:-4096
	v_add_f32_e32 v138, v30, v138
	global_store_dword v12, v138, s[0:1] offset:-3968
	v_add_f32_e32 v139, v47, v139
	global_store_dword v12, v139, s[0:1] offset:0
	v_add_f32_e32 v140, v31, v140
	global_store_dword v12, v140, s[0:1] offset:128
	s_branch .LBB0_405

; DI int otid() { int t = threadIdx.x; asm volatile("" : "+v"(t)); return t; }
; DI int crow(int i, int h) { return (i & 3) + 8 * (i >> 2) + 4 * h; }
;     DI void operator()(int unit, const f32x16 (&acc)[MT][NT]) const {
;         const int lane = otid() & 63, r = lane & 31, h = lane >> 5;
; #pragma unroll
;         for (int mi = 0; mi < MT; ++mi)
; #pragma unroll
;             for (int nj = 0; nj < NT; ++nj)
; #pragma unroll
;                 for (int i = 0; i < 16; ++i) { float* q = x + ((mi * 32 + crow(i, h) + (mi == 2 ? d2 : 0)) * DM + unit * UW + nj * 32 + r); *q = *q + acc[mi][nj][i]; if (i == 15) __builtin_amdgcn_sched_barrier(0); }
;     }
.LBB0_455:
	s_and_saveexec_b64 s[28:29], s[4:5]
	s_cbranch_execz .LBB0_444
	s_waitcnt vmcnt(0)
	v_and_b32_e32 v2, 31, v176
	v_lshlrev_b32_e32 v3, 9, v176
	v_and_b32_e32 v3, 0x4000, v3
	v_lshl_or_b32 v4, v2, 2, v3
	v_lshl_add_u32 v4, v238, 8, v4
	v_add_u32_e32 v5, 0x1000, v4
	global_load_dword v13, v5, s[0:1] offset:-4096
	global_load_dword v14, v5, s[0:1] offset:-3968
	global_load_dword v15, v5, s[0:1] offset:0
	global_load_dword v112, v5, s[0:1] offset:128
	v_add_u32_e32 v6, 0x3000, v4
	global_load_dword v113, v6, s[0:1] offset:-4096
	global_load_dword v114, v6, s[0:1] offset:-3968
	global_load_dword v115, v6, s[0:1] offset:0
	global_load_dword v116, v6, s[0:1] offset:128
	v_add_u32_e32 v7, 0x9000, v4
	global_load_dword v117, v7, s[0:1] offset:-4096
	global_load_dword v118, v7, s[0:1] offset:-3968
	global_load_dword v119, v7, s[0:1] offset:0
	global_load_dword v120, v7, s[0:1] offset:128
	v_add_u32_e32 v8, 0xb000, v4
	global_load_dword v121, v8, s[0:1] offset:-4096
	global_load_dword v122, v8, s[0:1] offset:-3968
	global_load_dword v123, v8, s[0:1] offset:0
	global_load_dword v124, v8, s[0:1] offset:128
	v_add_u32_e32 v9, 0x11000, v4
	global_load_dword v125, v9, s[0:1] offset:-4096
	global_load_dword v126, v9, s[0:1] offset:-3968
	global_load_dword v127, v9, s[0:1] offset:0
	global_load_dword v128, v9, s[0:1] offset:128
	v_add_u32_e32 v10, 0x13000, v4
	global_load_dword v129, v10, s[0:1] offset:-4096
	global_load_dword v130, v10, s[0:1] offset:-3968
	global_load_dword v131, v10, s[0:1] offset:0
	global_load_dword v132, v10, s[0:1] offset:128
	v_add_u32_e32 v11, 0x19000, v4
	global_load_dword v133, v11, s[0:1] offset:-4096
	global_load_dword v134, v11, s[0:1] offset:-3968
	global_load_dword v135, v11, s[0:1] offset:0
	global_load_dword v136, v11, s[0:1] offset:128
	v_add_u32_e32 v12, 0x1b000, v4
	global_load_dword v137, v12, s[0:1] offset:-4096
	global_load_dword v138, v12, s[0:1] offset:-3968
	global_load_dword v139, v12, s[0:1] offset:0
	global_load_dword v140, v12, s[0:1] offset:128
	s_waitcnt vmcnt(0)
	v_add_f32_e32 v13, v96, v13
	global_store_dword v5, v13, s[0:1] offset:-4096
	v_add_f32_e32 v14, v80, v14
	global_store_dword v5, v14, s[0:1] offset:-3968
	v_add_f32_e32 v15, v97, v15
	global_store_dword v5, v15, s[0:1] offset:0
	v_add_f32_e32 v112, v81, v112
	global_store_dword v5, v112, s[0:1] offset:128
	v_add_f32_e32 v113, v98, v113
	global_store_dword v6, v113, s[0:1] offset:-4096
	v_add_f32_e32 v114, v82, v114
	global_store_dword v6, v114, s[0:1] offset:-3968
	v_add_f32_e32 v115, v99, v115
	global_store_dword v6, v115, s[0:1] offset:0
	v_add_f32_e32 v116, v83, v116
	global_store_dword v6, v116, s[0:1] offset:128
	v_add_f32_e32 v117, v100, v117
	global_store_dword v7, v117, s[0:1] offset:-4096
	v_add_f32_e32 v118, v84, v118
	global_store_dword v7, v118, s[0:1] offset:-3968
	v_add_f32_e32 v119, v101, v119
	global_store_dword v7, v119, s[0:1] offset:0
	v_add_f32_e32 v120, v85, v120
	global_store_dword v7, v120, s[0:1] offset:128
	v_add_f32_e32 v121, v102, v121
	global_store_dword v8, v121, s[0:1] offset:-4096
	v_add_f32_e32 v122, v86, v122
	global_store_dword v8, v122, s[0:1] offset:-3968
	v_add_f32_e32 v123, v103, v123
	global_store_dword v8, v123, s[0:1] offset:0
	v_add_f32_e32 v124, v87, v124
	global_store_dword v8, v124, s[0:1] offset:128
	v_add_f32_e32 v125, v104, v125
	global_store_dword v9, v125, s[0:1] offset:-4096
	v_add_f32_e32 v126, v88, v126
	global_store_dword v9, v126, s[0:1] offset:-3968
	v_add_f32_e32 v127, v105, v127
	global_store_dword v9, v127, s[0:1] offset:0
	v_add_f32_e32 v128, v89, v128
	global_store_dword v9, v128, s[0:1] offset:128
	v_add_f32_e32 v129, v106, v129
	global_store_dword v10, v129, s[0:1] offset:-4096
	v_add_f32_e32 v130, v90, v130
	global_store_dword v10, v130, s[0:1] offset:-3968
	v_add_f32_e32 v131, v107, v131
	global_store_dword v10, v131, s[0:1] offset:0
	v_add_f32_e32 v132, v91, v132
	global_store_dword v10, v132, s[0:1] offset:128
	v_add_f32_e32 v133, v108, v133
	global_store_dword v11, v133, s[0:1] offset:-4096
	v_add_f32_e32 v134, v92, v134
	global_store_dword v11, v134, s[0:1] offset:-3968
	v_add_f32_e32 v135, v109, v135
	global_store_dword v11, v135, s[0:1] offset:0
	v_add_f32_e32 v136, v93, v136
	global_store_dword v11, v136, s[0:1] offset:128
	v_add_f32_e32 v137, v110, v137
	global_store_dword v12, v137, s[0:1] offset:-4096
	v_add_f32_e32 v138, v94, v138
	global_store_dword v12, v138, s[0:1] offset:-3968
	v_add_f32_e32 v139, v111, v139
	global_store_dword v12, v139, s[0:1] offset:0
	v_add_f32_e32 v140, v95, v140
	global_store_dword v12, v140, s[0:1] offset:128
	v_add_u32_e32 v5, 0x21000, v4
	global_load_dword v13, v5, s[0:1] offset:-4096
	global_load_dword v14, v5, s[0:1] offset:-3968
	global_load_dword v15, v5, s[0:1] offset:0
	global_load_dword v112, v5, s[0:1] offset:128
	v_add_u32_e32 v6, 0x23000, v4
	global_load_dword v113, v6, s[0:1] offset:-4096
	global_load_dword v114, v6, s[0:1] offset:-3968
	global_load_dword v115, v6, s[0:1] offset:0
	global_load_dword v116, v6, s[0:1] offset:128
	v_add_u32_e32 v7, 0x29000, v4
	global_load_dword v117, v7, s[0:1] offset:-4096
	global_load_dword v118, v7, s[0:1] offset:-3968
	global_load_dword v119, v7, s[0:1] offset:0
	global_load_dword v120, v7, s[0:1] offset:128
	v_add_u32_e32 v8, 0x2b000, v4
	global_load_dword v121, v8, s[0:1] offset:-4096
	global_load_dword v122, v8, s[0:1] offset:-3968
	global_load_dword v123, v8, s[0:1] offset:0
	global_load_dword v124, v8, s[0:1] offset:128
	v_add_u32_e32 v9, 0x31000, v4
	global_load_dword v125, v9, s[0:1] offset:-4096
	global_load_dword v126, v9, s[0:1] offset:-3968
	global_load_dword v127, v9, s[0:1] offset:0
	global_load_dword v128, v9, s[0:1] offset:128
	v_add_u32_e32 v10, 0x33000, v4
	global_load_dword v129, v10, s[0:1] offset:-4096
	global_load_dword v130, v10, s[0:1] offset:-3968
	global_load_dword v131, v10, s[0:1] offset:0
	global_load_dword v132, v10, s[0:1] offset:128
	v_add_u32_e32 v11, 0x39000, v4
	global_load_dword v133, v11, s[0:1] offset:-4096
	global_load_dword v134, v11, s[0:1] offset:-3968
	global_load_dword v135, v11, s[0:1] offset:0
	global_load_dword v136, v11, s[0:1] offset:128
	v_add_u32_e32 v12, 0x3b000, v4
	global_load_dword v137, v12, s[0:1] offset:-4096
	global_load_dword v138, v12, s[0:1] offset:-3968
	global_load_dword v139, v12, s[0:1] offset:0
	global_load_dword v140, v12, s[0:1] offset:128
	s_waitcnt vmcnt(0)
; DI int otid() { int t = threadIdx.x; asm volatile("" : "+v"(t)); return t; }
; DI int crow(int i, int h) { return (i & 3) + 8 * (i >> 2) + 4 * h; }
;     DI void operator()(int unit, const f32x16 (&acc)[MT][NT]) const {
;         const int lane = otid() & 63, r = lane & 31, h = lane >> 5;
; #pragma unroll
;         for (int mi = 0; mi < MT; ++mi)
; #pragma unroll
;             for (int nj = 0; nj < NT; ++nj)
; #pragma unroll
;                 for (int i = 0; i < 16; ++i) { float* q = x + ((mi * 32 + crow(i, h) + (mi == 2 ? d2 : 0)) * DM + unit * UW + nj * 32 + r); *q = *q + acc[mi][nj][i]; if (i == 15) __builtin_amdgcn_sched_barrier(0); }
;     }
	v_add_f32_e32 v13, v64, v13
	global_store_dword v5, v13, s[0:1] offset:-4096
	v_add_f32_e32 v14, v48, v14
	global_store_dword v5, v14, s[0:1] offset:-3968
	v_add_f32_e32 v15, v65, v15
	global_store_dword v5, v15, s[0:1] offset:0
	v_add_f32_e32 v112, v49, v112
	global_store_dword v5, v112, s[0:1] offset:128
	v_add_f32_e32 v113, v66, v113
	global_store_dword v6, v113, s[0:1] offset:-4096
	v_add_f32_e32 v114, v50, v114
	global_store_dword v6, v114, s[0:1] offset:-3968
	v_add_f32_e32 v115, v67, v115
	global_store_dword v6, v115, s[0:1] offset:0
	v_add_f32_e32 v116, v51, v116
	global_store_dword v6, v116, s[0:1] offset:128
	v_add_f32_e32 v117, v68, v117
	global_store_dword v7, v117, s[0:1] offset:-4096
	v_add_f32_e32 v118, v52, v118
	global_store_dword v7, v118, s[0:1] offset:-3968
	v_add_f32_e32 v119, v69, v119
	global_store_dword v7, v119, s[0:1] offset:0
	v_add_f32_e32 v120, v53, v120
	global_store_dword v7, v120, s[0:1] offset:128
	v_add_f32_e32 v121, v70, v121
	global_store_dword v8, v121, s[0:1] offset:-4096
	v_add_f32_e32 v122, v54, v122
	global_store_dword v8, v122, s[0:1] offset:-3968
	v_add_f32_e32 v123, v71, v123
	global_store_dword v8, v123, s[0:1] offset:0
	v_add_f32_e32 v124, v55, v124
	global_store_dword v8, v124, s[0:1] offset:128
	v_add_f32_e32 v125, v72, v125
	global_store_dword v9, v125, s[0:1] offset:-4096
	v_add_f32_e32 v126, v56, v126
	global_store_dword v9, v126, s[0:1] offset:-3968
	v_add_f32_e32 v127, v73, v127
	global_store_dword v9, v127, s[0:1] offset:0
	v_add_f32_e32 v128, v57, v128
	global_store_dword v9, v128, s[0:1] offset:128
	v_add_f32_e32 v129, v74, v129
	global_store_dword v10, v129, s[0:1] offset:-4096
	v_add_f32_e32 v130, v58, v130
	global_store_dword v10, v130, s[0:1] offset:-3968
	v_add_f32_e32 v131, v75, v131
	global_store_dword v10, v131, s[0:1] offset:0
	v_add_f32_e32 v132, v59, v132
	global_store_dword v10, v132, s[0:1] offset:128
	v_add_f32_e32 v133, v76, v133
	global_store_dword v11, v133, s[0:1] offset:-4096
	v_add_f32_e32 v134, v60, v134
	global_store_dword v11, v134, s[0:1] offset:-3968
	v_add_f32_e32 v135, v77, v135
	global_store_dword v11, v135, s[0:1] offset:0
	v_add_f32_e32 v136, v61, v136
	global_store_dword v11, v136, s[0:1] offset:128
	v_add_f32_e32 v137, v78, v137
	global_store_dword v12, v137, s[0:1] offset:-4096
	v_add_f32_e32 v138, v62, v138
	global_store_dword v12, v138, s[0:1] offset:-3968
	v_add_f32_e32 v139, v79, v139
	global_store_dword v12, v139, s[0:1] offset:0
	v_add_f32_e32 v140, v63, v140
	global_store_dword v12, v140, s[0:1] offset:128
	v_lshl_add_u32 v3, s59, 12, v4
	v_add_u32_e32 v5, 0x1000, v3
	global_load_dword v13, v5, s[0:1] offset:-4096
	global_load_dword v14, v5, s[0:1] offset:-3968
	global_load_dword v15, v5, s[0:1] offset:0
	global_load_dword v112, v5, s[0:1] offset:128
	v_add_u32_e32 v6, 0x3000, v3
	global_load_dword v113, v6, s[0:1] offset:-4096
	global_load_dword v114, v6, s[0:1] offset:-3968
	global_load_dword v115, v6, s[0:1] offset:0
	global_load_dword v116, v6, s[0:1] offset:128
	v_add_u32_e32 v7, 0x9000, v3
	global_load_dword v117, v7, s[0:1] offset:-4096
	global_load_dword v118, v7, s[0:1] offset:-3968
	global_load_dword v119, v7, s[0:1] offset:0
	global_load_dword v120, v7, s[0:1] offset:128
	v_add_u32_e32 v8, 0xb000, v3
	global_load_dword v121, v8, s[0:1] offset:-4096
	global_load_dword v122, v8, s[0:1] offset:-3968
	global_load_dword v123, v8, s[0:1] offset:0
	global_load_dword v124, v8, s[0:1] offset:128
	v_add_u32_e32 v9, 0x11000, v3
	global_load_dword v125, v9, s[0:1] offset:-4096
	global_load_dword v126, v9, s[0:1] offset:-3968
	global_load_dword v127, v9, s[0:1] offset:0
	global_load_dword v128, v9, s[0:1] offset:128
	v_add_u32_e32 v10, 0x13000, v3
	global_load_dword v129, v10, s[0:1] offset:-4096
	global_load_dword v130, v10, s[0:1] offset:-3968
	global_load_dword v131, v10, s[0:1] offset:0
	global_load_dword v132, v10, s[0:1] offset:128
	v_add_u32_e32 v11, 0x19000, v3
	global_load_dword v133, v11, s[0:1] offset:-4096
	global_load_dword v134, v11, s[0:1] offset:-3968
	global_load_dword v135, v11, s[0:1] offset:0
	global_load_dword v136, v11, s[0:1] offset:128
	v_add_u32_e32 v12, 0x1b000, v3
	global_load_dword v137, v12, s[0:1] offset:-4096
	global_load_dword v138, v12, s[0:1] offset:-3968
	global_load_dword v139, v12, s[0:1] offset:0
	global_load_dword v140, v12, s[0:1] offset:128
	s_waitcnt vmcnt(0)
	v_add_f32_e32 v13, v32, v13
	global_store_dword v5, v13, s[0:1] offset:-4096
	v_add_f32_e32 v14, v16, v14
	global_store_dword v5, v14, s[0:1] offset:-3968
	v_add_f32_e32 v15, v33, v15
	global_store_dword v5, v15, s[0:1] offset:0
	v_add_f32_e32 v112, v17, v112
	global_store_dword v5, v112, s[0:1] offset:128
	v_add_f32_e32 v113, v34, v113
	global_store_dword v6, v113, s[0:1] offset:-4096
	v_add_f32_e32 v114, v18, v114
	global_store_dword v6, v114, s[0:1] offset:-3968
	v_add_f32_e32 v115, v35, v115
	global_store_dword v6, v115, s[0:1] offset:0
	v_add_f32_e32 v116, v19, v116
	global_store_dword v6, v116, s[0:1] offset:128
	v_add_f32_e32 v117, v36, v117
	global_store_dword v7, v117, s[0:1] offset:-4096
	v_add_f32_e32 v118, v20, v118
	global_store_dword v7, v118, s[0:1] offset:-3968
	v_add_f32_e32 v119, v37, v119
	global_store_dword v7, v119, s[0:1] offset:0
	v_add_f32_e32 v120, v21, v120
	global_store_dword v7, v120, s[0:1] offset:128
	v_add_f32_e32 v121, v38, v121
	global_store_dword v8, v121, s[0:1] offset:-4096
	v_add_f32_e32 v122, v22, v122
	global_store_dword v8, v122, s[0:1] offset:-3968
	v_add_f32_e32 v123, v39, v123
	global_store_dword v8, v123, s[0:1] offset:0
	v_add_f32_e32 v124, v23, v124
	global_store_dword v8, v124, s[0:1] offset:128
	v_add_f32_e32 v125, v40, v125
	global_store_dword v9, v125, s[0:1] offset:-4096
	v_add_f32_e32 v126, v24, v126
	global_store_dword v9, v126, s[0:1] offset:-3968
	v_add_f32_e32 v127, v41, v127
	global_store_dword v9, v127, s[0:1] offset:0
	v_add_f32_e32 v128, v25, v128
	global_store_dword v9, v128, s[0:1] offset:128
	v_add_f32_e32 v129, v42, v129
	global_store_dword v10, v129, s[0:1] offset:-4096
	v_add_f32_e32 v130, v26, v130
	global_store_dword v10, v130, s[0:1] offset:-3968
	v_add_f32_e32 v131, v43, v131
	global_store_dword v10, v131, s[0:1] offset:0
	v_add_f32_e32 v132, v27, v132
	global_store_dword v10, v132, s[0:1] offset:128
	v_add_f32_e32 v133, v44, v133
	global_store_dword v11, v133, s[0:1] offset:-4096
	v_add_f32_e32 v134, v28, v134
	global_store_dword v11, v134, s[0:1] offset:-3968
	v_add_f32_e32 v135, v45, v135
	global_store_dword v11, v135, s[0:1] offset:0
	v_add_f32_e32 v136, v29, v136
	global_store_dword v11, v136, s[0:1] offset:128
	v_add_f32_e32 v137, v46, v137
	global_store_dword v12, v137, s[0:1] offset:-4096
	v_add_f32_e32 v138, v30, v138
	global_store_dword v12, v138, s[0:1] offset:-3968
	v_add_f32_e32 v139, v47, v139
	global_store_dword v12, v139, s[0:1] offset:0
	v_add_f32_e32 v140, v31, v140
	global_store_dword v12, v140, s[0:1] offset:128
	s_branch .LBB0_444

; #define MFMA32(a, b, c) __builtin_amdgcn_mfma_f32_32x32x16_f16((a), (b), (c), 0, 0, 0)
; template <int K, class Epi>
; DI void gemm64_res(const bf16_t* A, int lda, const bf16_t* Wp, int NU, unsigned char* lds, const Epi& epi) {
;     ...
; #pragma unroll 1
;         for (int kk = 0; kk < KS; kk += PD) {
; #pragma unroll
;             for (int s = 0; s < PD; ++s) {
;                 const int ks = kk + s, ksr = (ks + rot) & (KS - 1);
;                 const bf16x8 a0 = *(const bf16x8*)(ab + ksr * 32), a1 = *(const bf16x8*)(ab + 32 * LD + ksr * 32);
; #pragma unroll
;                 for (int j = 0; j < NT; ++j) { acc[0][j] = MFMA32(a0, __builtin_bit_cast(bf16x8, bq[s][j]), acc[0][j]); acc[1][j] = MFMA32(a1, __builtin_bit_cast(bf16x8, bq[s][j]), acc[1][j]); }
;                 int nk = ks + PD; nk = nk < KS ? nk : KS - 1; nk = (nk + rot) & (KS - 1);
; #pragma unroll
;                 for (int j = 0; j < NT; ++j) bq[s][j] = bp[(size_t)nk * kstr + j * 64];
;             }
;         }
.Lkoa2_loop:
	s_and_b32 s5, s3, 31
	s_lshl_b32 s5, s5, 5
	s_add_i32 s3, s3, 1
	v_add_u32_e32 v125, s5, v124
	ds_read_b128 v[148:151], v125
	ds_read_b128 v[152:155], v125 offset:33280
	s_waitcnt vmcnt(15) lgkmcnt(2)
	v_mfma_f32_32x32x16_f16 v[50:65], v[140:143], v[72:75], v[50:65]
	v_mfma_f32_32x32x16_f16 v[18:33], v[144:147], v[72:75], v[18:33]
	s_waitcnt vmcnt(14)
	v_mfma_f32_32x32x16_f16 v[34:49], v[140:143], v[76:79], v[34:49]
	v_mfma_f32_32x32x16_f16 v[2:17], v[144:147], v[76:79], v[2:17]
	s_and_b32 s5, s4, 31
	s_add_i32 s4, s4, 1
	s_mul_i32 s100, s5, 0x8000
	v_lshl_add_u64 v[70:71], v[68:69], 0, s[100:101]
	global_load_dwordx4 v[72:75], v[70:71], off
	global_load_dwordx4 v[76:79], v[70:71], off offset:1024
	s_and_b32 s5, s3, 31
	s_lshl_b32 s5, s5, 5
	s_add_i32 s3, s3, 1
	v_add_u32_e32 v125, s5, v124
	ds_read_b128 v[140:143], v125
	ds_read_b128 v[144:147], v125 offset:33280
	s_waitcnt vmcnt(15) lgkmcnt(2)
	v_mfma_f32_32x32x16_f16 v[50:65], v[148:151], v[80:83], v[50:65]
	v_mfma_f32_32x32x16_f16 v[18:33], v[152:155], v[80:83], v[18:33]
	s_waitcnt vmcnt(14)
	v_mfma_f32_32x32x16_f16 v[34:49], v[148:151], v[84:87], v[34:49]
	v_mfma_f32_32x32x16_f16 v[2:17], v[152:155], v[84:87], v[2:17]
	s_and_b32 s5, s4, 31
	s_add_i32 s4, s4, 1
	s_mul_i32 s100, s5, 0x8000
	v_lshl_add_u64 v[70:71], v[68:69], 0, s[100:101]
	global_load_dwordx4 v[80:83], v[70:71], off
	global_load_dwordx4 v[84:87], v[70:71], off offset:1024
	s_and_b32 s5, s3, 31
	s_lshl_b32 s5, s5, 5
	s_add_i32 s3, s3, 1
	v_add_u32_e32 v125, s5, v124
	ds_read_b128 v[148:151], v125
	ds_read_b128 v[152:155], v125 offset:33280
	s_waitcnt vmcnt(15) lgkmcnt(2)
	v_mfma_f32_32x32x16_f16 v[50:65], v[140:143], v[88:91], v[50:65]
	v_mfma_f32_32x32x16_f16 v[18:33], v[144:147], v[88:91], v[18:33]
	s_waitcnt vmcnt(14)
	v_mfma_f32_32x32x16_f16 v[34:49], v[140:143], v[92:95], v[34:49]
	v_mfma_f32_32x32x16_f16 v[2:17], v[144:147], v[92:95], v[2:17]
	s_and_b32 s5, s4, 31
	s_add_i32 s4, s4, 1
	s_mul_i32 s100, s5, 0x8000
	v_lshl_add_u64 v[70:71], v[68:69], 0, s[100:101]
	global_load_dwordx4 v[88:91], v[70:71], off
	global_load_dwordx4 v[92:95], v[70:71], off offset:1024
	s_and_b32 s5, s3, 31
	s_lshl_b32 s5, s5, 5
	s_add_i32 s3, s3, 1
	v_add_u32_e32 v125, s5, v124
	ds_read_b128 v[140:143], v125
	ds_read_b128 v[144:147], v125 offset:33280
	s_waitcnt vmcnt(15) lgkmcnt(2)
	v_mfma_f32_32x32x16_f16 v[50:65], v[148:151], v[96:99], v[50:65]
	v_mfma_f32_32x32x16_f16 v[18:33], v[152:155], v[96:99], v[18:33]
	s_waitcnt vmcnt(14)
	v_mfma_f32_32x32x16_f16 v[34:49], v[148:151], v[100:103], v[34:49]
	v_mfma_f32_32x32x16_f16 v[2:17], v[152:155], v[100:103], v[2:17]
	s_and_b32 s5, s4, 31
	s_add_i32 s4, s4, 1
	s_mul_i32 s100, s5, 0x8000
	v_lshl_add_u64 v[70:71], v[68:69], 0, s[100:101]
	global_load_dwordx4 v[96:99], v[70:71], off
	global_load_dwordx4 v[100:103], v[70:71], off offset:1024
	s_and_b32 s5, s3, 31
	s_lshl_b32 s5, s5, 5
	s_add_i32 s3, s3, 1
	v_add_u32_e32 v125, s5, v124
	ds_read_b128 v[148:151], v125
	ds_read_b128 v[152:155], v125 offset:33280
	s_waitcnt vmcnt(15) lgkmcnt(2)
	v_mfma_f32_32x32x16_f16 v[50:65], v[140:143], v[104:107], v[50:65]
	v_mfma_f32_32x32x16_f16 v[18:33], v[144:147], v[104:107], v[18:33]
	s_waitcnt vmcnt(14)
	v_mfma_f32_32x32x16_f16 v[34:49], v[140:143], v[108:111], v[34:49]
	v_mfma_f32_32x32x16_f16 v[2:17], v[144:147], v[108:111], v[2:17]
	s_and_b32 s5, s4, 31
	s_add_i32 s4, s4, 1
	s_mul_i32 s100, s5, 0x8000
	v_lshl_add_u64 v[70:71], v[68:69], 0, s[100:101]
	global_load_dwordx4 v[104:107], v[70:71], off
	global_load_dwordx4 v[108:111], v[70:71], off offset:1024
	s_and_b32 s5, s3, 31
	s_lshl_b32 s5, s5, 5
	s_add_i32 s3, s3, 1
	v_add_u32_e32 v125, s5, v124
	ds_read_b128 v[140:143], v125
	ds_read_b128 v[144:147], v125 offset:33280
	s_waitcnt vmcnt(15) lgkmcnt(2)
	v_mfma_f32_32x32x16_f16 v[50:65], v[148:151], v[112:115], v[50:65]
	v_mfma_f32_32x32x16_f16 v[18:33], v[152:155], v[112:115], v[18:33]
	s_waitcnt vmcnt(14)
	v_mfma_f32_32x32x16_f16 v[34:49], v[148:151], v[116:119], v[34:49]
	v_mfma_f32_32x32x16_f16 v[2:17], v[152:155], v[116:119], v[2:17]
	s_and_b32 s5, s4, 31
	s_add_i32 s4, s4, 1
	s_mul_i32 s100, s5, 0x8000
	v_lshl_add_u64 v[70:71], v[68:69], 0, s[100:101]
	global_load_dwordx4 v[112:115], v[70:71], off
	global_load_dwordx4 v[116:119], v[70:71], off offset:1024
	s_and_b32 s5, s3, 31
	s_lshl_b32 s5, s5, 5
	s_add_i32 s3, s3, 1
	v_add_u32_e32 v125, s5, v124
	ds_read_b128 v[148:151], v125
	ds_read_b128 v[152:155], v125 offset:33280
	s_waitcnt vmcnt(15) lgkmcnt(2)
	v_mfma_f32_32x32x16_f16 v[50:65], v[140:143], v[120:123], v[50:65]
	v_mfma_f32_32x32x16_f16 v[18:33], v[144:147], v[120:123], v[18:33]
	s_waitcnt vmcnt(14)
	v_mfma_f32_32x32x16_f16 v[34:49], v[140:143], v[128:131], v[34:49]
	v_mfma_f32_32x32x16_f16 v[2:17], v[144:147], v[128:131], v[2:17]
	s_and_b32 s5, s4, 31
	s_add_i32 s4, s4, 1
	s_mul_i32 s100, s5, 0x8000
	v_lshl_add_u64 v[70:71], v[68:69], 0, s[100:101]
	global_load_dwordx4 v[120:123], v[70:71], off
	global_load_dwordx4 v[128:131], v[70:71], off offset:1024
	s_and_b32 s5, s3, 31
	s_lshl_b32 s5, s5, 5
	s_add_i32 s3, s3, 1
	v_add_u32_e32 v125, s5, v124
	ds_read_b128 v[140:143], v125
	ds_read_b128 v[144:147], v125 offset:33280
	s_waitcnt vmcnt(15) lgkmcnt(2)
	v_mfma_f32_32x32x16_f16 v[50:65], v[148:151], v[132:135], v[50:65]
	v_mfma_f32_32x32x16_f16 v[18:33], v[152:155], v[132:135], v[18:33]
	s_waitcnt vmcnt(14)
	v_mfma_f32_32x32x16_f16 v[34:49], v[148:151], v[136:139], v[34:49]
	v_mfma_f32_32x32x16_f16 v[2:17], v[152:155], v[136:139], v[2:17]
	s_and_b32 s5, s4, 31
	s_add_i32 s4, s4, 1
	s_mul_i32 s100, s5, 0x8000
	v_lshl_add_u64 v[70:71], v[68:69], 0, s[100:101]
	global_load_dwordx4 v[132:135], v[70:71], off
	global_load_dwordx4 v[136:139], v[70:71], off offset:1024
	s_add_i32 s6, s6, -1
	s_cmp_lg_u32 s6, 0
	s_cbranch_scc1 .Lkoa2_loop
; #define MFMA32(a, b, c) __builtin_amdgcn_mfma_f32_32x32x16_f16((a), (b), (c), 0, 0, 0)
; DI int otid() { int t = threadIdx.x; asm volatile("" : "+v"(t)); return t; }
; DI bf16_t cv1(float x) { return (bf16_t)(pk2(x, 0.f) & 0xffffu); }
; DI float bf2f(bf16_t v) { return (float)__builtin_bit_cast(_Float16, v); }
; DI int crow(int i, int h) { return (i & 3) + 8 * (i >> 2) + 4 * h; }
; template <int K, class Epi>
; DI void gemm64_res(const bf16_t* A, int lda, const bf16_t* Wp, int NU, unsigned char* lds, const Epi& epi) {
;     ...
; #pragma unroll 1
;         for (int kk = 0; kk < KS; kk += PD) {
; #pragma unroll
;             for (int s = 0; s < PD; ++s) {
;                 const int ks = kk + s, ksr = (ks + rot) & (KS - 1);
;                 const bf16x8 a0 = *(const bf16x8*)(ab + ksr * 32), a1 = *(const bf16x8*)(ab + 32 * LD + ksr * 32);
; #pragma unroll
;                 for (int j = 0; j < NT; ++j) { acc[0][j] = MFMA32(a0, __builtin_bit_cast(bf16x8, bq[s][j]), acc[0][j]); acc[1][j] = MFMA32(a1, __builtin_bit_cast(bf16x8, bq[s][j]), acc[1][j]); }
;                 int nk = ks + PD; nk = nk < KS ? nk : KS - 1; nk = (nk + rot) & (KS - 1);
; #pragma unroll
;                 for (int j = 0; j < NT; ++j) bq[s][j] = bp[(size_t)nk * kstr + j * 64];
;             }
;         }
;     DI void operator()(int unit, const f32x16 (&acc)[MT][NT]) const {
;         const int lane = otid() & 63, r = lane & 31, h = lane >> 5;
; #pragma unroll
;         for (int mi = 0; mi < MT; ++mi)
; #pragma unroll
;             for (int nj = 0; nj < NT; ++nj)
; #pragma unroll
;                 for (int i = 0; i < 16; ++i) {
;                     bf16_t* rowp = priv + (mi * 32 + crow(i, h) + (mi == 2 ? d2 : 0)) * PRIVW; const int c = unit * UW + nj * 32 + r;
;                     float v = bf2f(rowp[gcol + c]) * acc[mi][nj][i];
;                     if (SECOND) v += bf2f(rowp[PC_M + c]);
;                     rowp[PC_M + c] = cv1(v);
;                     if (i == 15) __builtin_amdgcn_sched_barrier(0);
;                 }
;     }
	s_and_b32 s5, s3, 31
	s_lshl_b32 s5, s5, 5
	s_add_i32 s3, s3, 1
	v_add_u32_e32 v125, s5, v124
	ds_read_b128 v[148:151], v125
	ds_read_b128 v[152:155], v125 offset:33280
	s_waitcnt vmcnt(15) lgkmcnt(2)
	v_mfma_f32_32x32x16_f16 v[50:65], v[140:143], v[72:75], v[50:65]
	v_mfma_f32_32x32x16_f16 v[18:33], v[144:147], v[72:75], v[18:33]
	s_waitcnt vmcnt(14)
	v_mfma_f32_32x32x16_f16 v[34:49], v[140:143], v[76:79], v[34:49]
	v_mfma_f32_32x32x16_f16 v[2:17], v[144:147], v[76:79], v[2:17]
	s_and_b32 s5, s3, 31
	s_lshl_b32 s5, s5, 5
	s_add_i32 s3, s3, 1
	v_add_u32_e32 v125, s5, v124
	ds_read_b128 v[140:143], v125
	ds_read_b128 v[144:147], v125 offset:33280
	s_waitcnt vmcnt(13) lgkmcnt(2)
	v_mfma_f32_32x32x16_f16 v[50:65], v[148:151], v[80:83], v[50:65]
	v_mfma_f32_32x32x16_f16 v[18:33], v[152:155], v[80:83], v[18:33]
	s_waitcnt vmcnt(12)
	v_mfma_f32_32x32x16_f16 v[34:49], v[148:151], v[84:87], v[34:49]
	v_mfma_f32_32x32x16_f16 v[2:17], v[152:155], v[84:87], v[2:17]
	s_and_b32 s5, s3, 31
	s_lshl_b32 s5, s5, 5
	s_add_i32 s3, s3, 1
	v_add_u32_e32 v125, s5, v124
	ds_read_b128 v[148:151], v125
	ds_read_b128 v[152:155], v125 offset:33280
	s_waitcnt vmcnt(11) lgkmcnt(2)
	v_mfma_f32_32x32x16_f16 v[50:65], v[140:143], v[88:91], v[50:65]
	v_mfma_f32_32x32x16_f16 v[18:33], v[144:147], v[88:91], v[18:33]
	s_waitcnt vmcnt(10)
	v_mfma_f32_32x32x16_f16 v[34:49], v[140:143], v[92:95], v[34:49]
	v_mfma_f32_32x32x16_f16 v[2:17], v[144:147], v[92:95], v[2:17]
	s_and_b32 s5, s3, 31
	s_lshl_b32 s5, s5, 5
	s_add_i32 s3, s3, 1
	v_add_u32_e32 v125, s5, v124
	ds_read_b128 v[140:143], v125
	ds_read_b128 v[144:147], v125 offset:33280
	s_waitcnt vmcnt(9) lgkmcnt(2)
	v_mfma_f32_32x32x16_f16 v[50:65], v[148:151], v[96:99], v[50:65]
	v_mfma_f32_32x32x16_f16 v[18:33], v[152:155], v[96:99], v[18:33]
	s_waitcnt vmcnt(8)
	v_mfma_f32_32x32x16_f16 v[34:49], v[148:151], v[100:103], v[34:49]
	v_mfma_f32_32x32x16_f16 v[2:17], v[152:155], v[100:103], v[2:17]
	s_and_b32 s5, s3, 31
	s_lshl_b32 s5, s5, 5
	s_add_i32 s3, s3, 1
	v_add_u32_e32 v125, s5, v124
	ds_read_b128 v[148:151], v125
	ds_read_b128 v[152:155], v125 offset:33280
	s_waitcnt vmcnt(7) lgkmcnt(2)
	v_mfma_f32_32x32x16_f16 v[50:65], v[140:143], v[104:107], v[50:65]
	v_mfma_f32_32x32x16_f16 v[18:33], v[144:147], v[104:107], v[18:33]
	s_waitcnt vmcnt(6)
	v_mfma_f32_32x32x16_f16 v[34:49], v[140:143], v[108:111], v[34:49]
	v_mfma_f32_32x32x16_f16 v[2:17], v[144:147], v[108:111], v[2:17]
	s_and_b32 s5, s3, 31
	s_lshl_b32 s5, s5, 5
	s_add_i32 s3, s3, 1
	v_add_u32_e32 v125, s5, v124
	ds_read_b128 v[140:143], v125
	ds_read_b128 v[144:147], v125 offset:33280
	s_waitcnt vmcnt(5) lgkmcnt(2)
	v_mfma_f32_32x32x16_f16 v[50:65], v[148:151], v[112:115], v[50:65]
	v_mfma_f32_32x32x16_f16 v[18:33], v[152:155], v[112:115], v[18:33]
	s_waitcnt vmcnt(4)
	v_mfma_f32_32x32x16_f16 v[34:49], v[148:151], v[116:119], v[34:49]
	v_mfma_f32_32x32x16_f16 v[2:17], v[152:155], v[116:119], v[2:17]
	s_and_b32 s5, s3, 31
	s_lshl_b32 s5, s5, 5
	s_add_i32 s3, s3, 1
	v_add_u32_e32 v125, s5, v124
	ds_read_b128 v[148:151], v125
	ds_read_b128 v[152:155], v125 offset:33280
	s_waitcnt vmcnt(3) lgkmcnt(2)
	v_mfma_f32_32x32x16_f16 v[50:65], v[140:143], v[120:123], v[50:65]
	v_mfma_f32_32x32x16_f16 v[18:33], v[144:147], v[120:123], v[18:33]
	s_waitcnt vmcnt(2)
	v_mfma_f32_32x32x16_f16 v[34:49], v[140:143], v[128:131], v[34:49]
	v_mfma_f32_32x32x16_f16 v[2:17], v[144:147], v[128:131], v[2:17]
	s_waitcnt vmcnt(1) lgkmcnt(0)
	v_mfma_f32_32x32x16_f16 v[50:65], v[148:151], v[132:135], v[50:65]
	v_mfma_f32_32x32x16_f16 v[18:33], v[152:155], v[132:135], v[18:33]
	s_waitcnt vmcnt(0)
	v_mfma_f32_32x32x16_f16 v[34:49], v[148:151], v[136:139], v[34:49]
	v_mfma_f32_32x32x16_f16 v[2:17], v[152:155], v[136:139], v[2:17]
	s_nop 7
	s_nop 3
	s_waitcnt vmcnt(0)
	v_and_b32_e32 v68, 31, v176
	v_lshrrev_b32_e32 v69, 3, v176
	v_and_b32_e32 v69, 4, v69
	v_mul_u32_u24_e32 v69, 0x2c00, v69
	v_lshl_add_u32 v70, v68, 1, v69
	v_lshl_add_u32 v70, s1, 7, v70
	v_add_u32_e32 v71, 0x1400, v70
	global_load_ushort v87, v71, s[34:35] offset:-3072
	global_load_ushort v88, v71, s[34:35] offset:-3008
	v_add_u32_e32 v72, 0x4000, v70
	global_load_ushort v89, v72, s[34:35] offset:-3072
	global_load_ushort v90, v72, s[34:35] offset:-3008
	v_add_u32_e32 v73, 0x6c00, v70
	global_load_ushort v91, v73, s[34:35] offset:-3072
	global_load_ushort v92, v73, s[34:35] offset:-3008
	v_add_u32_e32 v74, 0x9800, v70
	global_load_ushort v93, v74, s[34:35] offset:-3072
	global_load_ushort v94, v74, s[34:35] offset:-3008
	v_add_u32_e32 v75, 0x17400, v70
	global_load_ushort v95, v75, s[34:35] offset:-3072
	global_load_ushort v96, v75, s[34:35] offset:-3008
	v_add_u32_e32 v76, 0x1a000, v70
	global_load_ushort v97, v76, s[34:35] offset:-3072
	global_load_ushort v98, v76, s[34:35] offset:-3008
	v_add_u32_e32 v77, 0x1cc00, v70
	global_load_ushort v99, v77, s[34:35] offset:-3072
	global_load_ushort v100, v77, s[34:35] offset:-3008
	v_add_u32_e32 v78, 0x1f800, v70
	global_load_ushort v101, v78, s[34:35] offset:-3072
	global_load_ushort v102, v78, s[34:35] offset:-3008
	v_add_u32_e32 v79, 0x2d400, v70
	global_load_ushort v103, v79, s[34:35] offset:-3072
	global_load_ushort v104, v79, s[34:35] offset:-3008
	v_add_u32_e32 v80, 0x30000, v70
	global_load_ushort v105, v80, s[34:35] offset:-3072
	global_load_ushort v106, v80, s[34:35] offset:-3008
	v_add_u32_e32 v81, 0x32c00, v70
	global_load_ushort v107, v81, s[34:35] offset:-3072
	global_load_ushort v108, v81, s[34:35] offset:-3008
	v_add_u32_e32 v82, 0x35800, v70
	global_load_ushort v109, v82, s[34:35] offset:-3072
	global_load_ushort v110, v82, s[34:35] offset:-3008
	v_add_u32_e32 v83, 0x43400, v70
	global_load_ushort v111, v83, s[34:35] offset:-3072
	global_load_ushort v112, v83, s[34:35] offset:-3008
	v_add_u32_e32 v84, 0x46000, v70
	global_load_ushort v113, v84, s[34:35] offset:-3072
	global_load_ushort v114, v84, s[34:35] offset:-3008
	v_add_u32_e32 v85, 0x48c00, v70
	global_load_ushort v116, v85, s[34:35] offset:-3072
	global_load_ushort v117, v85, s[34:35] offset:-3008
	v_add_u32_e32 v86, 0x4b800, v70
	global_load_ushort v118, v86, s[34:35] offset:-3072
	global_load_ushort v119, v86, s[34:35] offset:-3008
	s_waitcnt vmcnt(0)
; DI int otid() { int t = threadIdx.x; asm volatile("" : "+v"(t)); return t; }
; DI bf16_t cv1(float x) { return (bf16_t)(pk2(x, 0.f) & 0xffffu); }
; DI float bf2f(bf16_t v) { return (float)__builtin_bit_cast(_Float16, v); }
; DI int crow(int i, int h) { return (i & 3) + 8 * (i >> 2) + 4 * h; }
;     DI void operator()(int unit, const f32x16 (&acc)[MT][NT]) const {
;         const int lane = otid() & 63, r = lane & 31, h = lane >> 5;
; #pragma unroll
;         for (int mi = 0; mi < MT; ++mi)
; #pragma unroll
;             for (int nj = 0; nj < NT; ++nj)
; #pragma unroll
;                 for (int i = 0; i < 16; ++i) {
;                     bf16_t* rowp = priv + (mi * 32 + crow(i, h) + (mi == 2 ? d2 : 0)) * PRIVW; const int c = unit * UW + nj * 32 + r;
;                     float v = bf2f(rowp[gcol + c]) * acc[mi][nj][i];
;                     if (SECOND) v += bf2f(rowp[PC_M + c]);
;                     rowp[PC_M + c] = cv1(v);
;                     if (i == 15) __builtin_amdgcn_sched_barrier(0);
;                 }
;     }
	v_fma_mixlo_f16 v87, v50, v87, 0 op_sel_hi:[0,1,0]
	global_store_short v71, v87, s[34:35] offset:3072
	v_fma_mixlo_f16 v88, v34, v88, 0 op_sel_hi:[0,1,0]
	global_store_short v71, v88, s[34:35] offset:3136
	v_fma_mixlo_f16 v89, v51, v89, 0 op_sel_hi:[0,1,0]
	global_store_short v72, v89, s[34:35] offset:3072
	v_fma_mixlo_f16 v90, v35, v90, 0 op_sel_hi:[0,1,0]
	global_store_short v72, v90, s[34:35] offset:3136
	v_fma_mixlo_f16 v91, v52, v91, 0 op_sel_hi:[0,1,0]
	global_store_short v73, v91, s[34:35] offset:3072
	v_fma_mixlo_f16 v92, v36, v92, 0 op_sel_hi:[0,1,0]
	global_store_short v73, v92, s[34:35] offset:3136
	v_fma_mixlo_f16 v93, v53, v93, 0 op_sel_hi:[0,1,0]
	global_store_short v74, v93, s[34:35] offset:3072
	v_fma_mixlo_f16 v94, v37, v94, 0 op_sel_hi:[0,1,0]
	global_store_short v74, v94, s[34:35] offset:3136
	v_fma_mixlo_f16 v95, v54, v95, 0 op_sel_hi:[0,1,0]
	global_store_short v75, v95, s[34:35] offset:3072
	v_fma_mixlo_f16 v96, v38, v96, 0 op_sel_hi:[0,1,0]
	global_store_short v75, v96, s[34:35] offset:3136
	v_fma_mixlo_f16 v97, v55, v97, 0 op_sel_hi:[0,1,0]
	global_store_short v76, v97, s[34:35] offset:3072
	v_fma_mixlo_f16 v98, v39, v98, 0 op_sel_hi:[0,1,0]
	global_store_short v76, v98, s[34:35] offset:3136
	v_fma_mixlo_f16 v99, v56, v99, 0 op_sel_hi:[0,1,0]
	global_store_short v77, v99, s[34:35] offset:3072
	v_fma_mixlo_f16 v100, v40, v100, 0 op_sel_hi:[0,1,0]
	global_store_short v77, v100, s[34:35] offset:3136
	v_fma_mixlo_f16 v101, v57, v101, 0 op_sel_hi:[0,1,0]
	global_store_short v78, v101, s[34:35] offset:3072
	v_fma_mixlo_f16 v102, v41, v102, 0 op_sel_hi:[0,1,0]
	global_store_short v78, v102, s[34:35] offset:3136
	v_fma_mixlo_f16 v103, v58, v103, 0 op_sel_hi:[0,1,0]
	global_store_short v79, v103, s[34:35] offset:3072
	v_fma_mixlo_f16 v104, v42, v104, 0 op_sel_hi:[0,1,0]
	global_store_short v79, v104, s[34:35] offset:3136
	v_fma_mixlo_f16 v105, v59, v105, 0 op_sel_hi:[0,1,0]
	global_store_short v80, v105, s[34:35] offset:3072
	v_fma_mixlo_f16 v106, v43, v106, 0 op_sel_hi:[0,1,0]
	global_store_short v80, v106, s[34:35] offset:3136
	v_fma_mixlo_f16 v107, v60, v107, 0 op_sel_hi:[0,1,0]
	global_store_short v81, v107, s[34:35] offset:3072
	v_fma_mixlo_f16 v108, v44, v108, 0 op_sel_hi:[0,1,0]
	global_store_short v81, v108, s[34:35] offset:3136
	v_fma_mixlo_f16 v109, v61, v109, 0 op_sel_hi:[0,1,0]
	global_store_short v82, v109, s[34:35] offset:3072
	v_fma_mixlo_f16 v110, v45, v110, 0 op_sel_hi:[0,1,0]
	global_store_short v82, v110, s[34:35] offset:3136
	v_fma_mixlo_f16 v111, v62, v111, 0 op_sel_hi:[0,1,0]
	global_store_short v83, v111, s[34:35] offset:3072
	v_fma_mixlo_f16 v112, v46, v112, 0 op_sel_hi:[0,1,0]
	global_store_short v83, v112, s[34:35] offset:3136
	v_fma_mixlo_f16 v113, v63, v113, 0 op_sel_hi:[0,1,0]
	global_store_short v84, v113, s[34:35] offset:3072
	v_fma_mixlo_f16 v114, v47, v114, 0 op_sel_hi:[0,1,0]
	global_store_short v84, v114, s[34:35] offset:3136
	v_fma_mixlo_f16 v116, v64, v116, 0 op_sel_hi:[0,1,0]
	global_store_short v85, v116, s[34:35] offset:3072
	v_fma_mixlo_f16 v117, v48, v117, 0 op_sel_hi:[0,1,0]
	global_store_short v85, v117, s[34:35] offset:3136
	v_fma_mixlo_f16 v118, v65, v118, 0 op_sel_hi:[0,1,0]
	global_store_short v86, v118, s[34:35] offset:3072
	v_fma_mixlo_f16 v119, v49, v119, 0 op_sel_hi:[0,1,0]
	global_store_short v86, v119, s[34:35] offset:3136
	v_add_u32_e32 v71, 0x59400, v70
	global_load_ushort v87, v71, s[34:35] offset:-3072
	global_load_ushort v88, v71, s[34:35] offset:-3008
	v_add_u32_e32 v72, 0x5c000, v70
	global_load_ushort v89, v72, s[34:35] offset:-3072
	global_load_ushort v90, v72, s[34:35] offset:-3008
	v_add_u32_e32 v73, 0x5ec00, v70
	global_load_ushort v91, v73, s[34:35] offset:-3072
	global_load_ushort v92, v73, s[34:35] offset:-3008
	v_add_u32_e32 v74, 0x61800, v70
	global_load_ushort v93, v74, s[34:35] offset:-3072
	global_load_ushort v94, v74, s[34:35] offset:-3008
	v_add_u32_e32 v75, 0x6f400, v70
	global_load_ushort v95, v75, s[34:35] offset:-3072
	global_load_ushort v96, v75, s[34:35] offset:-3008
	v_add_u32_e32 v76, 0x72000, v70
	global_load_ushort v97, v76, s[34:35] offset:-3072
	global_load_ushort v98, v76, s[34:35] offset:-3008
	v_add_u32_e32 v77, 0x74c00, v70
	global_load_ushort v99, v77, s[34:35] offset:-3072
	global_load_ushort v100, v77, s[34:35] offset:-3008
	v_add_u32_e32 v78, 0x77800, v70
	global_load_ushort v101, v78, s[34:35] offset:-3072
	global_load_ushort v102, v78, s[34:35] offset:-3008
	v_add_u32_e32 v79, 0x85400, v70
	global_load_ushort v103, v79, s[34:35] offset:-3072
	global_load_ushort v104, v79, s[34:35] offset:-3008
	v_add_u32_e32 v80, 0x88000, v70
	global_load_ushort v105, v80, s[34:35] offset:-3072
	global_load_ushort v106, v80, s[34:35] offset:-3008
	v_add_u32_e32 v81, 0x8ac00, v70
	global_load_ushort v107, v81, s[34:35] offset:-3072
	global_load_ushort v108, v81, s[34:35] offset:-3008
	v_add_u32_e32 v82, 0x8d800, v70
	global_load_ushort v109, v82, s[34:35] offset:-3072
	global_load_ushort v110, v82, s[34:35] offset:-3008
	v_add_u32_e32 v83, 0x9b400, v70
	global_load_ushort v111, v83, s[34:35] offset:-3072
	global_load_ushort v112, v83, s[34:35] offset:-3008
	v_add_u32_e32 v84, 0x9e000, v70
	global_load_ushort v113, v84, s[34:35] offset:-3072
	global_load_ushort v114, v84, s[34:35] offset:-3008
	v_add_u32_e32 v85, 0xa0c00, v70
	global_load_ushort v116, v85, s[34:35] offset:-3072
	global_load_ushort v117, v85, s[34:35] offset:-3008
	v_add_u32_e32 v86, 0xa3800, v70
	global_load_ushort v118, v86, s[34:35] offset:-3072
	global_load_ushort v119, v86, s[34:35] offset:-3008
	s_waitcnt vmcnt(0)
; DI int otid() { int t = threadIdx.x; asm volatile("" : "+v"(t)); return t; }
; DI bf16_t cv1(float x) { return (bf16_t)(pk2(x, 0.f) & 0xffffu); }
; DI float bf2f(bf16_t v) { return (float)__builtin_bit_cast(_Float16, v); }
; DI int crow(int i, int h) { return (i & 3) + 8 * (i >> 2) + 4 * h; }
;     DI void operator()(int unit, const f32x16 (&acc)[MT][NT]) const {
;         const int lane = otid() & 63, r = lane & 31, h = lane >> 5;
; #pragma unroll
;         for (int mi = 0; mi < MT; ++mi)
; #pragma unroll
;             for (int nj = 0; nj < NT; ++nj)
; #pragma unroll
;                 for (int i = 0; i < 16; ++i) {
;                     bf16_t* rowp = priv + (mi * 32 + crow(i, h) + (mi == 2 ? d2 : 0)) * PRIVW; const int c = unit * UW + nj * 32 + r;
;                     float v = bf2f(rowp[gcol + c]) * acc[mi][nj][i];
;                     if (SECOND) v += bf2f(rowp[PC_M + c]);
;                     rowp[PC_M + c] = cv1(v);
;                     if (i == 15) __builtin_amdgcn_sched_barrier(0);
;                 }
;     }
	v_fma_mixlo_f16 v87, v18, v87, 0 op_sel_hi:[0,1,0]
	global_store_short v71, v87, s[34:35] offset:3072
	v_fma_mixlo_f16 v88, v2, v88, 0 op_sel_hi:[0,1,0]
	global_store_short v71, v88, s[34:35] offset:3136
	v_fma_mixlo_f16 v89, v19, v89, 0 op_sel_hi:[0,1,0]
	global_store_short v72, v89, s[34:35] offset:3072
	v_fma_mixlo_f16 v90, v3, v90, 0 op_sel_hi:[0,1,0]
	global_store_short v72, v90, s[34:35] offset:3136
	v_fma_mixlo_f16 v91, v20, v91, 0 op_sel_hi:[0,1,0]
	global_store_short v73, v91, s[34:35] offset:3072
	v_fma_mixlo_f16 v92, v4, v92, 0 op_sel_hi:[0,1,0]
	global_store_short v73, v92, s[34:35] offset:3136
	v_fma_mixlo_f16 v93, v21, v93, 0 op_sel_hi:[0,1,0]
	global_store_short v74, v93, s[34:35] offset:3072
	v_fma_mixlo_f16 v94, v5, v94, 0 op_sel_hi:[0,1,0]
	global_store_short v74, v94, s[34:35] offset:3136
	v_fma_mixlo_f16 v95, v22, v95, 0 op_sel_hi:[0,1,0]
	global_store_short v75, v95, s[34:35] offset:3072
	v_fma_mixlo_f16 v96, v6, v96, 0 op_sel_hi:[0,1,0]
	global_store_short v75, v96, s[34:35] offset:3136
	v_fma_mixlo_f16 v97, v23, v97, 0 op_sel_hi:[0,1,0]
	global_store_short v76, v97, s[34:35] offset:3072
	v_fma_mixlo_f16 v98, v7, v98, 0 op_sel_hi:[0,1,0]
	global_store_short v76, v98, s[34:35] offset:3136
	v_fma_mixlo_f16 v99, v24, v99, 0 op_sel_hi:[0,1,0]
	global_store_short v77, v99, s[34:35] offset:3072
	v_fma_mixlo_f16 v100, v8, v100, 0 op_sel_hi:[0,1,0]
	global_store_short v77, v100, s[34:35] offset:3136
	v_fma_mixlo_f16 v101, v25, v101, 0 op_sel_hi:[0,1,0]
	global_store_short v78, v101, s[34:35] offset:3072
	v_fma_mixlo_f16 v102, v9, v102, 0 op_sel_hi:[0,1,0]
	global_store_short v78, v102, s[34:35] offset:3136
	v_fma_mixlo_f16 v103, v26, v103, 0 op_sel_hi:[0,1,0]
	global_store_short v79, v103, s[34:35] offset:3072
	v_fma_mixlo_f16 v104, v10, v104, 0 op_sel_hi:[0,1,0]
	global_store_short v79, v104, s[34:35] offset:3136
	v_fma_mixlo_f16 v105, v27, v105, 0 op_sel_hi:[0,1,0]
	global_store_short v80, v105, s[34:35] offset:3072
	v_fma_mixlo_f16 v106, v11, v106, 0 op_sel_hi:[0,1,0]
	global_store_short v80, v106, s[34:35] offset:3136
	v_fma_mixlo_f16 v107, v28, v107, 0 op_sel_hi:[0,1,0]
	global_store_short v81, v107, s[34:35] offset:3072
	v_fma_mixlo_f16 v108, v12, v108, 0 op_sel_hi:[0,1,0]
	global_store_short v81, v108, s[34:35] offset:3136
	v_fma_mixlo_f16 v109, v29, v109, 0 op_sel_hi:[0,1,0]
	global_store_short v82, v109, s[34:35] offset:3072
	v_fma_mixlo_f16 v110, v13, v110, 0 op_sel_hi:[0,1,0]
	global_store_short v82, v110, s[34:35] offset:3136
	v_fma_mixlo_f16 v111, v30, v111, 0 op_sel_hi:[0,1,0]
	global_store_short v83, v111, s[34:35] offset:3072
	v_fma_mixlo_f16 v112, v14, v112, 0 op_sel_hi:[0,1,0]
	global_store_short v83, v112, s[34:35] offset:3136
	v_fma_mixlo_f16 v113, v31, v113, 0 op_sel_hi:[0,1,0]
	global_store_short v84, v113, s[34:35] offset:3072
	v_fma_mixlo_f16 v114, v15, v114, 0 op_sel_hi:[0,1,0]
	global_store_short v84, v114, s[34:35] offset:3136
	v_fma_mixlo_f16 v116, v32, v116, 0 op_sel_hi:[0,1,0]
	global_store_short v85, v116, s[34:35] offset:3072
	v_fma_mixlo_f16 v117, v16, v117, 0 op_sel_hi:[0,1,0]
	global_store_short v85, v117, s[34:35] offset:3136
	v_fma_mixlo_f16 v118, v33, v118, 0 op_sel_hi:[0,1,0]
	global_store_short v86, v118, s[34:35] offset:3072
	v_fma_mixlo_f16 v119, v17, v119, 0 op_sel_hi:[0,1,0]
	global_store_short v86, v119, s[34:35] offset:3136
	s_add_i32 s2, s1, 8
	s_cmp_lt_i32 s1, 8
	s_mov_b32 s1, s2
	s_cbranch_scc1 .LBB0_505
	s_movk_i32 s17, 0x810
	s_movk_i32 s64, 0x3fff

; #define MFMA32(a, b, c) __builtin_amdgcn_mfma_f32_32x32x16_f16((a), (b), (c), 0, 0, 0)
; template <int K, class Epi>
; DI void gemm64_res(const bf16_t* A, int lda, const bf16_t* Wp, int NU, unsigned char* lds, const Epi& epi) {
;     ...
; #pragma unroll 1
;         for (int kk = 0; kk < KS; kk += PD) {
; #pragma unroll
;             for (int s = 0; s < PD; ++s) {
;                 const int ks = kk + s, ksr = (ks + rot) & (KS - 1);
;                 const bf16x8 a0 = *(const bf16x8*)(ab + ksr * 32), a1 = *(const bf16x8*)(ab + 32 * LD + ksr * 32);
; #pragma unroll
;                 for (int j = 0; j < NT; ++j) { acc[0][j] = MFMA32(a0, __builtin_bit_cast(bf16x8, bq[s][j]), acc[0][j]); acc[1][j] = MFMA32(a1, __builtin_bit_cast(bf16x8, bq[s][j]), acc[1][j]); }
;                 int nk = ks + PD; nk = nk < KS ? nk : KS - 1; nk = (nk + rot) & (KS - 1);
; #pragma unroll
;                 for (int j = 0; j < NT; ++j) bq[s][j] = bp[(size_t)nk * kstr + j * 64];
;             }
;         }
.Lkob2_loop:
	s_and_b32 s5, s3, 31
	s_lshl_b32 s5, s5, 5
	s_add_i32 s3, s3, 1
	v_add_u32_e32 v129, s5, v128
	ds_read_b128 v[148:151], v129
	ds_read_b128 v[152:155], v129 offset:33280
	s_waitcnt vmcnt(15) lgkmcnt(2)
	v_mfma_f32_32x32x16_f16 v[50:65], v[140:143], v[72:75], v[50:65]
	v_mfma_f32_32x32x16_f16 v[18:33], v[144:147], v[72:75], v[18:33]
	s_waitcnt vmcnt(14)
	v_mfma_f32_32x32x16_f16 v[34:49], v[140:143], v[76:79], v[34:49]
	v_mfma_f32_32x32x16_f16 v[2:17], v[144:147], v[76:79], v[2:17]
	s_and_b32 s5, s4, 31
	s_add_i32 s4, s4, 1
	s_mul_i32 s100, s5, 0x8000
	v_lshl_add_u64 v[70:71], v[68:69], 0, s[100:101]
	global_load_dwordx4 v[72:75], v[70:71], off
	global_load_dwordx4 v[76:79], v[70:71], off offset:1024
	s_and_b32 s5, s3, 31
	s_lshl_b32 s5, s5, 5
	s_add_i32 s3, s3, 1
	v_add_u32_e32 v129, s5, v128
	ds_read_b128 v[140:143], v129
	ds_read_b128 v[144:147], v129 offset:33280
	s_waitcnt vmcnt(15) lgkmcnt(2)
	v_mfma_f32_32x32x16_f16 v[50:65], v[148:151], v[80:83], v[50:65]
	v_mfma_f32_32x32x16_f16 v[18:33], v[152:155], v[80:83], v[18:33]
	s_waitcnt vmcnt(14)
	v_mfma_f32_32x32x16_f16 v[34:49], v[148:151], v[84:87], v[34:49]
	v_mfma_f32_32x32x16_f16 v[2:17], v[152:155], v[84:87], v[2:17]
	s_and_b32 s5, s4, 31
	s_add_i32 s4, s4, 1
	s_mul_i32 s100, s5, 0x8000
	v_lshl_add_u64 v[70:71], v[68:69], 0, s[100:101]
	global_load_dwordx4 v[80:83], v[70:71], off
	global_load_dwordx4 v[84:87], v[70:71], off offset:1024
	s_and_b32 s5, s3, 31
	s_lshl_b32 s5, s5, 5
	s_add_i32 s3, s3, 1
	v_add_u32_e32 v129, s5, v128
	ds_read_b128 v[148:151], v129
	ds_read_b128 v[152:155], v129 offset:33280
	s_waitcnt vmcnt(15) lgkmcnt(2)
	v_mfma_f32_32x32x16_f16 v[50:65], v[140:143], v[88:91], v[50:65]
	v_mfma_f32_32x32x16_f16 v[18:33], v[144:147], v[88:91], v[18:33]
	s_waitcnt vmcnt(14)
	v_mfma_f32_32x32x16_f16 v[34:49], v[140:143], v[92:95], v[34:49]
	v_mfma_f32_32x32x16_f16 v[2:17], v[144:147], v[92:95], v[2:17]
	s_and_b32 s5, s4, 31
	s_add_i32 s4, s4, 1
	s_mul_i32 s100, s5, 0x8000
	v_lshl_add_u64 v[70:71], v[68:69], 0, s[100:101]
	global_load_dwordx4 v[88:91], v[70:71], off
	global_load_dwordx4 v[92:95], v[70:71], off offset:1024
	s_and_b32 s5, s3, 31
	s_lshl_b32 s5, s5, 5
	s_add_i32 s3, s3, 1
	v_add_u32_e32 v129, s5, v128
	ds_read_b128 v[140:143], v129
	ds_read_b128 v[144:147], v129 offset:33280
	s_waitcnt vmcnt(15) lgkmcnt(2)
	v_mfma_f32_32x32x16_f16 v[50:65], v[148:151], v[96:99], v[50:65]
	v_mfma_f32_32x32x16_f16 v[18:33], v[152:155], v[96:99], v[18:33]
	s_waitcnt vmcnt(14)
	v_mfma_f32_32x32x16_f16 v[34:49], v[148:151], v[100:103], v[34:49]
	v_mfma_f32_32x32x16_f16 v[2:17], v[152:155], v[100:103], v[2:17]
	s_and_b32 s5, s4, 31
	s_add_i32 s4, s4, 1
	s_mul_i32 s100, s5, 0x8000
	v_lshl_add_u64 v[70:71], v[68:69], 0, s[100:101]
	global_load_dwordx4 v[96:99], v[70:71], off
	global_load_dwordx4 v[100:103], v[70:71], off offset:1024
	s_and_b32 s5, s3, 31
	s_lshl_b32 s5, s5, 5
	s_add_i32 s3, s3, 1
	v_add_u32_e32 v129, s5, v128
	ds_read_b128 v[148:151], v129
	ds_read_b128 v[152:155], v129 offset:33280
	s_waitcnt vmcnt(15) lgkmcnt(2)
	v_mfma_f32_32x32x16_f16 v[50:65], v[140:143], v[104:107], v[50:65]
	v_mfma_f32_32x32x16_f16 v[18:33], v[144:147], v[104:107], v[18:33]
	s_waitcnt vmcnt(14)
	v_mfma_f32_32x32x16_f16 v[34:49], v[140:143], v[108:111], v[34:49]
	v_mfma_f32_32x32x16_f16 v[2:17], v[144:147], v[108:111], v[2:17]
	s_and_b32 s5, s4, 31
	s_add_i32 s4, s4, 1
	s_mul_i32 s100, s5, 0x8000
	v_lshl_add_u64 v[70:71], v[68:69], 0, s[100:101]
	global_load_dwordx4 v[104:107], v[70:71], off
	global_load_dwordx4 v[108:111], v[70:71], off offset:1024
	s_and_b32 s5, s3, 31
	s_lshl_b32 s5, s5, 5
	s_add_i32 s3, s3, 1
	v_add_u32_e32 v129, s5, v128
	ds_read_b128 v[140:143], v129
	ds_read_b128 v[144:147], v129 offset:33280
	s_waitcnt vmcnt(15) lgkmcnt(2)
	v_mfma_f32_32x32x16_f16 v[50:65], v[148:151], v[112:115], v[50:65]
	v_mfma_f32_32x32x16_f16 v[18:33], v[152:155], v[112:115], v[18:33]
	s_waitcnt vmcnt(14)
	v_mfma_f32_32x32x16_f16 v[34:49], v[148:151], v[116:119], v[34:49]
	v_mfma_f32_32x32x16_f16 v[2:17], v[152:155], v[116:119], v[2:17]
	s_and_b32 s5, s4, 31
	s_add_i32 s4, s4, 1
	s_mul_i32 s100, s5, 0x8000
	v_lshl_add_u64 v[70:71], v[68:69], 0, s[100:101]
	global_load_dwordx4 v[112:115], v[70:71], off
	global_load_dwordx4 v[116:119], v[70:71], off offset:1024
	s_and_b32 s5, s3, 31
	s_lshl_b32 s5, s5, 5
	s_add_i32 s3, s3, 1
	v_add_u32_e32 v129, s5, v128
	ds_read_b128 v[148:151], v129
	ds_read_b128 v[152:155], v129 offset:33280
	s_waitcnt vmcnt(15) lgkmcnt(2)
	v_mfma_f32_32x32x16_f16 v[50:65], v[140:143], v[120:123], v[50:65]
	v_mfma_f32_32x32x16_f16 v[18:33], v[144:147], v[120:123], v[18:33]
	s_waitcnt vmcnt(14)
	v_mfma_f32_32x32x16_f16 v[34:49], v[140:143], v[124:127], v[34:49]
	v_mfma_f32_32x32x16_f16 v[2:17], v[144:147], v[124:127], v[2:17]
	s_and_b32 s5, s4, 31
	s_add_i32 s4, s4, 1
	s_mul_i32 s100, s5, 0x8000
	v_lshl_add_u64 v[70:71], v[68:69], 0, s[100:101]
	global_load_dwordx4 v[120:123], v[70:71], off
	global_load_dwordx4 v[124:127], v[70:71], off offset:1024
	s_and_b32 s5, s3, 31
	s_lshl_b32 s5, s5, 5
	s_add_i32 s3, s3, 1
	v_add_u32_e32 v129, s5, v128
	ds_read_b128 v[140:143], v129
	ds_read_b128 v[144:147], v129 offset:33280
	s_waitcnt vmcnt(15) lgkmcnt(2)
	v_mfma_f32_32x32x16_f16 v[50:65], v[148:151], v[132:135], v[50:65]
	v_mfma_f32_32x32x16_f16 v[18:33], v[152:155], v[132:135], v[18:33]
	s_waitcnt vmcnt(14)
	v_mfma_f32_32x32x16_f16 v[34:49], v[148:151], v[136:139], v[34:49]
	v_mfma_f32_32x32x16_f16 v[2:17], v[152:155], v[136:139], v[2:17]
	s_and_b32 s5, s4, 31
	s_add_i32 s4, s4, 1
	s_mul_i32 s100, s5, 0x8000
	v_lshl_add_u64 v[70:71], v[68:69], 0, s[100:101]
	global_load_dwordx4 v[132:135], v[70:71], off
	global_load_dwordx4 v[136:139], v[70:71], off offset:1024
	s_add_i32 s6, s6, -1
	s_cmp_lg_u32 s6, 0
	s_cbranch_scc1 .Lkob2_loop
; #define MFMA32(a, b, c) __builtin_amdgcn_mfma_f32_32x32x16_f16((a), (b), (c), 0, 0, 0)
; DI int otid() { int t = threadIdx.x; asm volatile("" : "+v"(t)); return t; }
; DI bf16_t cv1(float x) { return (bf16_t)(pk2(x, 0.f) & 0xffffu); }
; DI float bf2f(bf16_t v) { return (float)__builtin_bit_cast(_Float16, v); }
; DI int crow(int i, int h) { return (i & 3) + 8 * (i >> 2) + 4 * h; }
; template <int K, class Epi>
; DI void gemm64_res(const bf16_t* A, int lda, const bf16_t* Wp, int NU, unsigned char* lds, const Epi& epi) {
;     ...
; #pragma unroll 1
;         for (int kk = 0; kk < KS; kk += PD) {
; #pragma unroll
;             for (int s = 0; s < PD; ++s) {
;                 const int ks = kk + s, ksr = (ks + rot) & (KS - 1);
;                 const bf16x8 a0 = *(const bf16x8*)(ab + ksr * 32), a1 = *(const bf16x8*)(ab + 32 * LD + ksr * 32);
; #pragma unroll
;                 for (int j = 0; j < NT; ++j) { acc[0][j] = MFMA32(a0, __builtin_bit_cast(bf16x8, bq[s][j]), acc[0][j]); acc[1][j] = MFMA32(a1, __builtin_bit_cast(bf16x8, bq[s][j]), acc[1][j]); }
;                 int nk = ks + PD; nk = nk < KS ? nk : KS - 1; nk = (nk + rot) & (KS - 1);
; #pragma unroll
;                 for (int j = 0; j < NT; ++j) bq[s][j] = bp[(size_t)nk * kstr + j * 64];
;             }
;         }
;     DI void operator()(int unit, const f32x16 (&acc)[MT][NT]) const {
;         const int lane = otid() & 63, r = lane & 31, h = lane >> 5;
; #pragma unroll
;         for (int mi = 0; mi < MT; ++mi)
; #pragma unroll
;             for (int nj = 0; nj < NT; ++nj)
; #pragma unroll
;                 for (int i = 0; i < 16; ++i) {
;                     bf16_t* rowp = priv + (mi * 32 + crow(i, h) + (mi == 2 ? d2 : 0)) * PRIVW; const int c = unit * UW + nj * 32 + r;
;                     float v = bf2f(rowp[gcol + c]) * acc[mi][nj][i];
;                     if (SECOND) v += bf2f(rowp[PC_M + c]);
;                     rowp[PC_M + c] = cv1(v);
;                     if (i == 15) __builtin_amdgcn_sched_barrier(0);
;                 }
;     }
	s_and_b32 s5, s3, 31
	s_lshl_b32 s5, s5, 5
	s_add_i32 s3, s3, 1
	v_add_u32_e32 v129, s5, v128
	ds_read_b128 v[148:151], v129
	ds_read_b128 v[152:155], v129 offset:33280
	s_waitcnt vmcnt(15) lgkmcnt(2)
	v_mfma_f32_32x32x16_f16 v[50:65], v[140:143], v[72:75], v[50:65]
	v_mfma_f32_32x32x16_f16 v[18:33], v[144:147], v[72:75], v[18:33]
	s_waitcnt vmcnt(14)
	v_mfma_f32_32x32x16_f16 v[34:49], v[140:143], v[76:79], v[34:49]
	v_mfma_f32_32x32x16_f16 v[2:17], v[144:147], v[76:79], v[2:17]
	s_and_b32 s5, s3, 31
	s_lshl_b32 s5, s5, 5
	s_add_i32 s3, s3, 1
	v_add_u32_e32 v129, s5, v128
	ds_read_b128 v[140:143], v129
	ds_read_b128 v[144:147], v129 offset:33280
	s_waitcnt vmcnt(13) lgkmcnt(2)
	v_mfma_f32_32x32x16_f16 v[50:65], v[148:151], v[80:83], v[50:65]
	v_mfma_f32_32x32x16_f16 v[18:33], v[152:155], v[80:83], v[18:33]
	s_waitcnt vmcnt(12)
	v_mfma_f32_32x32x16_f16 v[34:49], v[148:151], v[84:87], v[34:49]
	v_mfma_f32_32x32x16_f16 v[2:17], v[152:155], v[84:87], v[2:17]
	s_and_b32 s5, s3, 31
	s_lshl_b32 s5, s5, 5
	s_add_i32 s3, s3, 1
	v_add_u32_e32 v129, s5, v128
	ds_read_b128 v[148:151], v129
	ds_read_b128 v[152:155], v129 offset:33280
	s_waitcnt vmcnt(11) lgkmcnt(2)
	v_mfma_f32_32x32x16_f16 v[50:65], v[140:143], v[88:91], v[50:65]
	v_mfma_f32_32x32x16_f16 v[18:33], v[144:147], v[88:91], v[18:33]
	s_waitcnt vmcnt(10)
	v_mfma_f32_32x32x16_f16 v[34:49], v[140:143], v[92:95], v[34:49]
	v_mfma_f32_32x32x16_f16 v[2:17], v[144:147], v[92:95], v[2:17]
	s_and_b32 s5, s3, 31
	s_lshl_b32 s5, s5, 5
	s_add_i32 s3, s3, 1
	v_add_u32_e32 v129, s5, v128
	ds_read_b128 v[140:143], v129
	ds_read_b128 v[144:147], v129 offset:33280
	s_waitcnt vmcnt(9) lgkmcnt(2)
	v_mfma_f32_32x32x16_f16 v[50:65], v[148:151], v[96:99], v[50:65]
	v_mfma_f32_32x32x16_f16 v[18:33], v[152:155], v[96:99], v[18:33]
	s_waitcnt vmcnt(8)
	v_mfma_f32_32x32x16_f16 v[34:49], v[148:151], v[100:103], v[34:49]
	v_mfma_f32_32x32x16_f16 v[2:17], v[152:155], v[100:103], v[2:17]
	s_and_b32 s5, s3, 31
	s_lshl_b32 s5, s5, 5
	s_add_i32 s3, s3, 1
	v_add_u32_e32 v129, s5, v128
	ds_read_b128 v[148:151], v129
	ds_read_b128 v[152:155], v129 offset:33280
	s_waitcnt vmcnt(7) lgkmcnt(2)
	v_mfma_f32_32x32x16_f16 v[50:65], v[140:143], v[104:107], v[50:65]
	v_mfma_f32_32x32x16_f16 v[18:33], v[144:147], v[104:107], v[18:33]
	s_waitcnt vmcnt(6)
	v_mfma_f32_32x32x16_f16 v[34:49], v[140:143], v[108:111], v[34:49]
	v_mfma_f32_32x32x16_f16 v[2:17], v[144:147], v[108:111], v[2:17]
	s_and_b32 s5, s3, 31
	s_lshl_b32 s5, s5, 5
	s_add_i32 s3, s3, 1
	v_add_u32_e32 v129, s5, v128
	ds_read_b128 v[140:143], v129
	ds_read_b128 v[144:147], v129 offset:33280
	s_waitcnt vmcnt(5) lgkmcnt(2)
	v_mfma_f32_32x32x16_f16 v[50:65], v[148:151], v[112:115], v[50:65]
	v_mfma_f32_32x32x16_f16 v[18:33], v[152:155], v[112:115], v[18:33]
	s_waitcnt vmcnt(4)
	v_mfma_f32_32x32x16_f16 v[34:49], v[148:151], v[116:119], v[34:49]
	v_mfma_f32_32x32x16_f16 v[2:17], v[152:155], v[116:119], v[2:17]
	s_and_b32 s5, s3, 31
	s_lshl_b32 s5, s5, 5
	s_add_i32 s3, s3, 1
	v_add_u32_e32 v129, s5, v128
	ds_read_b128 v[148:151], v129
	ds_read_b128 v[152:155], v129 offset:33280
	s_waitcnt vmcnt(3) lgkmcnt(2)
	v_mfma_f32_32x32x16_f16 v[50:65], v[140:143], v[120:123], v[50:65]
	v_mfma_f32_32x32x16_f16 v[18:33], v[144:147], v[120:123], v[18:33]
	s_waitcnt vmcnt(2)
	v_mfma_f32_32x32x16_f16 v[34:49], v[140:143], v[124:127], v[34:49]
	v_mfma_f32_32x32x16_f16 v[2:17], v[144:147], v[124:127], v[2:17]
	s_waitcnt vmcnt(1) lgkmcnt(0)
	v_mfma_f32_32x32x16_f16 v[50:65], v[148:151], v[132:135], v[50:65]
	v_mfma_f32_32x32x16_f16 v[18:33], v[152:155], v[132:135], v[18:33]
	s_waitcnt vmcnt(0)
	v_mfma_f32_32x32x16_f16 v[34:49], v[148:151], v[136:139], v[34:49]
	v_mfma_f32_32x32x16_f16 v[2:17], v[152:155], v[136:139], v[2:17]
	s_nop 7
	s_nop 3
	s_waitcnt vmcnt(0)
	v_and_b32_e32 v68, 31, v176
	v_lshrrev_b32_e32 v69, 3, v176
	v_and_b32_e32 v69, 4, v69
	v_mul_u32_u24_e32 v69, 0x2c00, v69
	v_lshl_add_u32 v70, v68, 1, v69
	v_lshl_add_u32 v70, s1, 7, v70
	v_add_u32_e32 v71, 0x1800, v70
	global_load_ushort v87, v71, s[34:35] offset:-2048
	global_load_ushort v120, v71, s[34:35] offset:2048
	global_load_ushort v88, v71, s[34:35] offset:-1984
	global_load_ushort v121, v71, s[34:35] offset:2112
	v_add_u32_e32 v72, 0x4400, v70
	global_load_ushort v89, v72, s[34:35] offset:-2048
	global_load_ushort v122, v72, s[34:35] offset:2048
	global_load_ushort v90, v72, s[34:35] offset:-1984
	global_load_ushort v123, v72, s[34:35] offset:2112
	v_add_u32_e32 v73, 0x7000, v70
	global_load_ushort v91, v73, s[34:35] offset:-2048
	global_load_ushort v124, v73, s[34:35] offset:2048
	global_load_ushort v92, v73, s[34:35] offset:-1984
	global_load_ushort v125, v73, s[34:35] offset:2112
	v_add_u32_e32 v74, 0x9c00, v70
	global_load_ushort v93, v74, s[34:35] offset:-2048
	global_load_ushort v126, v74, s[34:35] offset:2048
	global_load_ushort v94, v74, s[34:35] offset:-1984
	global_load_ushort v127, v74, s[34:35] offset:2112
	v_add_u32_e32 v75, 0x17800, v70
	global_load_ushort v95, v75, s[34:35] offset:-2048
	global_load_ushort v129, v75, s[34:35] offset:2048
	global_load_ushort v96, v75, s[34:35] offset:-1984
	global_load_ushort v130, v75, s[34:35] offset:2112
	v_add_u32_e32 v76, 0x1a400, v70
	global_load_ushort v97, v76, s[34:35] offset:-2048
	global_load_ushort v131, v76, s[34:35] offset:2048
	global_load_ushort v98, v76, s[34:35] offset:-1984
	global_load_ushort v132, v76, s[34:35] offset:2112
	v_add_u32_e32 v77, 0x1d000, v70
	global_load_ushort v99, v77, s[34:35] offset:-2048
	global_load_ushort v133, v77, s[34:35] offset:2048
	global_load_ushort v100, v77, s[34:35] offset:-1984
	global_load_ushort v134, v77, s[34:35] offset:2112
; DI bf16_t cv1(float x) { return (bf16_t)(pk2(x, 0.f) & 0xffffu); }
; DI float bf2f(bf16_t v) { return (float)__builtin_bit_cast(_Float16, v); }
; DI int crow(int i, int h) { return (i & 3) + 8 * (i >> 2) + 4 * h; }
;     DI void operator()(int unit, const f32x16 (&acc)[MT][NT]) const {
;     ...
; #pragma unroll
;         for (int mi = 0; mi < MT; ++mi)
; #pragma unroll
;             for (int nj = 0; nj < NT; ++nj)
; #pragma unroll
;                 for (int i = 0; i < 16; ++i) {
;                     bf16_t* rowp = priv + (mi * 32 + crow(i, h) + (mi == 2 ? d2 : 0)) * PRIVW; const int c = unit * UW + nj * 32 + r;
;                     float v = bf2f(rowp[gcol + c]) * acc[mi][nj][i];
;                     if (SECOND) v += bf2f(rowp[PC_M + c]);
;                     rowp[PC_M + c] = cv1(v);
;                     if (i == 15) __builtin_amdgcn_sched_barrier(0);
;                 }
	v_add_u32_e32 v78, 0x1fc00, v70
	global_load_ushort v101, v78, s[34:35] offset:-2048
	global_load_ushort v135, v78, s[34:35] offset:2048
	global_load_ushort v102, v78, s[34:35] offset:-1984
	global_load_ushort v136, v78, s[34:35] offset:2112
	v_add_u32_e32 v79, 0x2d800, v70
	global_load_ushort v103, v79, s[34:35] offset:-2048
	global_load_ushort v137, v79, s[34:35] offset:2048
	global_load_ushort v104, v79, s[34:35] offset:-1984
	global_load_ushort v138, v79, s[34:35] offset:2112
	v_add_u32_e32 v80, 0x30400, v70
	global_load_ushort v105, v80, s[34:35] offset:-2048
	global_load_ushort v139, v80, s[34:35] offset:2048
	global_load_ushort v106, v80, s[34:35] offset:-1984
	global_load_ushort v140, v80, s[34:35] offset:2112
	v_add_u32_e32 v81, 0x33000, v70
	global_load_ushort v107, v81, s[34:35] offset:-2048
	global_load_ushort v141, v81, s[34:35] offset:2048
	global_load_ushort v108, v81, s[34:35] offset:-1984
	global_load_ushort v142, v81, s[34:35] offset:2112
	v_add_u32_e32 v82, 0x35c00, v70
	global_load_ushort v109, v82, s[34:35] offset:-2048
	global_load_ushort v143, v82, s[34:35] offset:2048
	global_load_ushort v110, v82, s[34:35] offset:-1984
	global_load_ushort v144, v82, s[34:35] offset:2112
	v_add_u32_e32 v83, 0x43800, v70
	global_load_ushort v111, v83, s[34:35] offset:-2048
	global_load_ushort v145, v83, s[34:35] offset:2048
	global_load_ushort v112, v83, s[34:35] offset:-1984
	global_load_ushort v146, v83, s[34:35] offset:2112
	v_add_u32_e32 v84, 0x46400, v70
	global_load_ushort v113, v84, s[34:35] offset:-2048
	global_load_ushort v147, v84, s[34:35] offset:2048
	global_load_ushort v114, v84, s[34:35] offset:-1984
	global_load_ushort v148, v84, s[34:35] offset:2112
	v_add_u32_e32 v85, 0x49000, v70
	global_load_ushort v116, v85, s[34:35] offset:-2048
	global_load_ushort v149, v85, s[34:35] offset:2048
	global_load_ushort v117, v85, s[34:35] offset:-1984
	global_load_ushort v150, v85, s[34:35] offset:2112
	v_add_u32_e32 v86, 0x4bc00, v70
	global_load_ushort v118, v86, s[34:35] offset:-2048
	global_load_ushort v151, v86, s[34:35] offset:2048
	global_load_ushort v119, v86, s[34:35] offset:-1984
	global_load_ushort v152, v86, s[34:35] offset:2112
	s_waitcnt vmcnt(0)
	v_fma_mixlo_f16 v87, v50, v87, v120 op_sel_hi:[0,1,1]
	global_store_short v71, v87, s[34:35] offset:2048
	v_fma_mixlo_f16 v88, v34, v88, v121 op_sel_hi:[0,1,1]
	global_store_short v71, v88, s[34:35] offset:2112
	v_fma_mixlo_f16 v89, v51, v89, v122 op_sel_hi:[0,1,1]
	global_store_short v72, v89, s[34:35] offset:2048
	v_fma_mixlo_f16 v90, v35, v90, v123 op_sel_hi:[0,1,1]
	global_store_short v72, v90, s[34:35] offset:2112
	v_fma_mixlo_f16 v91, v52, v91, v124 op_sel_hi:[0,1,1]
	global_store_short v73, v91, s[34:35] offset:2048
	v_fma_mixlo_f16 v92, v36, v92, v125 op_sel_hi:[0,1,1]
	global_store_short v73, v92, s[34:35] offset:2112
	v_fma_mixlo_f16 v93, v53, v93, v126 op_sel_hi:[0,1,1]
	global_store_short v74, v93, s[34:35] offset:2048
	v_fma_mixlo_f16 v94, v37, v94, v127 op_sel_hi:[0,1,1]
	global_store_short v74, v94, s[34:35] offset:2112
	v_fma_mixlo_f16 v95, v54, v95, v129 op_sel_hi:[0,1,1]
	global_store_short v75, v95, s[34:35] offset:2048
	v_fma_mixlo_f16 v96, v38, v96, v130 op_sel_hi:[0,1,1]
	global_store_short v75, v96, s[34:35] offset:2112
	v_fma_mixlo_f16 v97, v55, v97, v131 op_sel_hi:[0,1,1]
	global_store_short v76, v97, s[34:35] offset:2048
	v_fma_mixlo_f16 v98, v39, v98, v132 op_sel_hi:[0,1,1]
	global_store_short v76, v98, s[34:35] offset:2112
	v_fma_mixlo_f16 v99, v56, v99, v133 op_sel_hi:[0,1,1]
	global_store_short v77, v99, s[34:35] offset:2048
	v_fma_mixlo_f16 v100, v40, v100, v134 op_sel_hi:[0,1,1]
	global_store_short v77, v100, s[34:35] offset:2112
	v_fma_mixlo_f16 v101, v57, v101, v135 op_sel_hi:[0,1,1]
	global_store_short v78, v101, s[34:35] offset:2048
	v_fma_mixlo_f16 v102, v41, v102, v136 op_sel_hi:[0,1,1]
	global_store_short v78, v102, s[34:35] offset:2112
	v_fma_mixlo_f16 v103, v58, v103, v137 op_sel_hi:[0,1,1]
	global_store_short v79, v103, s[34:35] offset:2048
	v_fma_mixlo_f16 v104, v42, v104, v138 op_sel_hi:[0,1,1]
	global_store_short v79, v104, s[34:35] offset:2112
	v_fma_mixlo_f16 v105, v59, v105, v139 op_sel_hi:[0,1,1]
	global_store_short v80, v105, s[34:35] offset:2048
	v_fma_mixlo_f16 v106, v43, v106, v140 op_sel_hi:[0,1,1]
	global_store_short v80, v106, s[34:35] offset:2112
	v_fma_mixlo_f16 v107, v60, v107, v141 op_sel_hi:[0,1,1]
	global_store_short v81, v107, s[34:35] offset:2048
	v_fma_mixlo_f16 v108, v44, v108, v142 op_sel_hi:[0,1,1]
	global_store_short v81, v108, s[34:35] offset:2112
	v_fma_mixlo_f16 v109, v61, v109, v143 op_sel_hi:[0,1,1]
	global_store_short v82, v109, s[34:35] offset:2048
	v_fma_mixlo_f16 v110, v45, v110, v144 op_sel_hi:[0,1,1]
	global_store_short v82, v110, s[34:35] offset:2112
	v_fma_mixlo_f16 v111, v62, v111, v145 op_sel_hi:[0,1,1]
	global_store_short v83, v111, s[34:35] offset:2048
	v_fma_mixlo_f16 v112, v46, v112, v146 op_sel_hi:[0,1,1]
	global_store_short v83, v112, s[34:35] offset:2112
	v_fma_mixlo_f16 v113, v63, v113, v147 op_sel_hi:[0,1,1]
	global_store_short v84, v113, s[34:35] offset:2048
	v_fma_mixlo_f16 v114, v47, v114, v148 op_sel_hi:[0,1,1]
	global_store_short v84, v114, s[34:35] offset:2112
	v_fma_mixlo_f16 v116, v64, v116, v149 op_sel_hi:[0,1,1]
	global_store_short v85, v116, s[34:35] offset:2048
	v_fma_mixlo_f16 v117, v48, v117, v150 op_sel_hi:[0,1,1]
	global_store_short v85, v117, s[34:35] offset:2112
	v_fma_mixlo_f16 v118, v65, v118, v151 op_sel_hi:[0,1,1]
	global_store_short v86, v118, s[34:35] offset:2048
	v_fma_mixlo_f16 v119, v49, v119, v152 op_sel_hi:[0,1,1]
	global_store_short v86, v119, s[34:35] offset:2112
; DI bf16_t cv1(float x) { return (bf16_t)(pk2(x, 0.f) & 0xffffu); }
; DI float bf2f(bf16_t v) { return (float)__builtin_bit_cast(_Float16, v); }
; DI int crow(int i, int h) { return (i & 3) + 8 * (i >> 2) + 4 * h; }
;     DI void operator()(int unit, const f32x16 (&acc)[MT][NT]) const {
;     ...
; #pragma unroll
;         for (int mi = 0; mi < MT; ++mi)
; #pragma unroll
;             for (int nj = 0; nj < NT; ++nj)
; #pragma unroll
;                 for (int i = 0; i < 16; ++i) {
;                     bf16_t* rowp = priv + (mi * 32 + crow(i, h) + (mi == 2 ? d2 : 0)) * PRIVW; const int c = unit * UW + nj * 32 + r;
;                     float v = bf2f(rowp[gcol + c]) * acc[mi][nj][i];
;                     if (SECOND) v += bf2f(rowp[PC_M + c]);
;                     rowp[PC_M + c] = cv1(v);
;                     if (i == 15) __builtin_amdgcn_sched_barrier(0);
;                 }
	v_add_u32_e32 v71, 0x59800, v70
	global_load_ushort v87, v71, s[34:35] offset:-2048
	global_load_ushort v120, v71, s[34:35] offset:2048
	global_load_ushort v88, v71, s[34:35] offset:-1984
	global_load_ushort v121, v71, s[34:35] offset:2112
	v_add_u32_e32 v72, 0x5c400, v70
	global_load_ushort v89, v72, s[34:35] offset:-2048
	global_load_ushort v122, v72, s[34:35] offset:2048
	global_load_ushort v90, v72, s[34:35] offset:-1984
	global_load_ushort v123, v72, s[34:35] offset:2112
	v_add_u32_e32 v73, 0x5f000, v70
	global_load_ushort v91, v73, s[34:35] offset:-2048
	global_load_ushort v124, v73, s[34:35] offset:2048
	global_load_ushort v92, v73, s[34:35] offset:-1984
	global_load_ushort v125, v73, s[34:35] offset:2112
	v_add_u32_e32 v74, 0x61c00, v70
	global_load_ushort v93, v74, s[34:35] offset:-2048
	global_load_ushort v126, v74, s[34:35] offset:2048
	global_load_ushort v94, v74, s[34:35] offset:-1984
	global_load_ushort v127, v74, s[34:35] offset:2112
	v_add_u32_e32 v75, 0x6f800, v70
	global_load_ushort v95, v75, s[34:35] offset:-2048
	global_load_ushort v129, v75, s[34:35] offset:2048
	global_load_ushort v96, v75, s[34:35] offset:-1984
	global_load_ushort v130, v75, s[34:35] offset:2112
	v_add_u32_e32 v76, 0x72400, v70
	global_load_ushort v97, v76, s[34:35] offset:-2048
	global_load_ushort v131, v76, s[34:35] offset:2048
	global_load_ushort v98, v76, s[34:35] offset:-1984
	global_load_ushort v132, v76, s[34:35] offset:2112
	v_add_u32_e32 v77, 0x75000, v70
	global_load_ushort v99, v77, s[34:35] offset:-2048
	global_load_ushort v133, v77, s[34:35] offset:2048
	global_load_ushort v100, v77, s[34:35] offset:-1984
	global_load_ushort v134, v77, s[34:35] offset:2112
	v_add_u32_e32 v78, 0x77c00, v70
	global_load_ushort v101, v78, s[34:35] offset:-2048
	global_load_ushort v135, v78, s[34:35] offset:2048
	global_load_ushort v102, v78, s[34:35] offset:-1984
	global_load_ushort v136, v78, s[34:35] offset:2112
	v_add_u32_e32 v79, 0x85800, v70
	global_load_ushort v103, v79, s[34:35] offset:-2048
	global_load_ushort v137, v79, s[34:35] offset:2048
	global_load_ushort v104, v79, s[34:35] offset:-1984
	global_load_ushort v138, v79, s[34:35] offset:2112
	v_add_u32_e32 v80, 0x88400, v70
	global_load_ushort v105, v80, s[34:35] offset:-2048
	global_load_ushort v139, v80, s[34:35] offset:2048
	global_load_ushort v106, v80, s[34:35] offset:-1984
	global_load_ushort v140, v80, s[34:35] offset:2112
	v_add_u32_e32 v81, 0x8b000, v70
	global_load_ushort v107, v81, s[34:35] offset:-2048
	global_load_ushort v141, v81, s[34:35] offset:2048
	global_load_ushort v108, v81, s[34:35] offset:-1984
	global_load_ushort v142, v81, s[34:35] offset:2112
	v_add_u32_e32 v82, 0x8dc00, v70
	global_load_ushort v109, v82, s[34:35] offset:-2048
	global_load_ushort v143, v82, s[34:35] offset:2048
	global_load_ushort v110, v82, s[34:35] offset:-1984
	global_load_ushort v144, v82, s[34:35] offset:2112
	v_add_u32_e32 v83, 0x9b800, v70
	global_load_ushort v111, v83, s[34:35] offset:-2048
	global_load_ushort v145, v83, s[34:35] offset:2048
	global_load_ushort v112, v83, s[34:35] offset:-1984
	global_load_ushort v146, v83, s[34:35] offset:2112
	v_add_u32_e32 v84, 0x9e400, v70
	global_load_ushort v113, v84, s[34:35] offset:-2048
	global_load_ushort v147, v84, s[34:35] offset:2048
	global_load_ushort v114, v84, s[34:35] offset:-1984
	global_load_ushort v148, v84, s[34:35] offset:2112
	v_add_u32_e32 v85, 0xa1000, v70
	global_load_ushort v116, v85, s[34:35] offset:-2048
	global_load_ushort v149, v85, s[34:35] offset:2048
	global_load_ushort v117, v85, s[34:35] offset:-1984
	global_load_ushort v150, v85, s[34:35] offset:2112
	v_add_u32_e32 v86, 0xa3c00, v70
	global_load_ushort v118, v86, s[34:35] offset:-2048
	global_load_ushort v151, v86, s[34:35] offset:2048
	global_load_ushort v119, v86, s[34:35] offset:-1984
	global_load_ushort v152, v86, s[34:35] offset:2112
	s_waitcnt vmcnt(0)
; DI bf16_t cv1(float x) { return (bf16_t)(pk2(x, 0.f) & 0xffffu); }
; DI float bf2f(bf16_t v) { return (float)__builtin_bit_cast(_Float16, v); }
; DI int crow(int i, int h) { return (i & 3) + 8 * (i >> 2) + 4 * h; }
;     DI void operator()(int unit, const f32x16 (&acc)[MT][NT]) const {
;     ...
; #pragma unroll
;         for (int mi = 0; mi < MT; ++mi)
; #pragma unroll
;             for (int nj = 0; nj < NT; ++nj)
; #pragma unroll
;                 for (int i = 0; i < 16; ++i) {
;                     bf16_t* rowp = priv + (mi * 32 + crow(i, h) + (mi == 2 ? d2 : 0)) * PRIVW; const int c = unit * UW + nj * 32 + r;
;                     float v = bf2f(rowp[gcol + c]) * acc[mi][nj][i];
;                     if (SECOND) v += bf2f(rowp[PC_M + c]);
;                     rowp[PC_M + c] = cv1(v);
;                     if (i == 15) __builtin_amdgcn_sched_barrier(0);
;                 }
	v_fma_mixlo_f16 v87, v18, v87, v120 op_sel_hi:[0,1,1]
	global_store_short v71, v87, s[34:35] offset:2048
	v_fma_mixlo_f16 v88, v2, v88, v121 op_sel_hi:[0,1,1]
	global_store_short v71, v88, s[34:35] offset:2112
	v_fma_mixlo_f16 v89, v19, v89, v122 op_sel_hi:[0,1,1]
	global_store_short v72, v89, s[34:35] offset:2048
	v_fma_mixlo_f16 v90, v3, v90, v123 op_sel_hi:[0,1,1]
	global_store_short v72, v90, s[34:35] offset:2112
	v_fma_mixlo_f16 v91, v20, v91, v124 op_sel_hi:[0,1,1]
	global_store_short v73, v91, s[34:35] offset:2048
	v_fma_mixlo_f16 v92, v4, v92, v125 op_sel_hi:[0,1,1]
	global_store_short v73, v92, s[34:35] offset:2112
	v_fma_mixlo_f16 v93, v21, v93, v126 op_sel_hi:[0,1,1]
	global_store_short v74, v93, s[34:35] offset:2048
	v_fma_mixlo_f16 v94, v5, v94, v127 op_sel_hi:[0,1,1]
	global_store_short v74, v94, s[34:35] offset:2112
	v_fma_mixlo_f16 v95, v22, v95, v129 op_sel_hi:[0,1,1]
	global_store_short v75, v95, s[34:35] offset:2048
	v_fma_mixlo_f16 v96, v6, v96, v130 op_sel_hi:[0,1,1]
	global_store_short v75, v96, s[34:35] offset:2112
	v_fma_mixlo_f16 v97, v23, v97, v131 op_sel_hi:[0,1,1]
	global_store_short v76, v97, s[34:35] offset:2048
	v_fma_mixlo_f16 v98, v7, v98, v132 op_sel_hi:[0,1,1]
	global_store_short v76, v98, s[34:35] offset:2112
	v_fma_mixlo_f16 v99, v24, v99, v133 op_sel_hi:[0,1,1]
	global_store_short v77, v99, s[34:35] offset:2048
	v_fma_mixlo_f16 v100, v8, v100, v134 op_sel_hi:[0,1,1]
	global_store_short v77, v100, s[34:35] offset:2112
	v_fma_mixlo_f16 v101, v25, v101, v135 op_sel_hi:[0,1,1]
	global_store_short v78, v101, s[34:35] offset:2048
	v_fma_mixlo_f16 v102, v9, v102, v136 op_sel_hi:[0,1,1]
	global_store_short v78, v102, s[34:35] offset:2112
	v_fma_mixlo_f16 v103, v26, v103, v137 op_sel_hi:[0,1,1]
	global_store_short v79, v103, s[34:35] offset:2048
	v_fma_mixlo_f16 v104, v10, v104, v138 op_sel_hi:[0,1,1]
	global_store_short v79, v104, s[34:35] offset:2112
	v_fma_mixlo_f16 v105, v27, v105, v139 op_sel_hi:[0,1,1]
	global_store_short v80, v105, s[34:35] offset:2048
	v_fma_mixlo_f16 v106, v11, v106, v140 op_sel_hi:[0,1,1]
	global_store_short v80, v106, s[34:35] offset:2112
	v_fma_mixlo_f16 v107, v28, v107, v141 op_sel_hi:[0,1,1]
	global_store_short v81, v107, s[34:35] offset:2048
	v_fma_mixlo_f16 v108, v12, v108, v142 op_sel_hi:[0,1,1]
	global_store_short v81, v108, s[34:35] offset:2112
	v_fma_mixlo_f16 v109, v29, v109, v143 op_sel_hi:[0,1,1]
	global_store_short v82, v109, s[34:35] offset:2048
	v_fma_mixlo_f16 v110, v13, v110, v144 op_sel_hi:[0,1,1]
	global_store_short v82, v110, s[34:35] offset:2112
	v_fma_mixlo_f16 v111, v30, v111, v145 op_sel_hi:[0,1,1]
	global_store_short v83, v111, s[34:35] offset:2048
	v_fma_mixlo_f16 v112, v14, v112, v146 op_sel_hi:[0,1,1]
	global_store_short v83, v112, s[34:35] offset:2112
	v_fma_mixlo_f16 v113, v31, v113, v147 op_sel_hi:[0,1,1]
	global_store_short v84, v113, s[34:35] offset:2048
	v_fma_mixlo_f16 v114, v15, v114, v148 op_sel_hi:[0,1,1]
	global_store_short v84, v114, s[34:35] offset:2112
	v_fma_mixlo_f16 v116, v32, v116, v149 op_sel_hi:[0,1,1]
	global_store_short v85, v116, s[34:35] offset:2048
	v_fma_mixlo_f16 v117, v16, v117, v150 op_sel_hi:[0,1,1]
	global_store_short v85, v117, s[34:35] offset:2112
	v_fma_mixlo_f16 v118, v33, v118, v151 op_sel_hi:[0,1,1]
	global_store_short v86, v118, s[34:35] offset:2048
	v_fma_mixlo_f16 v119, v17, v119, v152 op_sel_hi:[0,1,1]
	global_store_short v86, v119, s[34:35] offset:2112
	s_add_i32 s2, s1, 8
	s_cmp_lt_i32 s1, 8
	s_mov_b32 s1, s2
	s_cbranch_scc1 .LBB0_511
	s_movk_i32 s17, 0x810
	s_movk_i32 s64, 0x3fff

; #define MFMA32(a, b, c) __builtin_amdgcn_mfma_f32_32x32x16_f16((a), (b), (c), 0, 0, 0)
; template <int K, class Epi>
; DI void gemm64_res(const bf16_t* A, int lda, const bf16_t* Wp, int NU, unsigned char* lds, const Epi& epi) {
;     ...
; #pragma unroll 1
;         for (int kk = 0; kk < KS; kk += PD) {
; #pragma unroll
;             for (int s = 0; s < PD; ++s) {
;                 const int ks = kk + s, ksr = (ks + rot) & (KS - 1);
;                 const bf16x8 a0 = *(const bf16x8*)(ab + ksr * 32), a1 = *(const bf16x8*)(ab + 32 * LD + ksr * 32);
; #pragma unroll
;                 for (int j = 0; j < NT; ++j) { acc[0][j] = MFMA32(a0, __builtin_bit_cast(bf16x8, bq[s][j]), acc[0][j]); acc[1][j] = MFMA32(a1, __builtin_bit_cast(bf16x8, bq[s][j]), acc[1][j]); }
;                 int nk = ks + PD; nk = nk < KS ? nk : KS - 1; nk = (nk + rot) & (KS - 1);
; #pragma unroll
;                 for (int j = 0; j < NT; ++j) bq[s][j] = bp[(size_t)nk * kstr + j * 64];
;             }
;         }
.Lkout2_loop:
	s_and_b32 s8, s3, 63
	s_lshl_b32 s8, s8, 5
	s_add_i32 s3, s3, 1
	v_add_u32_e32 v73, s8, v0
	v_add_u32_e32 v112, s8, v72
	ds_read_b128 v[152:155], v73
	ds_read_b128 v[156:159], v112
	s_waitcnt vmcnt(15) lgkmcnt(2)
	v_mfma_f32_32x32x16_f16 v[50:65], v[144:147], v[76:79], v[50:65]
	v_mfma_f32_32x32x16_f16 v[18:33], v[148:151], v[76:79], v[18:33]
	s_waitcnt vmcnt(14)
	v_mfma_f32_32x32x16_f16 v[34:49], v[144:147], v[80:83], v[34:49]
	v_mfma_f32_32x32x16_f16 v[2:17], v[148:151], v[80:83], v[2:17]
	s_and_b32 s8, s6, 63
	s_add_i32 s6, s6, 1
	s_mul_i32 s100, s8, 0x8000
	v_lshl_add_u64 v[74:75], v[68:69], 0, s[100:101]
	global_load_dwordx4 v[76:79], v[74:75], off
	global_load_dwordx4 v[80:83], v[74:75], off offset:1024
	s_and_b32 s8, s3, 63
	s_lshl_b32 s8, s8, 5
	s_add_i32 s3, s3, 1
	v_add_u32_e32 v73, s8, v0
	v_add_u32_e32 v112, s8, v72
	ds_read_b128 v[144:147], v73
	ds_read_b128 v[148:151], v112
	s_waitcnt vmcnt(15) lgkmcnt(2)
	v_mfma_f32_32x32x16_f16 v[50:65], v[152:155], v[84:87], v[50:65]
	v_mfma_f32_32x32x16_f16 v[18:33], v[156:159], v[84:87], v[18:33]
	s_waitcnt vmcnt(14)
	v_mfma_f32_32x32x16_f16 v[34:49], v[152:155], v[88:91], v[34:49]
	v_mfma_f32_32x32x16_f16 v[2:17], v[156:159], v[88:91], v[2:17]
	s_and_b32 s8, s6, 63
	s_add_i32 s6, s6, 1
	s_mul_i32 s100, s8, 0x8000
	v_lshl_add_u64 v[74:75], v[68:69], 0, s[100:101]
	global_load_dwordx4 v[84:87], v[74:75], off
	global_load_dwordx4 v[88:91], v[74:75], off offset:1024
	s_and_b32 s8, s3, 63
	s_lshl_b32 s8, s8, 5
	s_add_i32 s3, s3, 1
	v_add_u32_e32 v73, s8, v0
	v_add_u32_e32 v112, s8, v72
	ds_read_b128 v[152:155], v73
	ds_read_b128 v[156:159], v112
	s_waitcnt vmcnt(15) lgkmcnt(2)
	v_mfma_f32_32x32x16_f16 v[50:65], v[144:147], v[92:95], v[50:65]
	v_mfma_f32_32x32x16_f16 v[18:33], v[148:151], v[92:95], v[18:33]
	s_waitcnt vmcnt(14)
	v_mfma_f32_32x32x16_f16 v[34:49], v[144:147], v[96:99], v[34:49]
	v_mfma_f32_32x32x16_f16 v[2:17], v[148:151], v[96:99], v[2:17]
	s_and_b32 s8, s6, 63
	s_add_i32 s6, s6, 1
	s_mul_i32 s100, s8, 0x8000
	v_lshl_add_u64 v[74:75], v[68:69], 0, s[100:101]
	global_load_dwordx4 v[92:95], v[74:75], off
	global_load_dwordx4 v[96:99], v[74:75], off offset:1024
	s_and_b32 s8, s3, 63
	s_lshl_b32 s8, s8, 5
	s_add_i32 s3, s3, 1
	v_add_u32_e32 v73, s8, v0
	v_add_u32_e32 v112, s8, v72
	ds_read_b128 v[144:147], v73
	ds_read_b128 v[148:151], v112
	s_waitcnt vmcnt(15) lgkmcnt(2)
	v_mfma_f32_32x32x16_f16 v[50:65], v[152:155], v[100:103], v[50:65]
	v_mfma_f32_32x32x16_f16 v[18:33], v[156:159], v[100:103], v[18:33]
	s_waitcnt vmcnt(14)
	v_mfma_f32_32x32x16_f16 v[34:49], v[152:155], v[104:107], v[34:49]
	v_mfma_f32_32x32x16_f16 v[2:17], v[156:159], v[104:107], v[2:17]
	s_and_b32 s8, s6, 63
	s_add_i32 s6, s6, 1
	s_mul_i32 s100, s8, 0x8000
	v_lshl_add_u64 v[74:75], v[68:69], 0, s[100:101]
	global_load_dwordx4 v[100:103], v[74:75], off
	global_load_dwordx4 v[104:107], v[74:75], off offset:1024
	s_and_b32 s8, s3, 63
	s_lshl_b32 s8, s8, 5
	s_add_i32 s3, s3, 1
	v_add_u32_e32 v73, s8, v0
	v_add_u32_e32 v112, s8, v72
	ds_read_b128 v[152:155], v73
	ds_read_b128 v[156:159], v112
	s_waitcnt vmcnt(15) lgkmcnt(2)
	v_mfma_f32_32x32x16_f16 v[50:65], v[144:147], v[108:111], v[50:65]
	v_mfma_f32_32x32x16_f16 v[18:33], v[148:151], v[108:111], v[18:33]
	s_waitcnt vmcnt(14)
	v_mfma_f32_32x32x16_f16 v[34:49], v[144:147], v[116:119], v[34:49]
	v_mfma_f32_32x32x16_f16 v[2:17], v[148:151], v[116:119], v[2:17]
	s_and_b32 s8, s6, 63
	s_add_i32 s6, s6, 1
	s_mul_i32 s100, s8, 0x8000
	v_lshl_add_u64 v[74:75], v[68:69], 0, s[100:101]
	global_load_dwordx4 v[108:111], v[74:75], off
	global_load_dwordx4 v[116:119], v[74:75], off offset:1024
	s_and_b32 s8, s3, 63
	s_lshl_b32 s8, s8, 5
	s_add_i32 s3, s3, 1
	v_add_u32_e32 v73, s8, v0
	v_add_u32_e32 v112, s8, v72
	ds_read_b128 v[144:147], v73
	ds_read_b128 v[148:151], v112
	s_waitcnt vmcnt(15) lgkmcnt(2)
	v_mfma_f32_32x32x16_f16 v[50:65], v[152:155], v[120:123], v[50:65]
	v_mfma_f32_32x32x16_f16 v[18:33], v[156:159], v[120:123], v[18:33]
	s_waitcnt vmcnt(14)
	v_mfma_f32_32x32x16_f16 v[34:49], v[152:155], v[124:127], v[34:49]
	v_mfma_f32_32x32x16_f16 v[2:17], v[156:159], v[124:127], v[2:17]
	s_and_b32 s8, s6, 63
	s_add_i32 s6, s6, 1
	s_mul_i32 s100, s8, 0x8000
	v_lshl_add_u64 v[74:75], v[68:69], 0, s[100:101]
	global_load_dwordx4 v[120:123], v[74:75], off
	global_load_dwordx4 v[124:127], v[74:75], off offset:1024
	s_and_b32 s8, s3, 63
	s_lshl_b32 s8, s8, 5
	s_add_i32 s3, s3, 1
	v_add_u32_e32 v73, s8, v0
	v_add_u32_e32 v112, s8, v72
	ds_read_b128 v[152:155], v73
	ds_read_b128 v[156:159], v112
	s_waitcnt vmcnt(15) lgkmcnt(2)
	v_mfma_f32_32x32x16_f16 v[50:65], v[144:147], v[128:131], v[50:65]
	v_mfma_f32_32x32x16_f16 v[18:33], v[148:151], v[128:131], v[18:33]
	s_waitcnt vmcnt(14)
	v_mfma_f32_32x32x16_f16 v[34:49], v[144:147], v[132:135], v[34:49]
	v_mfma_f32_32x32x16_f16 v[2:17], v[148:151], v[132:135], v[2:17]
	s_and_b32 s8, s6, 63
	s_add_i32 s6, s6, 1
	s_mul_i32 s100, s8, 0x8000
	v_lshl_add_u64 v[74:75], v[68:69], 0, s[100:101]
	global_load_dwordx4 v[128:131], v[74:75], off
	global_load_dwordx4 v[132:135], v[74:75], off offset:1024
	s_and_b32 s8, s3, 63
	s_lshl_b32 s8, s8, 5
	s_add_i32 s3, s3, 1
	v_add_u32_e32 v73, s8, v0
	v_add_u32_e32 v112, s8, v72
	ds_read_b128 v[144:147], v73
	ds_read_b128 v[148:151], v112
	s_waitcnt vmcnt(15) lgkmcnt(2)
	v_mfma_f32_32x32x16_f16 v[50:65], v[152:155], v[136:139], v[50:65]
	v_mfma_f32_32x32x16_f16 v[18:33], v[156:159], v[136:139], v[18:33]
	s_waitcnt vmcnt(14)
	v_mfma_f32_32x32x16_f16 v[34:49], v[152:155], v[140:143], v[34:49]
	v_mfma_f32_32x32x16_f16 v[2:17], v[156:159], v[140:143], v[2:17]
	s_and_b32 s8, s6, 63
	s_add_i32 s6, s6, 1
	s_mul_i32 s100, s8, 0x8000
	v_lshl_add_u64 v[74:75], v[68:69], 0, s[100:101]
	global_load_dwordx4 v[136:139], v[74:75], off
	global_load_dwordx4 v[140:143], v[74:75], off offset:1024
	s_add_i32 s9, s9, -1
	s_cmp_lg_u32 s9, 0
	s_cbranch_scc1 .Lkout2_loop
; #define MFMA32(a, b, c) __builtin_amdgcn_mfma_f32_32x32x16_f16((a), (b), (c), 0, 0, 0)
; DI int otid() { int t = threadIdx.x; asm volatile("" : "+v"(t)); return t; }
; DI int crow(int i, int h) { return (i & 3) + 8 * (i >> 2) + 4 * h; }
; template <int K, class Epi>
; DI void gemm64_res(const bf16_t* A, int lda, const bf16_t* Wp, int NU, unsigned char* lds, const Epi& epi) {
;     ...
; #pragma unroll 1
;         for (int kk = 0; kk < KS; kk += PD) {
; #pragma unroll
;             for (int s = 0; s < PD; ++s) {
;                 const int ks = kk + s, ksr = (ks + rot) & (KS - 1);
;                 const bf16x8 a0 = *(const bf16x8*)(ab + ksr * 32), a1 = *(const bf16x8*)(ab + 32 * LD + ksr * 32);
; #pragma unroll
;                 for (int j = 0; j < NT; ++j) { acc[0][j] = MFMA32(a0, __builtin_bit_cast(bf16x8, bq[s][j]), acc[0][j]); acc[1][j] = MFMA32(a1, __builtin_bit_cast(bf16x8, bq[s][j]), acc[1][j]); }
;                 int nk = ks + PD; nk = nk < KS ? nk : KS - 1; nk = (nk + rot) & (KS - 1);
; #pragma unroll
;                 for (int j = 0; j < NT; ++j) bq[s][j] = bp[(size_t)nk * kstr + j * 64];
;             }
;         }
;     DI void operator()(int unit, const f32x16 (&acc)[MT][NT]) const {
;         const int lane = otid() & 63, r = lane & 31, h = lane >> 5;
; #pragma unroll
;         for (int mi = 0; mi < MT; ++mi)
; #pragma unroll
;             for (int nj = 0; nj < NT; ++nj)
; #pragma unroll
;                 for (int i = 0; i < 16; ++i) { float* q = x + ((mi * 32 + crow(i, h) + (mi == 2 ? d2 : 0)) * DM + unit * UW + nj * 32 + r); *q = *q + acc[mi][nj][i]; if (i == 15) __builtin_amdgcn_sched_barrier(0); }
	s_and_b32 s8, s3, 63
	s_lshl_b32 s8, s8, 5
	s_add_i32 s3, s3, 1
	v_add_u32_e32 v73, s8, v0
	v_add_u32_e32 v112, s8, v72
	ds_read_b128 v[152:155], v73
	ds_read_b128 v[156:159], v112
	s_waitcnt vmcnt(15) lgkmcnt(2)
	v_mfma_f32_32x32x16_f16 v[50:65], v[144:147], v[76:79], v[50:65]
	v_mfma_f32_32x32x16_f16 v[18:33], v[148:151], v[76:79], v[18:33]
	s_waitcnt vmcnt(14)
	v_mfma_f32_32x32x16_f16 v[34:49], v[144:147], v[80:83], v[34:49]
	v_mfma_f32_32x32x16_f16 v[2:17], v[148:151], v[80:83], v[2:17]
	s_and_b32 s8, s3, 63
	s_lshl_b32 s8, s8, 5
	s_add_i32 s3, s3, 1
	v_add_u32_e32 v73, s8, v0
	v_add_u32_e32 v112, s8, v72
	ds_read_b128 v[144:147], v73
	ds_read_b128 v[148:151], v112
	s_waitcnt vmcnt(13) lgkmcnt(2)
	v_mfma_f32_32x32x16_f16 v[50:65], v[152:155], v[84:87], v[50:65]
	v_mfma_f32_32x32x16_f16 v[18:33], v[156:159], v[84:87], v[18:33]
	s_waitcnt vmcnt(12)
	v_mfma_f32_32x32x16_f16 v[34:49], v[152:155], v[88:91], v[34:49]
	v_mfma_f32_32x32x16_f16 v[2:17], v[156:159], v[88:91], v[2:17]
	s_and_b32 s8, s3, 63
	s_lshl_b32 s8, s8, 5
	s_add_i32 s3, s3, 1
	v_add_u32_e32 v73, s8, v0
	v_add_u32_e32 v112, s8, v72
	ds_read_b128 v[152:155], v73
	ds_read_b128 v[156:159], v112
	s_waitcnt vmcnt(11) lgkmcnt(2)
	v_mfma_f32_32x32x16_f16 v[50:65], v[144:147], v[92:95], v[50:65]
	v_mfma_f32_32x32x16_f16 v[18:33], v[148:151], v[92:95], v[18:33]
	s_waitcnt vmcnt(10)
	v_mfma_f32_32x32x16_f16 v[34:49], v[144:147], v[96:99], v[34:49]
	v_mfma_f32_32x32x16_f16 v[2:17], v[148:151], v[96:99], v[2:17]
	s_and_b32 s8, s3, 63
	s_lshl_b32 s8, s8, 5
	s_add_i32 s3, s3, 1
	v_add_u32_e32 v73, s8, v0
	v_add_u32_e32 v112, s8, v72
	ds_read_b128 v[144:147], v73
	ds_read_b128 v[148:151], v112
	s_waitcnt vmcnt(9) lgkmcnt(2)
	v_mfma_f32_32x32x16_f16 v[50:65], v[152:155], v[100:103], v[50:65]
	v_mfma_f32_32x32x16_f16 v[18:33], v[156:159], v[100:103], v[18:33]
	s_waitcnt vmcnt(8)
	v_mfma_f32_32x32x16_f16 v[34:49], v[152:155], v[104:107], v[34:49]
	v_mfma_f32_32x32x16_f16 v[2:17], v[156:159], v[104:107], v[2:17]
	s_and_b32 s8, s3, 63
	s_lshl_b32 s8, s8, 5
	s_add_i32 s3, s3, 1
	v_add_u32_e32 v73, s8, v0
	v_add_u32_e32 v112, s8, v72
	ds_read_b128 v[152:155], v73
	ds_read_b128 v[156:159], v112
	s_waitcnt vmcnt(7) lgkmcnt(2)
	v_mfma_f32_32x32x16_f16 v[50:65], v[144:147], v[108:111], v[50:65]
	v_mfma_f32_32x32x16_f16 v[18:33], v[148:151], v[108:111], v[18:33]
	s_waitcnt vmcnt(6)
	v_mfma_f32_32x32x16_f16 v[34:49], v[144:147], v[116:119], v[34:49]
	v_mfma_f32_32x32x16_f16 v[2:17], v[148:151], v[116:119], v[2:17]
	s_and_b32 s8, s3, 63
	s_lshl_b32 s8, s8, 5
	s_add_i32 s3, s3, 1
	v_add_u32_e32 v73, s8, v0
	v_add_u32_e32 v112, s8, v72
	ds_read_b128 v[144:147], v73
	ds_read_b128 v[148:151], v112
	s_waitcnt vmcnt(5) lgkmcnt(2)
	v_mfma_f32_32x32x16_f16 v[50:65], v[152:155], v[120:123], v[50:65]
	v_mfma_f32_32x32x16_f16 v[18:33], v[156:159], v[120:123], v[18:33]
	s_waitcnt vmcnt(4)
	v_mfma_f32_32x32x16_f16 v[34:49], v[152:155], v[124:127], v[34:49]
	v_mfma_f32_32x32x16_f16 v[2:17], v[156:159], v[124:127], v[2:17]
	s_and_b32 s8, s3, 63
	s_lshl_b32 s8, s8, 5
	s_add_i32 s3, s3, 1
	v_add_u32_e32 v73, s8, v0
	v_add_u32_e32 v112, s8, v72
	ds_read_b128 v[152:155], v73
	ds_read_b128 v[156:159], v112
	s_waitcnt vmcnt(3) lgkmcnt(2)
	v_mfma_f32_32x32x16_f16 v[50:65], v[144:147], v[128:131], v[50:65]
	v_mfma_f32_32x32x16_f16 v[18:33], v[148:151], v[128:131], v[18:33]
	s_waitcnt vmcnt(2)
	v_mfma_f32_32x32x16_f16 v[34:49], v[144:147], v[132:135], v[34:49]
	v_mfma_f32_32x32x16_f16 v[2:17], v[148:151], v[132:135], v[2:17]
	s_waitcnt vmcnt(1) lgkmcnt(0)
	v_mfma_f32_32x32x16_f16 v[50:65], v[152:155], v[136:139], v[50:65]
	v_mfma_f32_32x32x16_f16 v[18:33], v[156:159], v[136:139], v[18:33]
	s_waitcnt vmcnt(0)
	v_mfma_f32_32x32x16_f16 v[34:49], v[152:155], v[140:143], v[34:49]
	v_mfma_f32_32x32x16_f16 v[2:17], v[156:159], v[140:143], v[2:17]
	s_nop 7
	s_nop 3
	s_waitcnt vmcnt(0)
	v_and_b32_e32 v68, 31, v176
	v_lshlrev_b32_e32 v69, 9, v176
	v_and_b32_e32 v69, 0x4000, v69
	v_lshl_or_b32 v70, v68, 2, v69
	v_lshl_add_u32 v70, s29, 8, v70
	v_add_u32_e32 v71, 0x1000, v70
	global_load_dword v80, v71, s[0:1] offset:-4096
	global_load_dword v81, v71, s[0:1] offset:-3968
	global_load_dword v82, v71, s[0:1] offset:0
	global_load_dword v83, v71, s[0:1] offset:128
	v_add_u32_e32 v73, 0x3000, v70
	global_load_dword v84, v73, s[0:1] offset:-4096
	global_load_dword v85, v73, s[0:1] offset:-3968
	global_load_dword v86, v73, s[0:1] offset:0
	global_load_dword v87, v73, s[0:1] offset:128
	v_add_u32_e32 v74, 0x9000, v70
	global_load_dword v88, v74, s[0:1] offset:-4096
	global_load_dword v89, v74, s[0:1] offset:-3968
	global_load_dword v90, v74, s[0:1] offset:0
	global_load_dword v91, v74, s[0:1] offset:128
	v_add_u32_e32 v75, 0xb000, v70
	global_load_dword v92, v75, s[0:1] offset:-4096
	global_load_dword v93, v75, s[0:1] offset:-3968
	global_load_dword v94, v75, s[0:1] offset:0
	global_load_dword v95, v75, s[0:1] offset:128
	v_add_u32_e32 v76, 0x11000, v70
	global_load_dword v96, v76, s[0:1] offset:-4096
	global_load_dword v97, v76, s[0:1] offset:-3968
	global_load_dword v98, v76, s[0:1] offset:0
	global_load_dword v99, v76, s[0:1] offset:128
	v_add_u32_e32 v77, 0x13000, v70
	global_load_dword v100, v77, s[0:1] offset:-4096
	global_load_dword v101, v77, s[0:1] offset:-3968
	global_load_dword v102, v77, s[0:1] offset:0
	global_load_dword v103, v77, s[0:1] offset:128
	v_add_u32_e32 v78, 0x19000, v70
	global_load_dword v104, v78, s[0:1] offset:-4096
	global_load_dword v105, v78, s[0:1] offset:-3968
	global_load_dword v106, v78, s[0:1] offset:0
	global_load_dword v107, v78, s[0:1] offset:128
	v_add_u32_e32 v79, 0x1b000, v70
	global_load_dword v108, v79, s[0:1] offset:-4096
	global_load_dword v109, v79, s[0:1] offset:-3968
	global_load_dword v110, v79, s[0:1] offset:0
	global_load_dword v111, v79, s[0:1] offset:128
	s_waitcnt vmcnt(0)
; DI int otid() { int t = threadIdx.x; asm volatile("" : "+v"(t)); return t; }
; DI int crow(int i, int h) { return (i & 3) + 8 * (i >> 2) + 4 * h; }
;     DI void operator()(int unit, const f32x16 (&acc)[MT][NT]) const {
;         const int lane = otid() & 63, r = lane & 31, h = lane >> 5;
; #pragma unroll
;         for (int mi = 0; mi < MT; ++mi)
; #pragma unroll
;             for (int nj = 0; nj < NT; ++nj)
; #pragma unroll
;                 for (int i = 0; i < 16; ++i) { float* q = x + ((mi * 32 + crow(i, h) + (mi == 2 ? d2 : 0)) * DM + unit * UW + nj * 32 + r); *q = *q + acc[mi][nj][i]; if (i == 15) __builtin_amdgcn_sched_barrier(0); }
	v_add_f32_e32 v80, v50, v80
	global_store_dword v71, v80, s[0:1] offset:-4096
	v_add_f32_e32 v81, v34, v81
	global_store_dword v71, v81, s[0:1] offset:-3968
	v_add_f32_e32 v82, v51, v82
	global_store_dword v71, v82, s[0:1] offset:0
	v_add_f32_e32 v83, v35, v83
	global_store_dword v71, v83, s[0:1] offset:128
	v_add_f32_e32 v84, v52, v84
	global_store_dword v73, v84, s[0:1] offset:-4096
	v_add_f32_e32 v85, v36, v85
	global_store_dword v73, v85, s[0:1] offset:-3968
	v_add_f32_e32 v86, v53, v86
	global_store_dword v73, v86, s[0:1] offset:0
	v_add_f32_e32 v87, v37, v87
	global_store_dword v73, v87, s[0:1] offset:128
	v_add_f32_e32 v88, v54, v88
	global_store_dword v74, v88, s[0:1] offset:-4096
	v_add_f32_e32 v89, v38, v89
	global_store_dword v74, v89, s[0:1] offset:-3968
	v_add_f32_e32 v90, v55, v90
	global_store_dword v74, v90, s[0:1] offset:0
	v_add_f32_e32 v91, v39, v91
	global_store_dword v74, v91, s[0:1] offset:128
	v_add_f32_e32 v92, v56, v92
	global_store_dword v75, v92, s[0:1] offset:-4096
	v_add_f32_e32 v93, v40, v93
	global_store_dword v75, v93, s[0:1] offset:-3968
	v_add_f32_e32 v94, v57, v94
	global_store_dword v75, v94, s[0:1] offset:0
	v_add_f32_e32 v95, v41, v95
	global_store_dword v75, v95, s[0:1] offset:128
	v_add_f32_e32 v96, v58, v96
	global_store_dword v76, v96, s[0:1] offset:-4096
	v_add_f32_e32 v97, v42, v97
	global_store_dword v76, v97, s[0:1] offset:-3968
	v_add_f32_e32 v98, v59, v98
	global_store_dword v76, v98, s[0:1] offset:0
	v_add_f32_e32 v99, v43, v99
	global_store_dword v76, v99, s[0:1] offset:128
	v_add_f32_e32 v100, v60, v100
	global_store_dword v77, v100, s[0:1] offset:-4096
	v_add_f32_e32 v101, v44, v101
	global_store_dword v77, v101, s[0:1] offset:-3968
	v_add_f32_e32 v102, v61, v102
	global_store_dword v77, v102, s[0:1] offset:0
	v_add_f32_e32 v103, v45, v103
	global_store_dword v77, v103, s[0:1] offset:128
	v_add_f32_e32 v104, v62, v104
	global_store_dword v78, v104, s[0:1] offset:-4096
	v_add_f32_e32 v105, v46, v105
	global_store_dword v78, v105, s[0:1] offset:-3968
	v_add_f32_e32 v106, v63, v106
	global_store_dword v78, v106, s[0:1] offset:0
	v_add_f32_e32 v107, v47, v107
	global_store_dword v78, v107, s[0:1] offset:128
	v_add_f32_e32 v108, v64, v108
	global_store_dword v79, v108, s[0:1] offset:-4096
	v_add_f32_e32 v109, v48, v109
	global_store_dword v79, v109, s[0:1] offset:-3968
	v_add_f32_e32 v110, v65, v110
	global_store_dword v79, v110, s[0:1] offset:0
	v_add_f32_e32 v111, v49, v111
	global_store_dword v79, v111, s[0:1] offset:128
	v_add_u32_e32 v71, 0x21000, v70
	global_load_dword v80, v71, s[0:1] offset:-4096
	global_load_dword v81, v71, s[0:1] offset:-3968
	global_load_dword v82, v71, s[0:1] offset:0
	global_load_dword v83, v71, s[0:1] offset:128
	v_add_u32_e32 v73, 0x23000, v70
	global_load_dword v84, v73, s[0:1] offset:-4096
	global_load_dword v85, v73, s[0:1] offset:-3968
	global_load_dword v86, v73, s[0:1] offset:0
	global_load_dword v87, v73, s[0:1] offset:128
	v_add_u32_e32 v74, 0x29000, v70
	global_load_dword v88, v74, s[0:1] offset:-4096
	global_load_dword v89, v74, s[0:1] offset:-3968
	global_load_dword v90, v74, s[0:1] offset:0
	global_load_dword v91, v74, s[0:1] offset:128
	v_add_u32_e32 v75, 0x2b000, v70
	global_load_dword v92, v75, s[0:1] offset:-4096
	global_load_dword v93, v75, s[0:1] offset:-3968
	global_load_dword v94, v75, s[0:1] offset:0
	global_load_dword v95, v75, s[0:1] offset:128
	v_add_u32_e32 v76, 0x31000, v70
	global_load_dword v96, v76, s[0:1] offset:-4096
	global_load_dword v97, v76, s[0:1] offset:-3968
	global_load_dword v98, v76, s[0:1] offset:0
	global_load_dword v99, v76, s[0:1] offset:128
	v_add_u32_e32 v77, 0x33000, v70
	global_load_dword v100, v77, s[0:1] offset:-4096
	global_load_dword v101, v77, s[0:1] offset:-3968
	global_load_dword v102, v77, s[0:1] offset:0
	global_load_dword v103, v77, s[0:1] offset:128
	v_add_u32_e32 v78, 0x39000, v70
	global_load_dword v104, v78, s[0:1] offset:-4096
	global_load_dword v105, v78, s[0:1] offset:-3968
	global_load_dword v106, v78, s[0:1] offset:0
	global_load_dword v107, v78, s[0:1] offset:128
	v_add_u32_e32 v79, 0x3b000, v70
	global_load_dword v108, v79, s[0:1] offset:-4096
	global_load_dword v109, v79, s[0:1] offset:-3968
	global_load_dword v110, v79, s[0:1] offset:0
	global_load_dword v111, v79, s[0:1] offset:128
	s_waitcnt vmcnt(0)
	v_add_f32_e32 v80, v18, v80
	global_store_dword v71, v80, s[0:1] offset:-4096
	v_add_f32_e32 v81, v2, v81
	global_store_dword v71, v81, s[0:1] offset:-3968
	v_add_f32_e32 v82, v19, v82
	global_store_dword v71, v82, s[0:1] offset:0
	v_add_f32_e32 v83, v3, v83
	global_store_dword v71, v83, s[0:1] offset:128
	v_add_f32_e32 v84, v20, v84
	global_store_dword v73, v84, s[0:1] offset:-4096
	v_add_f32_e32 v85, v4, v85
	global_store_dword v73, v85, s[0:1] offset:-3968
	v_add_f32_e32 v86, v21, v86
	global_store_dword v73, v86, s[0:1] offset:0
	v_add_f32_e32 v87, v5, v87
	global_store_dword v73, v87, s[0:1] offset:128
	v_add_f32_e32 v88, v22, v88
	global_store_dword v74, v88, s[0:1] offset:-4096
	v_add_f32_e32 v89, v6, v89
	global_store_dword v74, v89, s[0:1] offset:-3968
	v_add_f32_e32 v90, v23, v90
	global_store_dword v74, v90, s[0:1] offset:0
	v_add_f32_e32 v91, v7, v91
	global_store_dword v74, v91, s[0:1] offset:128
	v_add_f32_e32 v92, v24, v92
	global_store_dword v75, v92, s[0:1] offset:-4096
	v_add_f32_e32 v93, v8, v93
	global_store_dword v75, v93, s[0:1] offset:-3968
	v_add_f32_e32 v94, v25, v94
	global_store_dword v75, v94, s[0:1] offset:0
	v_add_f32_e32 v95, v9, v95
	global_store_dword v75, v95, s[0:1] offset:128
	v_add_f32_e32 v96, v26, v96
	global_store_dword v76, v96, s[0:1] offset:-4096
	v_add_f32_e32 v97, v10, v97
	global_store_dword v76, v97, s[0:1] offset:-3968
	v_add_f32_e32 v98, v27, v98
	global_store_dword v76, v98, s[0:1] offset:0
	v_add_f32_e32 v99, v11, v99
	global_store_dword v76, v99, s[0:1] offset:128
	v_add_f32_e32 v100, v28, v100
	global_store_dword v77, v100, s[0:1] offset:-4096
	v_add_f32_e32 v101, v12, v101
	global_store_dword v77, v101, s[0:1] offset:-3968
	v_add_f32_e32 v102, v29, v102
	global_store_dword v77, v102, s[0:1] offset:0
	v_add_f32_e32 v103, v13, v103
	global_store_dword v77, v103, s[0:1] offset:128
	v_add_f32_e32 v104, v30, v104
	global_store_dword v78, v104, s[0:1] offset:-4096
	v_add_f32_e32 v105, v14, v105
	global_store_dword v78, v105, s[0:1] offset:-3968
	v_add_f32_e32 v106, v31, v106
	global_store_dword v78, v106, s[0:1] offset:0
	v_add_f32_e32 v107, v15, v107
	global_store_dword v78, v107, s[0:1] offset:128
	v_add_f32_e32 v108, v32, v108
	global_store_dword v79, v108, s[0:1] offset:-4096
	v_add_f32_e32 v109, v16, v109
	global_store_dword v79, v109, s[0:1] offset:-3968
	v_add_f32_e32 v110, v33, v110
	global_store_dword v79, v110, s[0:1] offset:0
	v_add_f32_e32 v111, v17, v111
	global_store_dword v79, v111, s[0:1] offset:128
	s_add_i32 s2, s29, 8
	s_cmp_lt_i32 s29, 8
	s_mov_b32 s29, s2
	s_cbranch_scc1 .LBB0_517
	s_movk_i32 s17, 0x810
	s_movk_i32 s64, 0x3fff

; #define MFMA32(a, b, c) __builtin_amdgcn_mfma_f32_32x32x16_f16((a), (b), (c), 0, 0, 0)
; template <int K, class Epi>
; DI void gemm64_res(const bf16_t* A, int lda, const bf16_t* Wp, int NU, unsigned char* lds, const Epi& epi) {
;     ...
; #pragma unroll 1
;         for (int kk = 0; kk < KS; kk += PD) {
; #pragma unroll
;             for (int s = 0; s < PD; ++s) {
;                 const int ks = kk + s, ksr = (ks + rot) & (KS - 1);
;                 const bf16x8 a0 = *(const bf16x8*)(ab + ksr * 32), a1 = *(const bf16x8*)(ab + 32 * LD + ksr * 32);
; #pragma unroll
;                 for (int j = 0; j < NT; ++j) { acc[0][j] = MFMA32(a0, __builtin_bit_cast(bf16x8, bq[s][j]), acc[0][j]); acc[1][j] = MFMA32(a1, __builtin_bit_cast(bf16x8, bq[s][j]), acc[1][j]); }
;                 int nk = ks + PD; nk = nk < KS ? nk : KS - 1; nk = (nk + rot) & (KS - 1);
; #pragma unroll
;                 for (int j = 0; j < NT; ++j) bq[s][j] = bp[(size_t)nk * kstr + j * 64];
;             }
;         }
.Lkxo2_loop:
	s_and_b32 s8, s6, 31
	s_lshl_b32 s8, s8, 5
	s_add_i32 s6, s6, 1
	v_add_u32_e32 v112, s8, v0
	ds_read_b128 v[148:151], v112
	ds_read_b128 v[152:155], v112 offset:33280
	s_waitcnt vmcnt(15) lgkmcnt(2)
	v_mfma_f32_32x32x16_f16 v[50:65], v[140:143], v[72:75], v[50:65]
	v_mfma_f32_32x32x16_f16 v[18:33], v[144:147], v[72:75], v[18:33]
	s_waitcnt vmcnt(14)
	v_mfma_f32_32x32x16_f16 v[34:49], v[140:143], v[76:79], v[34:49]
	v_mfma_f32_32x32x16_f16 v[2:17], v[144:147], v[76:79], v[2:17]
	s_and_b32 s8, s7, 31
	s_add_i32 s7, s7, 1
	s_mul_i32 s100, s8, 0x8000
	v_lshl_add_u64 v[70:71], v[68:69], 0, s[100:101]
	global_load_dwordx4 v[72:75], v[70:71], off
	global_load_dwordx4 v[76:79], v[70:71], off offset:1024
	s_and_b32 s8, s6, 31
	s_lshl_b32 s8, s8, 5
	s_add_i32 s6, s6, 1
	v_add_u32_e32 v112, s8, v0
	ds_read_b128 v[140:143], v112
	ds_read_b128 v[144:147], v112 offset:33280
	s_waitcnt vmcnt(15) lgkmcnt(2)
	v_mfma_f32_32x32x16_f16 v[50:65], v[148:151], v[80:83], v[50:65]
	v_mfma_f32_32x32x16_f16 v[18:33], v[152:155], v[80:83], v[18:33]
	s_waitcnt vmcnt(14)
	v_mfma_f32_32x32x16_f16 v[34:49], v[148:151], v[84:87], v[34:49]
	v_mfma_f32_32x32x16_f16 v[2:17], v[152:155], v[84:87], v[2:17]
	s_and_b32 s8, s7, 31
	s_add_i32 s7, s7, 1
	s_mul_i32 s100, s8, 0x8000
	v_lshl_add_u64 v[70:71], v[68:69], 0, s[100:101]
	global_load_dwordx4 v[80:83], v[70:71], off
	global_load_dwordx4 v[84:87], v[70:71], off offset:1024
	s_and_b32 s8, s6, 31
	s_lshl_b32 s8, s8, 5
	s_add_i32 s6, s6, 1
	v_add_u32_e32 v112, s8, v0
	ds_read_b128 v[148:151], v112
	ds_read_b128 v[152:155], v112 offset:33280
	s_waitcnt vmcnt(15) lgkmcnt(2)
	v_mfma_f32_32x32x16_f16 v[50:65], v[140:143], v[88:91], v[50:65]
	v_mfma_f32_32x32x16_f16 v[18:33], v[144:147], v[88:91], v[18:33]
	s_waitcnt vmcnt(14)
	v_mfma_f32_32x32x16_f16 v[34:49], v[140:143], v[92:95], v[34:49]
	v_mfma_f32_32x32x16_f16 v[2:17], v[144:147], v[92:95], v[2:17]
	s_and_b32 s8, s7, 31
	s_add_i32 s7, s7, 1
	s_mul_i32 s100, s8, 0x8000
	v_lshl_add_u64 v[70:71], v[68:69], 0, s[100:101]
	global_load_dwordx4 v[88:91], v[70:71], off
	global_load_dwordx4 v[92:95], v[70:71], off offset:1024
	s_and_b32 s8, s6, 31
	s_lshl_b32 s8, s8, 5
	s_add_i32 s6, s6, 1
	v_add_u32_e32 v112, s8, v0
	ds_read_b128 v[140:143], v112
	ds_read_b128 v[144:147], v112 offset:33280
	s_waitcnt vmcnt(15) lgkmcnt(2)
	v_mfma_f32_32x32x16_f16 v[50:65], v[148:151], v[96:99], v[50:65]
	v_mfma_f32_32x32x16_f16 v[18:33], v[152:155], v[96:99], v[18:33]
	s_waitcnt vmcnt(14)
	v_mfma_f32_32x32x16_f16 v[34:49], v[148:151], v[100:103], v[34:49]
	v_mfma_f32_32x32x16_f16 v[2:17], v[152:155], v[100:103], v[2:17]
	s_and_b32 s8, s7, 31
	s_add_i32 s7, s7, 1
	s_mul_i32 s100, s8, 0x8000
	v_lshl_add_u64 v[70:71], v[68:69], 0, s[100:101]
	global_load_dwordx4 v[96:99], v[70:71], off
	global_load_dwordx4 v[100:103], v[70:71], off offset:1024
	s_and_b32 s8, s6, 31
	s_lshl_b32 s8, s8, 5
	s_add_i32 s6, s6, 1
	v_add_u32_e32 v112, s8, v0
	ds_read_b128 v[148:151], v112
	ds_read_b128 v[152:155], v112 offset:33280
	s_waitcnt vmcnt(15) lgkmcnt(2)
	v_mfma_f32_32x32x16_f16 v[50:65], v[140:143], v[104:107], v[50:65]
	v_mfma_f32_32x32x16_f16 v[18:33], v[144:147], v[104:107], v[18:33]
	s_waitcnt vmcnt(14)
	v_mfma_f32_32x32x16_f16 v[34:49], v[140:143], v[108:111], v[34:49]
	v_mfma_f32_32x32x16_f16 v[2:17], v[144:147], v[108:111], v[2:17]
	s_and_b32 s8, s7, 31
	s_add_i32 s7, s7, 1
	s_mul_i32 s100, s8, 0x8000
	v_lshl_add_u64 v[70:71], v[68:69], 0, s[100:101]
	global_load_dwordx4 v[104:107], v[70:71], off
	global_load_dwordx4 v[108:111], v[70:71], off offset:1024
	s_and_b32 s8, s6, 31
	s_lshl_b32 s8, s8, 5
	s_add_i32 s6, s6, 1
	v_add_u32_e32 v112, s8, v0
	ds_read_b128 v[140:143], v112
	ds_read_b128 v[144:147], v112 offset:33280
	s_waitcnt vmcnt(15) lgkmcnt(2)
	v_mfma_f32_32x32x16_f16 v[50:65], v[148:151], v[116:119], v[50:65]
	v_mfma_f32_32x32x16_f16 v[18:33], v[152:155], v[116:119], v[18:33]
	s_waitcnt vmcnt(14)
	v_mfma_f32_32x32x16_f16 v[34:49], v[148:151], v[120:123], v[34:49]
	v_mfma_f32_32x32x16_f16 v[2:17], v[152:155], v[120:123], v[2:17]
	s_and_b32 s8, s7, 31
	s_add_i32 s7, s7, 1
	s_mul_i32 s100, s8, 0x8000
	v_lshl_add_u64 v[70:71], v[68:69], 0, s[100:101]
	global_load_dwordx4 v[116:119], v[70:71], off
	global_load_dwordx4 v[120:123], v[70:71], off offset:1024
	s_and_b32 s8, s6, 31
	s_lshl_b32 s8, s8, 5
	s_add_i32 s6, s6, 1
	v_add_u32_e32 v112, s8, v0
	ds_read_b128 v[148:151], v112
	ds_read_b128 v[152:155], v112 offset:33280
	s_waitcnt vmcnt(15) lgkmcnt(2)
	v_mfma_f32_32x32x16_f16 v[50:65], v[140:143], v[124:127], v[50:65]
	v_mfma_f32_32x32x16_f16 v[18:33], v[144:147], v[124:127], v[18:33]
	s_waitcnt vmcnt(14)
	v_mfma_f32_32x32x16_f16 v[34:49], v[140:143], v[128:131], v[34:49]
	v_mfma_f32_32x32x16_f16 v[2:17], v[144:147], v[128:131], v[2:17]
	s_and_b32 s8, s7, 31
	s_add_i32 s7, s7, 1
	s_mul_i32 s100, s8, 0x8000
	v_lshl_add_u64 v[70:71], v[68:69], 0, s[100:101]
	global_load_dwordx4 v[124:127], v[70:71], off
	global_load_dwordx4 v[128:131], v[70:71], off offset:1024
	s_and_b32 s8, s6, 31
	s_lshl_b32 s8, s8, 5
	s_add_i32 s6, s6, 1
	v_add_u32_e32 v112, s8, v0
	ds_read_b128 v[140:143], v112
	ds_read_b128 v[144:147], v112 offset:33280
	s_waitcnt vmcnt(15) lgkmcnt(2)
	v_mfma_f32_32x32x16_f16 v[50:65], v[148:151], v[132:135], v[50:65]
	v_mfma_f32_32x32x16_f16 v[18:33], v[152:155], v[132:135], v[18:33]
	s_waitcnt vmcnt(14)
	v_mfma_f32_32x32x16_f16 v[34:49], v[148:151], v[136:139], v[34:49]
	v_mfma_f32_32x32x16_f16 v[2:17], v[152:155], v[136:139], v[2:17]
	s_and_b32 s8, s7, 31
	s_add_i32 s7, s7, 1
	s_mul_i32 s100, s8, 0x8000
	v_lshl_add_u64 v[70:71], v[68:69], 0, s[100:101]
	global_load_dwordx4 v[132:135], v[70:71], off
	global_load_dwordx4 v[136:139], v[70:71], off offset:1024
	s_add_i32 s9, s9, -1
	s_cmp_lg_u32 s9, 0
	s_cbranch_scc1 .Lkxo2_loop
; #define MFMA32(a, b, c) __builtin_amdgcn_mfma_f32_32x32x16_f16((a), (b), (c), 0, 0, 0)
; DI int otid() { int t = threadIdx.x; asm volatile("" : "+v"(t)); return t; }
; DI int crow(int i, int h) { return (i & 3) + 8 * (i >> 2) + 4 * h; }
; template <int K, class Epi>
; DI void gemm64_res(const bf16_t* A, int lda, const bf16_t* Wp, int NU, unsigned char* lds, const Epi& epi) {
;     ...
; #pragma unroll 1
;         for (int kk = 0; kk < KS; kk += PD) {
; #pragma unroll
;             for (int s = 0; s < PD; ++s) {
;                 const int ks = kk + s, ksr = (ks + rot) & (KS - 1);
;                 const bf16x8 a0 = *(const bf16x8*)(ab + ksr * 32), a1 = *(const bf16x8*)(ab + 32 * LD + ksr * 32);
; #pragma unroll
;                 for (int j = 0; j < NT; ++j) { acc[0][j] = MFMA32(a0, __builtin_bit_cast(bf16x8, bq[s][j]), acc[0][j]); acc[1][j] = MFMA32(a1, __builtin_bit_cast(bf16x8, bq[s][j]), acc[1][j]); }
;                 int nk = ks + PD; nk = nk < KS ? nk : KS - 1; nk = (nk + rot) & (KS - 1);
; #pragma unroll
;                 for (int j = 0; j < NT; ++j) bq[s][j] = bp[(size_t)nk * kstr + j * 64];
;             }
;         }
;     DI void operator()(int unit, const f32x16 (&acc)[MT][NT]) const {
;         const int lane = otid() & 63, r = lane & 31, h = lane >> 5;
; #pragma unroll
;         for (int mi = 0; mi < MT; ++mi)
; #pragma unroll
;             for (int nj = 0; nj < NT; ++nj)
; #pragma unroll
;                 for (int i = 0; i < 16; ++i) { float* q = x + ((mi * 32 + crow(i, h) + (mi == 2 ? d2 : 0)) * DM + unit * UW + nj * 32 + r); *q = *q + acc[mi][nj][i]; if (i == 15) __builtin_amdgcn_sched_barrier(0); }
	s_and_b32 s8, s6, 31
	s_lshl_b32 s8, s8, 5
	s_add_i32 s6, s6, 1
	v_add_u32_e32 v112, s8, v0
	ds_read_b128 v[148:151], v112
	ds_read_b128 v[152:155], v112 offset:33280
	s_waitcnt vmcnt(15) lgkmcnt(2)
	v_mfma_f32_32x32x16_f16 v[50:65], v[140:143], v[72:75], v[50:65]
	v_mfma_f32_32x32x16_f16 v[18:33], v[144:147], v[72:75], v[18:33]
	s_waitcnt vmcnt(14)
	v_mfma_f32_32x32x16_f16 v[34:49], v[140:143], v[76:79], v[34:49]
	v_mfma_f32_32x32x16_f16 v[2:17], v[144:147], v[76:79], v[2:17]
	s_and_b32 s8, s6, 31
	s_lshl_b32 s8, s8, 5
	s_add_i32 s6, s6, 1
	v_add_u32_e32 v112, s8, v0
	ds_read_b128 v[140:143], v112
	ds_read_b128 v[144:147], v112 offset:33280
	s_waitcnt vmcnt(13) lgkmcnt(2)
	v_mfma_f32_32x32x16_f16 v[50:65], v[148:151], v[80:83], v[50:65]
	v_mfma_f32_32x32x16_f16 v[18:33], v[152:155], v[80:83], v[18:33]
	s_waitcnt vmcnt(12)
	v_mfma_f32_32x32x16_f16 v[34:49], v[148:151], v[84:87], v[34:49]
	v_mfma_f32_32x32x16_f16 v[2:17], v[152:155], v[84:87], v[2:17]
	s_and_b32 s8, s6, 31
	s_lshl_b32 s8, s8, 5
	s_add_i32 s6, s6, 1
	v_add_u32_e32 v112, s8, v0
	ds_read_b128 v[148:151], v112
	ds_read_b128 v[152:155], v112 offset:33280
	s_waitcnt vmcnt(11) lgkmcnt(2)
	v_mfma_f32_32x32x16_f16 v[50:65], v[140:143], v[88:91], v[50:65]
	v_mfma_f32_32x32x16_f16 v[18:33], v[144:147], v[88:91], v[18:33]
	s_waitcnt vmcnt(10)
	v_mfma_f32_32x32x16_f16 v[34:49], v[140:143], v[92:95], v[34:49]
	v_mfma_f32_32x32x16_f16 v[2:17], v[144:147], v[92:95], v[2:17]
	s_and_b32 s8, s6, 31
	s_lshl_b32 s8, s8, 5
	s_add_i32 s6, s6, 1
	v_add_u32_e32 v112, s8, v0
	ds_read_b128 v[140:143], v112
	ds_read_b128 v[144:147], v112 offset:33280
	s_waitcnt vmcnt(9) lgkmcnt(2)
	v_mfma_f32_32x32x16_f16 v[50:65], v[148:151], v[96:99], v[50:65]
	v_mfma_f32_32x32x16_f16 v[18:33], v[152:155], v[96:99], v[18:33]
	s_waitcnt vmcnt(8)
	v_mfma_f32_32x32x16_f16 v[34:49], v[148:151], v[100:103], v[34:49]
	v_mfma_f32_32x32x16_f16 v[2:17], v[152:155], v[100:103], v[2:17]
	s_and_b32 s8, s6, 31
	s_lshl_b32 s8, s8, 5
	s_add_i32 s6, s6, 1
	v_add_u32_e32 v112, s8, v0
	ds_read_b128 v[148:151], v112
	ds_read_b128 v[152:155], v112 offset:33280
	s_waitcnt vmcnt(7) lgkmcnt(2)
	v_mfma_f32_32x32x16_f16 v[50:65], v[140:143], v[104:107], v[50:65]
	v_mfma_f32_32x32x16_f16 v[18:33], v[144:147], v[104:107], v[18:33]
	s_waitcnt vmcnt(6)
	v_mfma_f32_32x32x16_f16 v[34:49], v[140:143], v[108:111], v[34:49]
	v_mfma_f32_32x32x16_f16 v[2:17], v[144:147], v[108:111], v[2:17]
	s_and_b32 s8, s6, 31
	s_lshl_b32 s8, s8, 5
	s_add_i32 s6, s6, 1
	v_add_u32_e32 v112, s8, v0
	ds_read_b128 v[140:143], v112
	ds_read_b128 v[144:147], v112 offset:33280
	s_waitcnt vmcnt(5) lgkmcnt(2)
	v_mfma_f32_32x32x16_f16 v[50:65], v[148:151], v[116:119], v[50:65]
	v_mfma_f32_32x32x16_f16 v[18:33], v[152:155], v[116:119], v[18:33]
	s_waitcnt vmcnt(4)
	v_mfma_f32_32x32x16_f16 v[34:49], v[148:151], v[120:123], v[34:49]
	v_mfma_f32_32x32x16_f16 v[2:17], v[152:155], v[120:123], v[2:17]
	s_and_b32 s8, s6, 31
	s_lshl_b32 s8, s8, 5
	s_add_i32 s6, s6, 1
	v_add_u32_e32 v112, s8, v0
	ds_read_b128 v[148:151], v112
	ds_read_b128 v[152:155], v112 offset:33280
	s_waitcnt vmcnt(3) lgkmcnt(2)
	v_mfma_f32_32x32x16_f16 v[50:65], v[140:143], v[124:127], v[50:65]
	v_mfma_f32_32x32x16_f16 v[18:33], v[144:147], v[124:127], v[18:33]
	s_waitcnt vmcnt(2)
	v_mfma_f32_32x32x16_f16 v[34:49], v[140:143], v[128:131], v[34:49]
	v_mfma_f32_32x32x16_f16 v[2:17], v[144:147], v[128:131], v[2:17]
	s_waitcnt vmcnt(1) lgkmcnt(0)
	v_mfma_f32_32x32x16_f16 v[50:65], v[148:151], v[132:135], v[50:65]
	v_mfma_f32_32x32x16_f16 v[18:33], v[152:155], v[132:135], v[18:33]
	s_waitcnt vmcnt(0)
	v_mfma_f32_32x32x16_f16 v[34:49], v[148:151], v[136:139], v[34:49]
	v_mfma_f32_32x32x16_f16 v[2:17], v[152:155], v[136:139], v[2:17]
	s_nop 7
	s_nop 3
	s_waitcnt vmcnt(0)
	v_and_b32_e32 v68, 31, v176
	v_lshlrev_b32_e32 v69, 9, v176
	v_and_b32_e32 v69, 0x4000, v69
	v_lshl_or_b32 v70, v68, 2, v69
	v_lshl_add_u32 v70, s2, 8, v70
	v_add_u32_e32 v71, 0x1000, v70
	global_load_dword v79, v71, s[0:1] offset:-4096
	global_load_dword v80, v71, s[0:1] offset:-3968
	global_load_dword v81, v71, s[0:1] offset:0
	global_load_dword v82, v71, s[0:1] offset:128
	v_add_u32_e32 v72, 0x3000, v70
	global_load_dword v83, v72, s[0:1] offset:-4096
	global_load_dword v84, v72, s[0:1] offset:-3968
	global_load_dword v85, v72, s[0:1] offset:0
	global_load_dword v86, v72, s[0:1] offset:128
	v_add_u32_e32 v73, 0x9000, v70
	global_load_dword v87, v73, s[0:1] offset:-4096
	global_load_dword v88, v73, s[0:1] offset:-3968
	global_load_dword v89, v73, s[0:1] offset:0
	global_load_dword v90, v73, s[0:1] offset:128
	v_add_u32_e32 v74, 0xb000, v70
	global_load_dword v91, v74, s[0:1] offset:-4096
	global_load_dword v92, v74, s[0:1] offset:-3968
	global_load_dword v93, v74, s[0:1] offset:0
	global_load_dword v94, v74, s[0:1] offset:128
	v_add_u32_e32 v75, 0x11000, v70
	global_load_dword v95, v75, s[0:1] offset:-4096
	global_load_dword v96, v75, s[0:1] offset:-3968
	global_load_dword v97, v75, s[0:1] offset:0
	global_load_dword v98, v75, s[0:1] offset:128
	v_add_u32_e32 v76, 0x13000, v70
	global_load_dword v99, v76, s[0:1] offset:-4096
	global_load_dword v100, v76, s[0:1] offset:-3968
	global_load_dword v101, v76, s[0:1] offset:0
	global_load_dword v102, v76, s[0:1] offset:128
	v_add_u32_e32 v77, 0x19000, v70
	global_load_dword v103, v77, s[0:1] offset:-4096
	global_load_dword v104, v77, s[0:1] offset:-3968
	global_load_dword v105, v77, s[0:1] offset:0
	global_load_dword v106, v77, s[0:1] offset:128
	v_add_u32_e32 v78, 0x1b000, v70
	global_load_dword v107, v78, s[0:1] offset:-4096
	global_load_dword v108, v78, s[0:1] offset:-3968
	global_load_dword v109, v78, s[0:1] offset:0
	global_load_dword v110, v78, s[0:1] offset:128
	s_waitcnt vmcnt(0)
; DI int otid() { int t = threadIdx.x; asm volatile("" : "+v"(t)); return t; }
; DI int crow(int i, int h) { return (i & 3) + 8 * (i >> 2) + 4 * h; }
;     DI void operator()(int unit, const f32x16 (&acc)[MT][NT]) const {
;         const int lane = otid() & 63, r = lane & 31, h = lane >> 5;
; #pragma unroll
;         for (int mi = 0; mi < MT; ++mi)
; #pragma unroll
;             for (int nj = 0; nj < NT; ++nj)
; #pragma unroll
;                 for (int i = 0; i < 16; ++i) { float* q = x + ((mi * 32 + crow(i, h) + (mi == 2 ? d2 : 0)) * DM + unit * UW + nj * 32 + r); *q = *q + acc[mi][nj][i]; if (i == 15) __builtin_amdgcn_sched_barrier(0); }
	v_add_f32_e32 v79, v50, v79
	global_store_dword v71, v79, s[0:1] offset:-4096
	v_add_f32_e32 v80, v34, v80
	global_store_dword v71, v80, s[0:1] offset:-3968
	v_add_f32_e32 v81, v51, v81
	global_store_dword v71, v81, s[0:1] offset:0
	v_add_f32_e32 v82, v35, v82
	global_store_dword v71, v82, s[0:1] offset:128
	v_add_f32_e32 v83, v52, v83
	global_store_dword v72, v83, s[0:1] offset:-4096
	v_add_f32_e32 v84, v36, v84
	global_store_dword v72, v84, s[0:1] offset:-3968
	v_add_f32_e32 v85, v53, v85
	global_store_dword v72, v85, s[0:1] offset:0
	v_add_f32_e32 v86, v37, v86
	global_store_dword v72, v86, s[0:1] offset:128
	v_add_f32_e32 v87, v54, v87
	global_store_dword v73, v87, s[0:1] offset:-4096
	v_add_f32_e32 v88, v38, v88
	global_store_dword v73, v88, s[0:1] offset:-3968
	v_add_f32_e32 v89, v55, v89
	global_store_dword v73, v89, s[0:1] offset:0
	v_add_f32_e32 v90, v39, v90
	global_store_dword v73, v90, s[0:1] offset:128
	v_add_f32_e32 v91, v56, v91
	global_store_dword v74, v91, s[0:1] offset:-4096
	v_add_f32_e32 v92, v40, v92
	global_store_dword v74, v92, s[0:1] offset:-3968
	v_add_f32_e32 v93, v57, v93
	global_store_dword v74, v93, s[0:1] offset:0
	v_add_f32_e32 v94, v41, v94
	global_store_dword v74, v94, s[0:1] offset:128
	v_add_f32_e32 v95, v58, v95
	global_store_dword v75, v95, s[0:1] offset:-4096
	v_add_f32_e32 v96, v42, v96
	global_store_dword v75, v96, s[0:1] offset:-3968
	v_add_f32_e32 v97, v59, v97
	global_store_dword v75, v97, s[0:1] offset:0
	v_add_f32_e32 v98, v43, v98
	global_store_dword v75, v98, s[0:1] offset:128
	v_add_f32_e32 v99, v60, v99
	global_store_dword v76, v99, s[0:1] offset:-4096
	v_add_f32_e32 v100, v44, v100
	global_store_dword v76, v100, s[0:1] offset:-3968
	v_add_f32_e32 v101, v61, v101
	global_store_dword v76, v101, s[0:1] offset:0
	v_add_f32_e32 v102, v45, v102
	global_store_dword v76, v102, s[0:1] offset:128
	v_add_f32_e32 v103, v62, v103
	global_store_dword v77, v103, s[0:1] offset:-4096
	v_add_f32_e32 v104, v46, v104
	global_store_dword v77, v104, s[0:1] offset:-3968
	v_add_f32_e32 v105, v63, v105
	global_store_dword v77, v105, s[0:1] offset:0
	v_add_f32_e32 v106, v47, v106
	global_store_dword v77, v106, s[0:1] offset:128
	v_add_f32_e32 v107, v64, v107
	global_store_dword v78, v107, s[0:1] offset:-4096
	v_add_f32_e32 v108, v48, v108
	global_store_dword v78, v108, s[0:1] offset:-3968
	v_add_f32_e32 v109, v65, v109
	global_store_dword v78, v109, s[0:1] offset:0
	v_add_f32_e32 v110, v49, v110
	global_store_dword v78, v110, s[0:1] offset:128
	v_add_u32_e32 v71, 0x21000, v70
	global_load_dword v79, v71, s[0:1] offset:-4096
	global_load_dword v80, v71, s[0:1] offset:-3968
	global_load_dword v81, v71, s[0:1] offset:0
	global_load_dword v82, v71, s[0:1] offset:128
	v_add_u32_e32 v72, 0x23000, v70
	global_load_dword v83, v72, s[0:1] offset:-4096
	global_load_dword v84, v72, s[0:1] offset:-3968
	global_load_dword v85, v72, s[0:1] offset:0
	global_load_dword v86, v72, s[0:1] offset:128
	v_add_u32_e32 v73, 0x29000, v70
	global_load_dword v87, v73, s[0:1] offset:-4096
	global_load_dword v88, v73, s[0:1] offset:-3968
	global_load_dword v89, v73, s[0:1] offset:0
	global_load_dword v90, v73, s[0:1] offset:128
	v_add_u32_e32 v74, 0x2b000, v70
	global_load_dword v91, v74, s[0:1] offset:-4096
	global_load_dword v92, v74, s[0:1] offset:-3968
	global_load_dword v93, v74, s[0:1] offset:0
	global_load_dword v94, v74, s[0:1] offset:128
	v_add_u32_e32 v75, 0x31000, v70
	global_load_dword v95, v75, s[0:1] offset:-4096
	global_load_dword v96, v75, s[0:1] offset:-3968
	global_load_dword v97, v75, s[0:1] offset:0
	global_load_dword v98, v75, s[0:1] offset:128
	v_add_u32_e32 v76, 0x33000, v70
	global_load_dword v99, v76, s[0:1] offset:-4096
	global_load_dword v100, v76, s[0:1] offset:-3968
	global_load_dword v101, v76, s[0:1] offset:0
	global_load_dword v102, v76, s[0:1] offset:128
	v_add_u32_e32 v77, 0x39000, v70
	global_load_dword v103, v77, s[0:1] offset:-4096
	global_load_dword v104, v77, s[0:1] offset:-3968
	global_load_dword v105, v77, s[0:1] offset:0
	global_load_dword v106, v77, s[0:1] offset:128
	v_add_u32_e32 v78, 0x3b000, v70
	global_load_dword v107, v78, s[0:1] offset:-4096
	global_load_dword v108, v78, s[0:1] offset:-3968
	global_load_dword v109, v78, s[0:1] offset:0
	global_load_dword v110, v78, s[0:1] offset:128
	s_waitcnt vmcnt(0)
	v_add_f32_e32 v79, v18, v79
	global_store_dword v71, v79, s[0:1] offset:-4096
	v_add_f32_e32 v80, v2, v80
	global_store_dword v71, v80, s[0:1] offset:-3968
	v_add_f32_e32 v81, v19, v81
	global_store_dword v71, v81, s[0:1] offset:0
	v_add_f32_e32 v82, v3, v82
	global_store_dword v71, v82, s[0:1] offset:128
	v_add_f32_e32 v83, v20, v83
	global_store_dword v72, v83, s[0:1] offset:-4096
	v_add_f32_e32 v84, v4, v84
	global_store_dword v72, v84, s[0:1] offset:-3968
	v_add_f32_e32 v85, v21, v85
	global_store_dword v72, v85, s[0:1] offset:0
	v_add_f32_e32 v86, v5, v86
	global_store_dword v72, v86, s[0:1] offset:128
	v_add_f32_e32 v87, v22, v87
	global_store_dword v73, v87, s[0:1] offset:-4096
	v_add_f32_e32 v88, v6, v88
	global_store_dword v73, v88, s[0:1] offset:-3968
	v_add_f32_e32 v89, v23, v89
	global_store_dword v73, v89, s[0:1] offset:0
	v_add_f32_e32 v90, v7, v90
	global_store_dword v73, v90, s[0:1] offset:128
	v_add_f32_e32 v91, v24, v91
	global_store_dword v74, v91, s[0:1] offset:-4096
	v_add_f32_e32 v92, v8, v92
	global_store_dword v74, v92, s[0:1] offset:-3968
	v_add_f32_e32 v93, v25, v93
	global_store_dword v74, v93, s[0:1] offset:0
	v_add_f32_e32 v94, v9, v94
	global_store_dword v74, v94, s[0:1] offset:128
	v_add_f32_e32 v95, v26, v95
	global_store_dword v75, v95, s[0:1] offset:-4096
	v_add_f32_e32 v96, v10, v96
	global_store_dword v75, v96, s[0:1] offset:-3968
	v_add_f32_e32 v97, v27, v97
	global_store_dword v75, v97, s[0:1] offset:0
	v_add_f32_e32 v98, v11, v98
	global_store_dword v75, v98, s[0:1] offset:128
	v_add_f32_e32 v99, v28, v99
	global_store_dword v76, v99, s[0:1] offset:-4096
	v_add_f32_e32 v100, v12, v100
	global_store_dword v76, v100, s[0:1] offset:-3968
	v_add_f32_e32 v101, v29, v101
	global_store_dword v76, v101, s[0:1] offset:0
	v_add_f32_e32 v102, v13, v102
	global_store_dword v76, v102, s[0:1] offset:128
	v_add_f32_e32 v103, v30, v103
	global_store_dword v77, v103, s[0:1] offset:-4096
	v_add_f32_e32 v104, v14, v104
	global_store_dword v77, v104, s[0:1] offset:-3968
	v_add_f32_e32 v105, v31, v105
	global_store_dword v77, v105, s[0:1] offset:0
	v_add_f32_e32 v106, v15, v106
	global_store_dword v77, v106, s[0:1] offset:128
	v_add_f32_e32 v107, v32, v107
	global_store_dword v78, v107, s[0:1] offset:-4096
	v_add_f32_e32 v108, v16, v108
	global_store_dword v78, v108, s[0:1] offset:-3968
	v_add_f32_e32 v109, v33, v109
	global_store_dword v78, v109, s[0:1] offset:0
	v_add_f32_e32 v110, v17, v110
	global_store_dword v78, v110, s[0:1] offset:128
	s_add_i32 s3, s2, 8
	s_cmp_lt_i32 s2, 8
	s_mov_b32 s2, s3
	s_cbranch_scc1 .LBB0_533
	s_movk_i32 s17, 0x810
	s_movk_i32 s64, 0x3fff

; DI int otid() { int t = threadIdx.x; asm volatile("" : "+v"(t)); return t; }
; DI int crow(int i, int h) { return (i & 3) + 8 * (i >> 2) + 4 * h; }
;     DI void operator()(int unit, const f32x16 (&acc)[MT][NT]) const {
;         const int lane = otid() & 63, r = lane & 31, h = lane >> 5;
; #pragma unroll
;         for (int mi = 0; mi < MT; ++mi)
; #pragma unroll
;             for (int nj = 0; nj < NT; ++nj)
; #pragma unroll
;                 for (int i = 0; i < 16; ++i) { float* q = x + ((mi * 32 + crow(i, h) + (mi == 2 ? d2 : 0)) * DM + unit * UW + nj * 32 + r); *q = *q + acc[mi][nj][i]; if (i == 15) __builtin_amdgcn_sched_barrier(0); }
.LBB0_814:
	s_and_saveexec_b64 s[56:57], s[6:7]
	s_cbranch_execz .LBB0_803
	s_waitcnt vmcnt(0)
	v_and_b32_e32 v2, 31, v176
	v_lshlrev_b32_e32 v112, 9, v176
	v_and_b32_e32 v112, 0x4000, v112
	v_lshl_or_b32 v113, v2, 2, v112
	v_lshl_add_u32 v113, v232, 8, v113
	v_add_u32_e32 v114, 0x1000, v113
	global_load_dword v123, v114, s[8:9] offset:-4096
	global_load_dword v124, v114, s[8:9] offset:-3968
	global_load_dword v125, v114, s[8:9] offset:0
	global_load_dword v126, v114, s[8:9] offset:128
	v_add_u32_e32 v116, 0x3000, v113
	global_load_dword v127, v116, s[8:9] offset:-4096
	global_load_dword v128, v116, s[8:9] offset:-3968
	global_load_dword v129, v116, s[8:9] offset:0
	global_load_dword v130, v116, s[8:9] offset:128
	v_add_u32_e32 v117, 0x9000, v113
	global_load_dword v131, v117, s[8:9] offset:-4096
	global_load_dword v132, v117, s[8:9] offset:-3968
	global_load_dword v133, v117, s[8:9] offset:0
	global_load_dword v134, v117, s[8:9] offset:128
	v_add_u32_e32 v118, 0xb000, v113
	global_load_dword v135, v118, s[8:9] offset:-4096
	global_load_dword v136, v118, s[8:9] offset:-3968
	global_load_dword v137, v118, s[8:9] offset:0
	global_load_dword v138, v118, s[8:9] offset:128
	v_add_u32_e32 v119, 0x11000, v113
	global_load_dword v139, v119, s[8:9] offset:-4096
	global_load_dword v140, v119, s[8:9] offset:-3968
	global_load_dword v141, v119, s[8:9] offset:0
	global_load_dword v142, v119, s[8:9] offset:128
	v_add_u32_e32 v120, 0x13000, v113
	global_load_dword v143, v120, s[8:9] offset:-4096
	global_load_dword v144, v120, s[8:9] offset:-3968
	global_load_dword v145, v120, s[8:9] offset:0
	global_load_dword v146, v120, s[8:9] offset:128
	v_add_u32_e32 v121, 0x19000, v113
	global_load_dword v147, v121, s[8:9] offset:-4096
	global_load_dword v148, v121, s[8:9] offset:-3968
	global_load_dword v149, v121, s[8:9] offset:0
	global_load_dword v150, v121, s[8:9] offset:128
	v_add_u32_e32 v122, 0x1b000, v113
	global_load_dword v151, v122, s[8:9] offset:-4096
	global_load_dword v152, v122, s[8:9] offset:-3968
	global_load_dword v153, v122, s[8:9] offset:0
	global_load_dword v154, v122, s[8:9] offset:128
	s_waitcnt vmcnt(0)
	v_add_f32_e32 v123, v96, v123
	global_store_dword v114, v123, s[8:9] offset:-4096
	v_add_f32_e32 v124, v80, v124
	global_store_dword v114, v124, s[8:9] offset:-3968
	v_add_f32_e32 v125, v97, v125
	global_store_dword v114, v125, s[8:9] offset:0
	v_add_f32_e32 v126, v81, v126
	global_store_dword v114, v126, s[8:9] offset:128
	v_add_f32_e32 v127, v98, v127
	global_store_dword v116, v127, s[8:9] offset:-4096
	v_add_f32_e32 v128, v82, v128
	global_store_dword v116, v128, s[8:9] offset:-3968
	v_add_f32_e32 v129, v99, v129
	global_store_dword v116, v129, s[8:9] offset:0
	v_add_f32_e32 v130, v83, v130
	global_store_dword v116, v130, s[8:9] offset:128
	v_add_f32_e32 v131, v100, v131
	global_store_dword v117, v131, s[8:9] offset:-4096
	v_add_f32_e32 v132, v84, v132
	global_store_dword v117, v132, s[8:9] offset:-3968
	v_add_f32_e32 v133, v101, v133
	global_store_dword v117, v133, s[8:9] offset:0
	v_add_f32_e32 v134, v85, v134
	global_store_dword v117, v134, s[8:9] offset:128
	v_add_f32_e32 v135, v102, v135
	global_store_dword v118, v135, s[8:9] offset:-4096
	v_add_f32_e32 v136, v86, v136
	global_store_dword v118, v136, s[8:9] offset:-3968
	v_add_f32_e32 v137, v103, v137
	global_store_dword v118, v137, s[8:9] offset:0
	v_add_f32_e32 v138, v87, v138
	global_store_dword v118, v138, s[8:9] offset:128
	v_add_f32_e32 v139, v104, v139
	global_store_dword v119, v139, s[8:9] offset:-4096
	v_add_f32_e32 v140, v88, v140
	global_store_dword v119, v140, s[8:9] offset:-3968
	v_add_f32_e32 v141, v105, v141
	global_store_dword v119, v141, s[8:9] offset:0
	v_add_f32_e32 v142, v89, v142
	global_store_dword v119, v142, s[8:9] offset:128
	v_add_f32_e32 v143, v106, v143
	global_store_dword v120, v143, s[8:9] offset:-4096
	v_add_f32_e32 v144, v90, v144
	global_store_dword v120, v144, s[8:9] offset:-3968
	v_add_f32_e32 v145, v107, v145
	global_store_dword v120, v145, s[8:9] offset:0
	v_add_f32_e32 v146, v91, v146
	global_store_dword v120, v146, s[8:9] offset:128
	v_add_f32_e32 v147, v108, v147
	global_store_dword v121, v147, s[8:9] offset:-4096
	v_add_f32_e32 v148, v92, v148
	global_store_dword v121, v148, s[8:9] offset:-3968
	v_add_f32_e32 v149, v109, v149
	global_store_dword v121, v149, s[8:9] offset:0
	v_add_f32_e32 v150, v93, v150
	global_store_dword v121, v150, s[8:9] offset:128
	v_add_f32_e32 v151, v110, v151
	global_store_dword v122, v151, s[8:9] offset:-4096
	v_add_f32_e32 v152, v94, v152
	global_store_dword v122, v152, s[8:9] offset:-3968
	v_add_f32_e32 v153, v111, v153
	global_store_dword v122, v153, s[8:9] offset:0
	v_add_f32_e32 v154, v95, v154
	global_store_dword v122, v154, s[8:9] offset:128
	v_add_u32_e32 v114, 0x21000, v113
	global_load_dword v123, v114, s[8:9] offset:-4096
	global_load_dword v124, v114, s[8:9] offset:-3968
	global_load_dword v125, v114, s[8:9] offset:0
	global_load_dword v126, v114, s[8:9] offset:128
	v_add_u32_e32 v116, 0x23000, v113
	global_load_dword v127, v116, s[8:9] offset:-4096
	global_load_dword v128, v116, s[8:9] offset:-3968
	global_load_dword v129, v116, s[8:9] offset:0
	global_load_dword v130, v116, s[8:9] offset:128
	v_add_u32_e32 v117, 0x29000, v113
	global_load_dword v131, v117, s[8:9] offset:-4096
	global_load_dword v132, v117, s[8:9] offset:-3968
	global_load_dword v133, v117, s[8:9] offset:0
	global_load_dword v134, v117, s[8:9] offset:128
	v_add_u32_e32 v118, 0x2b000, v113
	global_load_dword v135, v118, s[8:9] offset:-4096
	global_load_dword v136, v118, s[8:9] offset:-3968
	global_load_dword v137, v118, s[8:9] offset:0
	global_load_dword v138, v118, s[8:9] offset:128
	v_add_u32_e32 v119, 0x31000, v113
	global_load_dword v139, v119, s[8:9] offset:-4096
	global_load_dword v140, v119, s[8:9] offset:-3968
	global_load_dword v141, v119, s[8:9] offset:0
	global_load_dword v142, v119, s[8:9] offset:128
	v_add_u32_e32 v120, 0x33000, v113
	global_load_dword v143, v120, s[8:9] offset:-4096
	global_load_dword v144, v120, s[8:9] offset:-3968
	global_load_dword v145, v120, s[8:9] offset:0
	global_load_dword v146, v120, s[8:9] offset:128
	v_add_u32_e32 v121, 0x39000, v113
	global_load_dword v147, v121, s[8:9] offset:-4096
	global_load_dword v148, v121, s[8:9] offset:-3968
	global_load_dword v149, v121, s[8:9] offset:0
	global_load_dword v150, v121, s[8:9] offset:128
	v_add_u32_e32 v122, 0x3b000, v113
	global_load_dword v151, v122, s[8:9] offset:-4096
	global_load_dword v152, v122, s[8:9] offset:-3968
	global_load_dword v153, v122, s[8:9] offset:0
	global_load_dword v154, v122, s[8:9] offset:128
	s_waitcnt vmcnt(0)
; DI int otid() { int t = threadIdx.x; asm volatile("" : "+v"(t)); return t; }
; DI int crow(int i, int h) { return (i & 3) + 8 * (i >> 2) + 4 * h; }
;     DI void operator()(int unit, const f32x16 (&acc)[MT][NT]) const {
;         const int lane = otid() & 63, r = lane & 31, h = lane >> 5;
; #pragma unroll
;         for (int mi = 0; mi < MT; ++mi)
; #pragma unroll
;             for (int nj = 0; nj < NT; ++nj)
; #pragma unroll
;                 for (int i = 0; i < 16; ++i) { float* q = x + ((mi * 32 + crow(i, h) + (mi == 2 ? d2 : 0)) * DM + unit * UW + nj * 32 + r); *q = *q + acc[mi][nj][i]; if (i == 15) __builtin_amdgcn_sched_barrier(0); }
	v_add_f32_e32 v123, v64, v123
	global_store_dword v114, v123, s[8:9] offset:-4096
	v_add_f32_e32 v124, v48, v124
	global_store_dword v114, v124, s[8:9] offset:-3968
	v_add_f32_e32 v125, v65, v125
	global_store_dword v114, v125, s[8:9] offset:0
	v_add_f32_e32 v126, v49, v126
	global_store_dword v114, v126, s[8:9] offset:128
	v_add_f32_e32 v127, v66, v127
	global_store_dword v116, v127, s[8:9] offset:-4096
	v_add_f32_e32 v128, v50, v128
	global_store_dword v116, v128, s[8:9] offset:-3968
	v_add_f32_e32 v129, v67, v129
	global_store_dword v116, v129, s[8:9] offset:0
	v_add_f32_e32 v130, v51, v130
	global_store_dword v116, v130, s[8:9] offset:128
	v_add_f32_e32 v131, v68, v131
	global_store_dword v117, v131, s[8:9] offset:-4096
	v_add_f32_e32 v132, v52, v132
	global_store_dword v117, v132, s[8:9] offset:-3968
	v_add_f32_e32 v133, v69, v133
	global_store_dword v117, v133, s[8:9] offset:0
	v_add_f32_e32 v134, v53, v134
	global_store_dword v117, v134, s[8:9] offset:128
	v_add_f32_e32 v135, v70, v135
	global_store_dword v118, v135, s[8:9] offset:-4096
	v_add_f32_e32 v136, v54, v136
	global_store_dword v118, v136, s[8:9] offset:-3968
	v_add_f32_e32 v137, v71, v137
	global_store_dword v118, v137, s[8:9] offset:0
	v_add_f32_e32 v138, v55, v138
	global_store_dword v118, v138, s[8:9] offset:128
	v_add_f32_e32 v139, v72, v139
	global_store_dword v119, v139, s[8:9] offset:-4096
	v_add_f32_e32 v140, v56, v140
	global_store_dword v119, v140, s[8:9] offset:-3968
	v_add_f32_e32 v141, v73, v141
	global_store_dword v119, v141, s[8:9] offset:0
	v_add_f32_e32 v142, v57, v142
	global_store_dword v119, v142, s[8:9] offset:128
	v_add_f32_e32 v143, v74, v143
	global_store_dword v120, v143, s[8:9] offset:-4096
	v_add_f32_e32 v144, v58, v144
	global_store_dword v120, v144, s[8:9] offset:-3968
	v_add_f32_e32 v145, v75, v145
	global_store_dword v120, v145, s[8:9] offset:0
	v_add_f32_e32 v146, v59, v146
	global_store_dword v120, v146, s[8:9] offset:128
	v_add_f32_e32 v147, v76, v147
	global_store_dword v121, v147, s[8:9] offset:-4096
	v_add_f32_e32 v148, v60, v148
	global_store_dword v121, v148, s[8:9] offset:-3968
	v_add_f32_e32 v149, v77, v149
	global_store_dword v121, v149, s[8:9] offset:0
	v_add_f32_e32 v150, v61, v150
	global_store_dword v121, v150, s[8:9] offset:128
	v_add_f32_e32 v151, v78, v151
	global_store_dword v122, v151, s[8:9] offset:-4096
	v_add_f32_e32 v152, v62, v152
	global_store_dword v122, v152, s[8:9] offset:-3968
	v_add_f32_e32 v153, v79, v153
	global_store_dword v122, v153, s[8:9] offset:0
	v_add_f32_e32 v154, v63, v154
	global_store_dword v122, v154, s[8:9] offset:128
	s_sub_i32 s100, 0x4000, s94
	v_lshl_add_u32 v112, s100, 12, v113
	v_add_u32_e32 v114, 0x1000, v112
	global_load_dword v123, v114, s[8:9] offset:-4096
	global_load_dword v124, v114, s[8:9] offset:-3968
	global_load_dword v125, v114, s[8:9] offset:0
	global_load_dword v126, v114, s[8:9] offset:128
	v_add_u32_e32 v116, 0x3000, v112
	global_load_dword v127, v116, s[8:9] offset:-4096
	global_load_dword v128, v116, s[8:9] offset:-3968
	global_load_dword v129, v116, s[8:9] offset:0
	global_load_dword v130, v116, s[8:9] offset:128
	v_add_u32_e32 v117, 0x9000, v112
	global_load_dword v131, v117, s[8:9] offset:-4096
	global_load_dword v132, v117, s[8:9] offset:-3968
	global_load_dword v133, v117, s[8:9] offset:0
	global_load_dword v134, v117, s[8:9] offset:128
	v_add_u32_e32 v118, 0xb000, v112
	global_load_dword v135, v118, s[8:9] offset:-4096
	global_load_dword v136, v118, s[8:9] offset:-3968
	global_load_dword v137, v118, s[8:9] offset:0
	global_load_dword v138, v118, s[8:9] offset:128
	v_add_u32_e32 v119, 0x11000, v112
	global_load_dword v139, v119, s[8:9] offset:-4096
	global_load_dword v140, v119, s[8:9] offset:-3968
	global_load_dword v141, v119, s[8:9] offset:0
	global_load_dword v142, v119, s[8:9] offset:128
	v_add_u32_e32 v120, 0x13000, v112
	global_load_dword v143, v120, s[8:9] offset:-4096
	global_load_dword v144, v120, s[8:9] offset:-3968
	global_load_dword v145, v120, s[8:9] offset:0
	global_load_dword v146, v120, s[8:9] offset:128
	v_add_u32_e32 v121, 0x19000, v112
	global_load_dword v147, v121, s[8:9] offset:-4096
	global_load_dword v148, v121, s[8:9] offset:-3968
	global_load_dword v149, v121, s[8:9] offset:0
	global_load_dword v150, v121, s[8:9] offset:128
	v_add_u32_e32 v122, 0x1b000, v112
	global_load_dword v151, v122, s[8:9] offset:-4096
	global_load_dword v152, v122, s[8:9] offset:-3968
	global_load_dword v153, v122, s[8:9] offset:0
	global_load_dword v154, v122, s[8:9] offset:128
	s_waitcnt vmcnt(0)
; DI int otid() { int t = threadIdx.x; asm volatile("" : "+v"(t)); return t; }
; DI int crow(int i, int h) { return (i & 3) + 8 * (i >> 2) + 4 * h; }
;     DI void operator()(int unit, const f32x16 (&acc)[MT][NT]) const {
;         const int lane = otid() & 63, r = lane & 31, h = lane >> 5;
; #pragma unroll
;         for (int mi = 0; mi < MT; ++mi)
; #pragma unroll
;             for (int nj = 0; nj < NT; ++nj)
; #pragma unroll
;                 for (int i = 0; i < 16; ++i) { float* q = x + ((mi * 32 + crow(i, h) + (mi == 2 ? d2 : 0)) * DM + unit * UW + nj * 32 + r); *q = *q + acc[mi][nj][i]; if (i == 15) __builtin_amdgcn_sched_barrier(0); }
	v_add_f32_e32 v123, v32, v123
	global_store_dword v114, v123, s[8:9] offset:-4096
	v_add_f32_e32 v124, v16, v124
	global_store_dword v114, v124, s[8:9] offset:-3968
	v_add_f32_e32 v125, v33, v125
	global_store_dword v114, v125, s[8:9] offset:0
	v_add_f32_e32 v126, v17, v126
	global_store_dword v114, v126, s[8:9] offset:128
	v_add_f32_e32 v127, v34, v127
	global_store_dword v116, v127, s[8:9] offset:-4096
	v_add_f32_e32 v128, v18, v128
	global_store_dword v116, v128, s[8:9] offset:-3968
	v_add_f32_e32 v129, v35, v129
	global_store_dword v116, v129, s[8:9] offset:0
	v_add_f32_e32 v130, v19, v130
	global_store_dword v116, v130, s[8:9] offset:128
	v_add_f32_e32 v131, v36, v131
	global_store_dword v117, v131, s[8:9] offset:-4096
	v_add_f32_e32 v132, v20, v132
	global_store_dword v117, v132, s[8:9] offset:-3968
	v_add_f32_e32 v133, v37, v133
	global_store_dword v117, v133, s[8:9] offset:0
	v_add_f32_e32 v134, v21, v134
	global_store_dword v117, v134, s[8:9] offset:128
	v_add_f32_e32 v135, v38, v135
	global_store_dword v118, v135, s[8:9] offset:-4096
	v_add_f32_e32 v136, v22, v136
	global_store_dword v118, v136, s[8:9] offset:-3968
	v_add_f32_e32 v137, v39, v137
	global_store_dword v118, v137, s[8:9] offset:0
	v_add_f32_e32 v138, v23, v138
	global_store_dword v118, v138, s[8:9] offset:128
	v_add_f32_e32 v139, v40, v139
	global_store_dword v119, v139, s[8:9] offset:-4096
	v_add_f32_e32 v140, v24, v140
	global_store_dword v119, v140, s[8:9] offset:-3968
	v_add_f32_e32 v141, v41, v141
	global_store_dword v119, v141, s[8:9] offset:0
	v_add_f32_e32 v142, v25, v142
	global_store_dword v119, v142, s[8:9] offset:128
	v_add_f32_e32 v143, v42, v143
	global_store_dword v120, v143, s[8:9] offset:-4096
	v_add_f32_e32 v144, v26, v144
	global_store_dword v120, v144, s[8:9] offset:-3968
	v_add_f32_e32 v145, v43, v145
	global_store_dword v120, v145, s[8:9] offset:0
	v_add_f32_e32 v146, v27, v146
	global_store_dword v120, v146, s[8:9] offset:128
	v_add_f32_e32 v147, v44, v147
	global_store_dword v121, v147, s[8:9] offset:-4096
	v_add_f32_e32 v148, v28, v148
	global_store_dword v121, v148, s[8:9] offset:-3968
	v_add_f32_e32 v149, v45, v149
	global_store_dword v121, v149, s[8:9] offset:0
	v_add_f32_e32 v150, v29, v150
	global_store_dword v121, v150, s[8:9] offset:128
	v_add_f32_e32 v151, v46, v151
	global_store_dword v122, v151, s[8:9] offset:-4096
	v_add_f32_e32 v152, v30, v152
	global_store_dword v122, v152, s[8:9] offset:-3968
	v_add_f32_e32 v153, v47, v153
	global_store_dword v122, v153, s[8:9] offset:0
	v_add_f32_e32 v154, v31, v154
	global_store_dword v122, v154, s[8:9] offset:128
	s_branch .LBB0_803

; DI int otid() { int t = threadIdx.x; asm volatile("" : "+v"(t)); return t; }
; DI int crow(int i, int h) { return (i & 3) + 8 * (i >> 2) + 4 * h; }
;     DI void operator()(int unit, const f32x16 (&acc)[MT][NT]) const {
;         const int lane = otid() & 63, r = lane & 31, h = lane >> 5;
; #pragma unroll
;         for (int mi = 0; mi < MT; ++mi)
; #pragma unroll
;             for (int nj = 0; nj < NT; ++nj)
; #pragma unroll
;                 for (int i = 0; i < 16; ++i) { float* q = x + ((mi * 32 + crow(i, h) + (mi == 2 ? d2 : 0)) * DM + unit * UW + nj * 32 + r); *q = *q + acc[mi][nj][i]; if (i == 15) __builtin_amdgcn_sched_barrier(0); }
.LBB0_879:
	s_and_saveexec_b64 s[56:57], s[6:7]
	s_cbranch_execz .LBB0_868
	s_waitcnt vmcnt(0)
	v_and_b32_e32 v2, 31, v176
	v_lshlrev_b32_e32 v80, 9, v176
	v_and_b32_e32 v80, 0x4000, v80
	v_lshl_or_b32 v81, v2, 2, v80
	v_lshl_add_u32 v81, v143, 8, v81
	v_add_u32_e32 v82, 0x1000, v81
	global_load_dword v90, v82, s[8:9] offset:-4096
	global_load_dword v91, v82, s[8:9] offset:-3968
	global_load_dword v92, v82, s[8:9] offset:0
	global_load_dword v93, v82, s[8:9] offset:128
	v_add_u32_e32 v83, 0x3000, v81
	global_load_dword v94, v83, s[8:9] offset:-4096
	global_load_dword v95, v83, s[8:9] offset:-3968
	global_load_dword v96, v83, s[8:9] offset:0
	global_load_dword v97, v83, s[8:9] offset:128
	v_add_u32_e32 v84, 0x9000, v81
	global_load_dword v98, v84, s[8:9] offset:-4096
	global_load_dword v99, v84, s[8:9] offset:-3968
	global_load_dword v100, v84, s[8:9] offset:0
	global_load_dword v101, v84, s[8:9] offset:128
	v_add_u32_e32 v85, 0xb000, v81
	global_load_dword v102, v85, s[8:9] offset:-4096
	global_load_dword v103, v85, s[8:9] offset:-3968
	global_load_dword v104, v85, s[8:9] offset:0
	global_load_dword v105, v85, s[8:9] offset:128
	v_add_u32_e32 v86, 0x11000, v81
	global_load_dword v106, v86, s[8:9] offset:-4096
	global_load_dword v107, v86, s[8:9] offset:-3968
	global_load_dword v108, v86, s[8:9] offset:0
	global_load_dword v109, v86, s[8:9] offset:128
	v_add_u32_e32 v87, 0x13000, v81
	global_load_dword v110, v87, s[8:9] offset:-4096
	global_load_dword v111, v87, s[8:9] offset:-3968
	global_load_dword v112, v87, s[8:9] offset:0
	global_load_dword v113, v87, s[8:9] offset:128
	v_add_u32_e32 v88, 0x19000, v81
	global_load_dword v114, v88, s[8:9] offset:-4096
	global_load_dword v116, v88, s[8:9] offset:-3968
	global_load_dword v117, v88, s[8:9] offset:0
	global_load_dword v118, v88, s[8:9] offset:128
	v_add_u32_e32 v89, 0x1b000, v81
	global_load_dword v119, v89, s[8:9] offset:-4096
	global_load_dword v128, v89, s[8:9] offset:-3968
	global_load_dword v129, v89, s[8:9] offset:0
	global_load_dword v130, v89, s[8:9] offset:128
	s_waitcnt vmcnt(0)
	v_add_f32_e32 v90, v64, v90
	global_store_dword v82, v90, s[8:9] offset:-4096
	v_add_f32_e32 v91, v48, v91
	global_store_dword v82, v91, s[8:9] offset:-3968
	v_add_f32_e32 v92, v65, v92
	global_store_dword v82, v92, s[8:9] offset:0
	v_add_f32_e32 v93, v49, v93
	global_store_dword v82, v93, s[8:9] offset:128
	v_add_f32_e32 v94, v66, v94
	global_store_dword v83, v94, s[8:9] offset:-4096
	v_add_f32_e32 v95, v50, v95
	global_store_dword v83, v95, s[8:9] offset:-3968
	v_add_f32_e32 v96, v67, v96
	global_store_dword v83, v96, s[8:9] offset:0
	v_add_f32_e32 v97, v51, v97
	global_store_dword v83, v97, s[8:9] offset:128
	v_add_f32_e32 v98, v68, v98
	global_store_dword v84, v98, s[8:9] offset:-4096
	v_add_f32_e32 v99, v52, v99
	global_store_dword v84, v99, s[8:9] offset:-3968
	v_add_f32_e32 v100, v69, v100
	global_store_dword v84, v100, s[8:9] offset:0
	v_add_f32_e32 v101, v53, v101
	global_store_dword v84, v101, s[8:9] offset:128
	v_add_f32_e32 v102, v70, v102
	global_store_dword v85, v102, s[8:9] offset:-4096
	v_add_f32_e32 v103, v54, v103
	global_store_dword v85, v103, s[8:9] offset:-3968
	v_add_f32_e32 v104, v71, v104
	global_store_dword v85, v104, s[8:9] offset:0
	v_add_f32_e32 v105, v55, v105
	global_store_dword v85, v105, s[8:9] offset:128
	v_add_f32_e32 v106, v72, v106
	global_store_dword v86, v106, s[8:9] offset:-4096
	v_add_f32_e32 v107, v56, v107
	global_store_dword v86, v107, s[8:9] offset:-3968
	v_add_f32_e32 v108, v73, v108
	global_store_dword v86, v108, s[8:9] offset:0
	v_add_f32_e32 v109, v57, v109
	global_store_dword v86, v109, s[8:9] offset:128
	v_add_f32_e32 v110, v74, v110
	global_store_dword v87, v110, s[8:9] offset:-4096
	v_add_f32_e32 v111, v58, v111
	global_store_dword v87, v111, s[8:9] offset:-3968
	v_add_f32_e32 v112, v75, v112
	global_store_dword v87, v112, s[8:9] offset:0
	v_add_f32_e32 v113, v59, v113
	global_store_dword v87, v113, s[8:9] offset:128
	v_add_f32_e32 v114, v76, v114
	global_store_dword v88, v114, s[8:9] offset:-4096
	v_add_f32_e32 v116, v60, v116
	global_store_dword v88, v116, s[8:9] offset:-3968
	v_add_f32_e32 v117, v77, v117
	global_store_dword v88, v117, s[8:9] offset:0
	v_add_f32_e32 v118, v61, v118
	global_store_dword v88, v118, s[8:9] offset:128
	v_add_f32_e32 v119, v78, v119
	global_store_dword v89, v119, s[8:9] offset:-4096
	v_add_f32_e32 v128, v62, v128
	global_store_dword v89, v128, s[8:9] offset:-3968
	v_add_f32_e32 v129, v79, v129
	global_store_dword v89, v129, s[8:9] offset:0
	v_add_f32_e32 v130, v63, v130
	global_store_dword v89, v130, s[8:9] offset:128
	v_add_u32_e32 v82, 0x21000, v81
	global_load_dword v90, v82, s[8:9] offset:-4096
	global_load_dword v91, v82, s[8:9] offset:-3968
	global_load_dword v92, v82, s[8:9] offset:0
	global_load_dword v93, v82, s[8:9] offset:128
	v_add_u32_e32 v83, 0x23000, v81
	global_load_dword v94, v83, s[8:9] offset:-4096
	global_load_dword v95, v83, s[8:9] offset:-3968
	global_load_dword v96, v83, s[8:9] offset:0
	global_load_dword v97, v83, s[8:9] offset:128
	v_add_u32_e32 v84, 0x29000, v81
	global_load_dword v98, v84, s[8:9] offset:-4096
	global_load_dword v99, v84, s[8:9] offset:-3968
	global_load_dword v100, v84, s[8:9] offset:0
	global_load_dword v101, v84, s[8:9] offset:128
	v_add_u32_e32 v85, 0x2b000, v81
	global_load_dword v102, v85, s[8:9] offset:-4096
	global_load_dword v103, v85, s[8:9] offset:-3968
	global_load_dword v104, v85, s[8:9] offset:0
	global_load_dword v105, v85, s[8:9] offset:128
	v_add_u32_e32 v86, 0x31000, v81
	global_load_dword v106, v86, s[8:9] offset:-4096
	global_load_dword v107, v86, s[8:9] offset:-3968
	global_load_dword v108, v86, s[8:9] offset:0
	global_load_dword v109, v86, s[8:9] offset:128
	v_add_u32_e32 v87, 0x33000, v81
	global_load_dword v110, v87, s[8:9] offset:-4096
	global_load_dword v111, v87, s[8:9] offset:-3968
	global_load_dword v112, v87, s[8:9] offset:0
	global_load_dword v113, v87, s[8:9] offset:128
	v_add_u32_e32 v88, 0x39000, v81
	global_load_dword v114, v88, s[8:9] offset:-4096
	global_load_dword v116, v88, s[8:9] offset:-3968
	global_load_dword v117, v88, s[8:9] offset:0
	global_load_dword v118, v88, s[8:9] offset:128
	v_add_u32_e32 v89, 0x3b000, v81
	global_load_dword v119, v89, s[8:9] offset:-4096
	global_load_dword v128, v89, s[8:9] offset:-3968
	global_load_dword v129, v89, s[8:9] offset:0
	global_load_dword v130, v89, s[8:9] offset:128
	s_waitcnt vmcnt(0)
; DI int otid() { int t = threadIdx.x; asm volatile("" : "+v"(t)); return t; }
; DI int crow(int i, int h) { return (i & 3) + 8 * (i >> 2) + 4 * h; }
;     DI void operator()(int unit, const f32x16 (&acc)[MT][NT]) const {
;         const int lane = otid() & 63, r = lane & 31, h = lane >> 5;
; #pragma unroll
;         for (int mi = 0; mi < MT; ++mi)
; #pragma unroll
;             for (int nj = 0; nj < NT; ++nj)
; #pragma unroll
;                 for (int i = 0; i < 16; ++i) { float* q = x + ((mi * 32 + crow(i, h) + (mi == 2 ? d2 : 0)) * DM + unit * UW + nj * 32 + r); *q = *q + acc[mi][nj][i]; if (i == 15) __builtin_amdgcn_sched_barrier(0); }
	v_add_f32_e32 v90, v32, v90
	global_store_dword v82, v90, s[8:9] offset:-4096
	v_add_f32_e32 v91, v16, v91
	global_store_dword v82, v91, s[8:9] offset:-3968
	v_add_f32_e32 v92, v33, v92
	global_store_dword v82, v92, s[8:9] offset:0
	v_add_f32_e32 v93, v17, v93
	global_store_dword v82, v93, s[8:9] offset:128
	v_add_f32_e32 v94, v34, v94
	global_store_dword v83, v94, s[8:9] offset:-4096
	v_add_f32_e32 v95, v18, v95
	global_store_dword v83, v95, s[8:9] offset:-3968
	v_add_f32_e32 v96, v35, v96
	global_store_dword v83, v96, s[8:9] offset:0
	v_add_f32_e32 v97, v19, v97
	global_store_dword v83, v97, s[8:9] offset:128
	v_add_f32_e32 v98, v36, v98
	global_store_dword v84, v98, s[8:9] offset:-4096
	v_add_f32_e32 v99, v20, v99
	global_store_dword v84, v99, s[8:9] offset:-3968
	v_add_f32_e32 v100, v37, v100
	global_store_dword v84, v100, s[8:9] offset:0
	v_add_f32_e32 v101, v21, v101
	global_store_dword v84, v101, s[8:9] offset:128
	v_add_f32_e32 v102, v38, v102
	global_store_dword v85, v102, s[8:9] offset:-4096
	v_add_f32_e32 v103, v22, v103
	global_store_dword v85, v103, s[8:9] offset:-3968
	v_add_f32_e32 v104, v39, v104
	global_store_dword v85, v104, s[8:9] offset:0
	v_add_f32_e32 v105, v23, v105
	global_store_dword v85, v105, s[8:9] offset:128
	v_add_f32_e32 v106, v40, v106
	global_store_dword v86, v106, s[8:9] offset:-4096
	v_add_f32_e32 v107, v24, v107
	global_store_dword v86, v107, s[8:9] offset:-3968
	v_add_f32_e32 v108, v41, v108
	global_store_dword v86, v108, s[8:9] offset:0
	v_add_f32_e32 v109, v25, v109
	global_store_dword v86, v109, s[8:9] offset:128
	v_add_f32_e32 v110, v42, v110
	global_store_dword v87, v110, s[8:9] offset:-4096
	v_add_f32_e32 v111, v26, v111
	global_store_dword v87, v111, s[8:9] offset:-3968
	v_add_f32_e32 v112, v43, v112
	global_store_dword v87, v112, s[8:9] offset:0
	v_add_f32_e32 v113, v27, v113
	global_store_dword v87, v113, s[8:9] offset:128
	v_add_f32_e32 v114, v44, v114
	global_store_dword v88, v114, s[8:9] offset:-4096
	v_add_f32_e32 v116, v28, v116
	global_store_dword v88, v116, s[8:9] offset:-3968
	v_add_f32_e32 v117, v45, v117
	global_store_dword v88, v117, s[8:9] offset:0
	v_add_f32_e32 v118, v29, v118
	global_store_dword v88, v118, s[8:9] offset:128
	v_add_f32_e32 v119, v46, v119
	global_store_dword v89, v119, s[8:9] offset:-4096
	v_add_f32_e32 v128, v30, v128
	global_store_dword v89, v128, s[8:9] offset:-3968
	v_add_f32_e32 v129, v47, v129
	global_store_dword v89, v129, s[8:9] offset:0
	v_add_f32_e32 v130, v31, v130
	global_store_dword v89, v130, s[8:9] offset:128
	s_branch .LBB0_868
